# v65 + second A base pair kept intact in the K-loops: half-tile step in loop-invariant VGPR offsets, M0 scratch folded, last two +128 DMAs via SGPR base (6 fewer instructions per body in 7 loops)
# baseline (speedup 1.0000x reference)
;     __host__ __device__ bool next(int i, Unit& u) const { const int P = (i >> 1) * G + c; if (P >= 256) return false; u.pm = P >> 3; u.pn = (P & 7) + 8 * (i & 1); return true; }
; template <class Epi, class Sched, bool ALIGN_EPI = false, bool SP2 = false>
; __device__ __forceinline__ void gemm_phase(PG8_LAS unsigned char* lds, const Gemm g, const Sched& S, const Epi& E, const int wv) {
;     ...
;     for (;;) {
;         const bool has_next = S.next(ui + 1, nxt);
;         const char* nA = has_next ? (const char*)g.A + (size_t)nxt.pm * tstepA + (g.amod ? (size_t)(nxt.pn % g.amod) * K * 2 : (size_t)0) : cA; const char* nB = has_next ? (const char*)g.Bt + (size_t)nxt.pn * tstepB : cB;
;         for (int t = 0; t < nt; t += 2) {
;             const bool last = (t == nt - 2);
;             const char* a1 = cA + (size_t)(t + 1) * kstep;
;             const char* a2 = last ? nA : cA + (size_t)(t + 2) * kstep; const char* b2 = last ? nB : cB + (size_t)(t + 2) * kstep;
;             const char* a3 = a2 + kstep; const char* b3 = b2 + kstep;
;     ...
; #pragma unroll
;         for (int a = 0; a < 2; ++a)
; #pragma unroll
;             for (int b = 0; b < 2; ++b)
; #pragma unroll
;                 for (int m = 0; m < 4; ++m)
; #pragma unroll
;                     for (int n = 0; n < 2; ++n) acc[a][b][m][n] = (f32x4){0.f, 0.f, 0.f, 0.f};
.LBB0_174:
	s_ashr_i32 s35, s34, 31
	s_lshl_b64 s[46:47], s[34:35], 20
	s_add_u32 s46, s51, s46
	v_mov_b32_e32 v153, 0
	s_addc_u32 s47, s52, s47
	s_andn2_b64 vcc, exec, s[28:29]
	v_mov_b32_e32 v152, v153
	v_pk_mov_b32 v[150:151], v[152:153], v[152:153]
	v_pk_mov_b32 v[148:149], v[152:153], v[152:153]
	v_pk_mov_b32 v[146:147], v[152:153], v[152:153]
	v_pk_mov_b32 v[136:137], v[152:153], v[152:153]
	v_pk_mov_b32 v[134:135], v[152:153], v[152:153]
	v_pk_mov_b32 v[132:133], v[152:153], v[152:153]
	v_pk_mov_b32 v[130:131], v[152:153], v[152:153]
	v_pk_mov_b32 v[120:121], v[152:153], v[152:153]
	v_pk_mov_b32 v[118:119], v[152:153], v[152:153]
	v_pk_mov_b32 v[116:117], v[152:153], v[152:153]
	v_pk_mov_b32 v[114:115], v[152:153], v[152:153]
	v_pk_mov_b32 v[104:105], v[152:153], v[152:153]
	v_pk_mov_b32 v[102:103], v[152:153], v[152:153]
	v_pk_mov_b32 v[100:101], v[152:153], v[152:153]
	v_pk_mov_b32 v[98:99], v[152:153], v[152:153]
	v_pk_mov_b32 v[144:145], v[152:153], v[152:153]
	v_pk_mov_b32 v[142:143], v[152:153], v[152:153]
	v_pk_mov_b32 v[140:141], v[152:153], v[152:153]
	v_pk_mov_b32 v[138:139], v[152:153], v[152:153]
	v_pk_mov_b32 v[128:129], v[152:153], v[152:153]
	v_pk_mov_b32 v[126:127], v[152:153], v[152:153]
	v_pk_mov_b32 v[124:125], v[152:153], v[152:153]
	v_pk_mov_b32 v[122:123], v[152:153], v[152:153]
	v_pk_mov_b32 v[112:113], v[152:153], v[152:153]
	v_pk_mov_b32 v[110:111], v[152:153], v[152:153]
	v_pk_mov_b32 v[108:109], v[152:153], v[152:153]
	v_pk_mov_b32 v[106:107], v[152:153], v[152:153]
	v_pk_mov_b32 v[96:97], v[152:153], v[152:153]
	v_pk_mov_b32 v[94:95], v[152:153], v[152:153]
	v_pk_mov_b32 v[92:93], v[152:153], v[152:153]
	v_pk_mov_b32 v[90:91], v[152:153], v[152:153]
	v_pk_mov_b32 v[80:81], v[152:153], v[152:153]
	v_pk_mov_b32 v[78:79], v[152:153], v[152:153]
	v_pk_mov_b32 v[72:73], v[152:153], v[152:153]
	v_pk_mov_b32 v[70:71], v[152:153], v[152:153]
	v_pk_mov_b32 v[48:49], v[152:153], v[152:153]
	v_pk_mov_b32 v[46:47], v[152:153], v[152:153]
	v_pk_mov_b32 v[44:45], v[152:153], v[152:153]
	v_pk_mov_b32 v[42:43], v[152:153], v[152:153]
	v_pk_mov_b32 v[32:33], v[152:153], v[152:153]
	v_pk_mov_b32 v[30:31], v[152:153], v[152:153]
	v_pk_mov_b32 v[28:29], v[152:153], v[152:153]
	v_pk_mov_b32 v[26:27], v[152:153], v[152:153]
	v_pk_mov_b32 v[16:17], v[152:153], v[152:153]
	v_pk_mov_b32 v[14:15], v[152:153], v[152:153]
	v_pk_mov_b32 v[12:13], v[152:153], v[152:153]
	v_pk_mov_b32 v[10:11], v[152:153], v[152:153]
	v_pk_mov_b32 v[64:65], v[152:153], v[152:153]
	v_pk_mov_b32 v[62:63], v[152:153], v[152:153]
	v_pk_mov_b32 v[56:57], v[152:153], v[152:153]
	v_pk_mov_b32 v[54:55], v[152:153], v[152:153]
	v_pk_mov_b32 v[40:41], v[152:153], v[152:153]
	v_pk_mov_b32 v[38:39], v[152:153], v[152:153]
	v_pk_mov_b32 v[36:37], v[152:153], v[152:153]
	v_pk_mov_b32 v[34:35], v[152:153], v[152:153]
	v_pk_mov_b32 v[24:25], v[152:153], v[152:153]
	v_pk_mov_b32 v[22:23], v[152:153], v[152:153]
	v_pk_mov_b32 v[20:21], v[152:153], v[152:153]
	v_pk_mov_b32 v[18:19], v[152:153], v[152:153]
	v_pk_mov_b32 v[8:9], v[152:153], v[152:153]
	v_pk_mov_b32 v[6:7], v[152:153], v[152:153]
	v_pk_mov_b32 v[4:5], v[152:153], v[152:153]
	v_pk_mov_b32 v[2:3], v[152:153], v[152:153]
	s_cbranch_vccnz .LBB0_178
	s_and_b64 s[42:43], s[42:43], exec
	s_cselect_b32 s11, s47, s13
	s_cselect_b32 s35, s46, s12
	s_add_u32 s12, s12, 0x80080
	s_addc_u32 s13, s13, 0
	s_add_u32 s42, s14, 0x100
	v_mov_b32_e32 v2, 0
	s_addc_u32 s43, s15, 0
	s_mov_b32 s14, 0
	v_mov_b32_e32 v3, v2
	v_pk_mov_b32 v[4:5], v[2:3], v[2:3]
	v_pk_mov_b32 v[6:7], v[2:3], v[2:3]
	v_pk_mov_b32 v[8:9], v[2:3], v[2:3]
	v_pk_mov_b32 v[18:19], v[2:3], v[2:3]
	v_pk_mov_b32 v[20:21], v[2:3], v[2:3]
	v_pk_mov_b32 v[22:23], v[2:3], v[2:3]
	v_pk_mov_b32 v[24:25], v[2:3], v[2:3]
	v_pk_mov_b32 v[34:35], v[2:3], v[2:3]
	v_pk_mov_b32 v[36:37], v[2:3], v[2:3]
	v_pk_mov_b32 v[38:39], v[2:3], v[2:3]
	v_pk_mov_b32 v[40:41], v[2:3], v[2:3]
	v_pk_mov_b32 v[54:55], v[2:3], v[2:3]
	v_pk_mov_b32 v[56:57], v[2:3], v[2:3]
	v_pk_mov_b32 v[62:63], v[2:3], v[2:3]
	v_pk_mov_b32 v[64:65], v[2:3], v[2:3]
	v_pk_mov_b32 v[10:11], v[2:3], v[2:3]
	v_pk_mov_b32 v[12:13], v[2:3], v[2:3]
	v_pk_mov_b32 v[14:15], v[2:3], v[2:3]
	v_pk_mov_b32 v[16:17], v[2:3], v[2:3]
	v_pk_mov_b32 v[26:27], v[2:3], v[2:3]
	v_pk_mov_b32 v[28:29], v[2:3], v[2:3]
	v_pk_mov_b32 v[30:31], v[2:3], v[2:3]
	v_pk_mov_b32 v[32:33], v[2:3], v[2:3]
	v_pk_mov_b32 v[42:43], v[2:3], v[2:3]
	v_pk_mov_b32 v[44:45], v[2:3], v[2:3]
	v_pk_mov_b32 v[46:47], v[2:3], v[2:3]
	v_pk_mov_b32 v[48:49], v[2:3], v[2:3]
	v_pk_mov_b32 v[70:71], v[2:3], v[2:3]
	v_pk_mov_b32 v[72:73], v[2:3], v[2:3]
	v_pk_mov_b32 v[78:79], v[2:3], v[2:3]
	v_pk_mov_b32 v[80:81], v[2:3], v[2:3]
	v_pk_mov_b32 v[90:91], v[2:3], v[2:3]
	v_pk_mov_b32 v[92:93], v[2:3], v[2:3]
	v_pk_mov_b32 v[94:95], v[2:3], v[2:3]
	v_pk_mov_b32 v[96:97], v[2:3], v[2:3]
	v_pk_mov_b32 v[106:107], v[2:3], v[2:3]
	v_pk_mov_b32 v[108:109], v[2:3], v[2:3]
	v_pk_mov_b32 v[110:111], v[2:3], v[2:3]
	v_pk_mov_b32 v[112:113], v[2:3], v[2:3]
	v_pk_mov_b32 v[122:123], v[2:3], v[2:3]
	v_pk_mov_b32 v[124:125], v[2:3], v[2:3]
	v_pk_mov_b32 v[126:127], v[2:3], v[2:3]
	v_pk_mov_b32 v[128:129], v[2:3], v[2:3]
	v_pk_mov_b32 v[138:139], v[2:3], v[2:3]
	v_pk_mov_b32 v[140:141], v[2:3], v[2:3]
	v_pk_mov_b32 v[142:143], v[2:3], v[2:3]
	v_pk_mov_b32 v[144:145], v[2:3], v[2:3]
	v_pk_mov_b32 v[98:99], v[2:3], v[2:3]
	v_pk_mov_b32 v[100:101], v[2:3], v[2:3]
	v_pk_mov_b32 v[102:103], v[2:3], v[2:3]
	v_pk_mov_b32 v[104:105], v[2:3], v[2:3]
	v_pk_mov_b32 v[114:115], v[2:3], v[2:3]
	v_pk_mov_b32 v[116:117], v[2:3], v[2:3]
	v_pk_mov_b32 v[118:119], v[2:3], v[2:3]
	v_pk_mov_b32 v[120:121], v[2:3], v[2:3]
	v_pk_mov_b32 v[130:131], v[2:3], v[2:3]
	v_pk_mov_b32 v[132:133], v[2:3], v[2:3]
	v_pk_mov_b32 v[134:135], v[2:3], v[2:3]
	v_pk_mov_b32 v[136:137], v[2:3], v[2:3]
	v_pk_mov_b32 v[146:147], v[2:3], v[2:3]
	v_pk_mov_b32 v[148:149], v[2:3], v[2:3]
	v_pk_mov_b32 v[150:151], v[2:3], v[2:3]
	v_pk_mov_b32 v[152:153], v[2:3], v[2:3]
	v_add_u32_e32 v171, 0x10000, v185
	v_add_u32_e32 v173, 0x14000, v185
	v_add_u32_e32 v201, 0x18000, v185
	v_add_u32_e32 v227, 0x1c000, v185
	v_add_u32_e32 v59, 0x80000, v162
	v_add_u32_e32 v246, 0x80000, v164
; #define PG8_STAGE(bufoff, gbase, voff) do { _Pragma("unroll") for (int _i = 0; _i < 2; ++_i) \
;         __builtin_amdgcn_global_load_lds((const unsigned*)((const char*)(gbase) + (voff)[_i]), (PG8_LAS unsigned*)(lds + (bufoff) + ldsw + _i * 8192), 16, 0, 0); } while (0)
; #define PG8_LDA(dst, b, h) do { _Pragma("unroll") for (int m = 0; m < 4; ++m) _Pragma("unroll") for (int k = 0; k < 2; ++k) dst[m][k] = *(const PG8_LAS bf16x8*)(lds + PG8_SA(b, h) + aoff + m * 2048 + k * 1024); } while (0)
; #define PG8_LDB(dst, b, h) do { _Pragma("unroll") for (int n = 0; n < 2; ++n) _Pragma("unroll") for (int k = 0; k < 2; ++k) dst[n][k] = *(const PG8_LAS bf16x8*)(lds + PG8_SB(b, h) + boff + n * 2048 + k * 1024); } while (0)
; #define PG8_MMA(ai, bj, At, Bt) do { __builtin_amdgcn_s_setprio(1); _Pragma("unroll") for (int m = 0; m < 4; ++m) _Pragma("unroll") for (int n = 0; n < 2; ++n) _Pragma("unroll") for (int k = 0; k < 2; ++k) \
;         acc[ai][bj][m][n] = __builtin_amdgcn_mfma_f32_16x16x32_bf16(Bt[n][k], At[m][k], acc[ai][bj][m][n], 0, 0, 0); __builtin_amdgcn_s_setprio(0); } while (0)
; #define PG8_WAIT_V(n) asm volatile("s_waitcnt vmcnt(" #n ")" ::: "memory")
; #define PG8_BAR __builtin_amdgcn_s_barrier()
; template <class Epi, class Sched, bool ALIGN_EPI = false, bool SP2 = false>
; __device__ __forceinline__ void gemm_phase(PG8_LAS unsigned char* lds, const Gemm g, const Sched& S, const Epi& E, const int wv) {
;     ...
;         for (int t = 0; t < nt; t += 2) {
;             const bool last = (t == nt - 2);
;             const char* a1 = cA + (size_t)(t + 1) * kstep;
;             const char* a2 = last ? nA : cA + (size_t)(t + 2) * kstep; const char* b2 = last ? nB : cB + (size_t)(t + 2) * kstep;
;             const char* a3 = a2 + kstep; const char* b3 = b2 + kstep;
;             if (last && has_next) S.a_ready(nxt);
;             if constexpr (SP2) {
;             PG8_LDB(B0, 0, 0); PG8_LDB(B1, 0, 1); PG8_SCHED; PG8_LDA(At, 0, 0); PG8_STAGE(PG8_SA(1, 1), a1 + hstepA, voffA);
;             PG8_WAIT_V(8); PG8_WAIT_L(0); PG8_BAR; PG8_MMA(0, 0, At, B0); PG8_MMA(0, 1, At, B1); PG8_BAR; PG8_SCHED;
;             PG8_LDA(At, 0, 1); PG8_STAGE(PG8_SB(0, 0), b2, voffB); PG8_STAGE(PG8_SB(0, 1), b2 + hstepB, voffB); PG8_STAGE(PG8_SA(0, 0), a2, voffA);
;             PG8_WAIT_V(8); PG8_WAIT_L(0); PG8_BAR; PG8_MMA(1, 0, At, B0); PG8_MMA(1, 1, At, B1); PG8_BAR; PG8_SCHED;
.LBB0_176:
	s_add_i32 s67, s14, 2
	s_add_u32 s68, s12, 0xfff80080
	s_addc_u32 s15, s13, -1
	s_cmp_eq_u32 s61, s14
	s_cselect_b32 s15, s11, s15
	s_cselect_b32 s14, s35, s68
	s_cselect_b32 s69, s45, s43
	s_cselect_b32 s68, s44, s42
	ds_read_b128 v[66:69], v171
	ds_read_b128 v[74:77], v171 offset:1024
	ds_read_b128 v[82:85], v171 offset:2048
	ds_read_b128 v[86:89], v171 offset:3072
	ds_read_b128 v[154:157], v173
	ds_read_b128 v[158:161], v173 offset:1024
	ds_read_b128 v[174:177], v173 offset:2048
	ds_read_b128 v[178:181], v173 offset:3072
	s_add_i32 m0, s54, 0xc000
	ds_read_b128 v[202:205], v200
	ds_read_b128 v[206:209], v200 offset:1024
	ds_read_b128 v[210:213], v200 offset:2048
	ds_read_b128 v[214:217], v200 offset:3072
	ds_read_b128 v[228:231], v200 offset:4096
	ds_read_b128 v[232:235], v200 offset:5120
	ds_read_b128 v[236:239], v200 offset:6144
	ds_read_b128 v[240:243], v200 offset:7168
	global_load_lds_dwordx4 v170, s[12:13]
	s_add_i32 m0, s54, 0xe000
	s_nop 0
	global_load_lds_dwordx4 v172, s[12:13]
	s_waitcnt vmcnt(8) lgkmcnt(0)
	s_barrier
	v_mfma_f32_16x16x32_bf16 v[150:153], v[66:69], v[202:205], v[150:153]
	v_mfma_f32_16x16x32_bf16 v[146:149], v[82:85], v[202:205], v[146:149]
	v_mfma_f32_16x16x32_bf16 v[134:137], v[66:69], v[210:213], v[134:137]
	v_mfma_f32_16x16x32_bf16 v[130:133], v[82:85], v[210:213], v[130:133]
	v_mfma_f32_16x16x32_bf16 v[118:121], v[66:69], v[228:231], v[118:121]
	v_mfma_f32_16x16x32_bf16 v[114:117], v[82:85], v[228:231], v[114:117]
	v_mfma_f32_16x16x32_bf16 v[102:105], v[66:69], v[236:239], v[102:105]
	v_mfma_f32_16x16x32_bf16 v[98:101], v[82:85], v[236:239], v[98:101]
	v_mfma_f32_16x16x32_bf16 v[150:153], v[74:77], v[206:209], v[150:153]
	v_mfma_f32_16x16x32_bf16 v[146:149], v[86:89], v[206:209], v[146:149]
	v_mfma_f32_16x16x32_bf16 v[134:137], v[74:77], v[214:217], v[134:137]
	v_mfma_f32_16x16x32_bf16 v[130:133], v[86:89], v[214:217], v[130:133]
	v_mfma_f32_16x16x32_bf16 v[118:121], v[74:77], v[232:235], v[118:121]
	v_mfma_f32_16x16x32_bf16 v[114:117], v[86:89], v[232:235], v[114:117]
	v_mfma_f32_16x16x32_bf16 v[102:105], v[74:77], v[240:243], v[102:105]
	v_mfma_f32_16x16x32_bf16 v[98:101], v[86:89], v[240:243], v[98:101]
	v_mfma_f32_16x16x32_bf16 v[142:145], v[154:157], v[202:205], v[142:145]
	v_mfma_f32_16x16x32_bf16 v[138:141], v[174:177], v[202:205], v[138:141]
	v_mfma_f32_16x16x32_bf16 v[126:129], v[154:157], v[210:213], v[126:129]
	v_mfma_f32_16x16x32_bf16 v[122:125], v[174:177], v[210:213], v[122:125]
	v_mfma_f32_16x16x32_bf16 v[110:113], v[154:157], v[228:231], v[110:113]
	v_mfma_f32_16x16x32_bf16 v[106:109], v[174:177], v[228:231], v[106:109]
	v_mfma_f32_16x16x32_bf16 v[94:97], v[154:157], v[236:239], v[94:97]
	v_mfma_f32_16x16x32_bf16 v[90:93], v[174:177], v[236:239], v[90:93]
	v_mfma_f32_16x16x32_bf16 v[142:145], v[158:161], v[206:209], v[142:145]
	v_mfma_f32_16x16x32_bf16 v[138:141], v[178:181], v[206:209], v[138:141]
	v_mfma_f32_16x16x32_bf16 v[126:129], v[158:161], v[214:217], v[126:129]
	v_mfma_f32_16x16x32_bf16 v[122:125], v[178:181], v[214:217], v[122:125]
	v_mfma_f32_16x16x32_bf16 v[110:113], v[158:161], v[232:235], v[110:113]
	v_mfma_f32_16x16x32_bf16 v[106:109], v[178:181], v[232:235], v[106:109]
	v_mfma_f32_16x16x32_bf16 v[94:97], v[158:161], v[240:243], v[94:97]
	v_mfma_f32_16x16x32_bf16 v[90:93], v[178:181], v[240:243], v[90:93]
	s_barrier
	s_add_i32 s70, s53, 0x10000
	v_lshl_add_u64 v[218:219], s[68:69], 0, v[0:1]
	s_mov_b32 m0, s70
	ds_read_b128 v[202:205], v200 offset:16384
	ds_read_b128 v[206:209], v200 offset:17408
	ds_read_b128 v[210:213], v200 offset:18432
	ds_read_b128 v[214:217], v200 offset:19456
	ds_read_b128 v[228:231], v200 offset:20480
	ds_read_b128 v[232:235], v200 offset:21504
	ds_read_b128 v[236:239], v200 offset:22528
	ds_read_b128 v[240:243], v200 offset:23552
	global_load_lds_dwordx4 v[218:219], off
	s_add_i32 m0, s70, 0x2000
	v_lshl_add_u64 v[244:245], s[68:69], 0, v[166:167]
	s_add_u32 s68, s68, s24
	s_addc_u32 s69, s69, s25
	s_add_i32 s70, s53, 0x14000
	global_load_lds_dwordx4 v[244:245], off
	s_mov_b32 m0, s70
	global_load_lds_dwordx4 v0, s[68:69]
	s_add_i32 m0, s70, 0x2000
	global_load_lds_dwordx4 v166, s[68:69]
	s_mov_b32 m0, s54
	global_load_lds_dwordx4 v162, s[14:15]
	s_mov_b32 m0, s55
	s_nop 0
	global_load_lds_dwordx4 v164, s[14:15]
	s_waitcnt vmcnt(8) lgkmcnt(0)
	s_barrier
	v_mfma_f32_16x16x32_bf16 v[78:81], v[66:69], v[202:205], v[78:81]
	v_mfma_f32_16x16x32_bf16 v[70:73], v[82:85], v[202:205], v[70:73]
	v_mfma_f32_16x16x32_bf16 v[46:49], v[66:69], v[210:213], v[46:49]
	v_mfma_f32_16x16x32_bf16 v[42:45], v[82:85], v[210:213], v[42:45]
	v_mfma_f32_16x16x32_bf16 v[30:33], v[66:69], v[228:231], v[30:33]
	v_mfma_f32_16x16x32_bf16 v[26:29], v[82:85], v[228:231], v[26:29]
	v_mfma_f32_16x16x32_bf16 v[14:17], v[66:69], v[236:239], v[14:17]
	v_mfma_f32_16x16x32_bf16 v[10:13], v[82:85], v[236:239], v[10:13]
	v_mfma_f32_16x16x32_bf16 v[78:81], v[74:77], v[206:209], v[78:81]
	v_mfma_f32_16x16x32_bf16 v[70:73], v[86:89], v[206:209], v[70:73]
	v_mfma_f32_16x16x32_bf16 v[46:49], v[74:77], v[214:217], v[46:49]
	v_mfma_f32_16x16x32_bf16 v[42:45], v[86:89], v[214:217], v[42:45]
	v_mfma_f32_16x16x32_bf16 v[30:33], v[74:77], v[232:235], v[30:33]
	v_mfma_f32_16x16x32_bf16 v[26:29], v[86:89], v[232:235], v[26:29]
	v_mfma_f32_16x16x32_bf16 v[14:17], v[74:77], v[240:243], v[14:17]
	v_mfma_f32_16x16x32_bf16 v[10:13], v[86:89], v[240:243], v[10:13]
	v_mfma_f32_16x16x32_bf16 v[60:63], v[154:157], v[202:205], v[62:65]
	v_mfma_f32_16x16x32_bf16 v[54:57], v[174:177], v[202:205], v[54:57]
	v_mfma_f32_16x16x32_bf16 v[38:41], v[154:157], v[210:213], v[38:41]
	v_mfma_f32_16x16x32_bf16 v[34:37], v[174:177], v[210:213], v[34:37]
	v_mfma_f32_16x16x32_bf16 v[22:25], v[154:157], v[228:231], v[22:25]
	v_mfma_f32_16x16x32_bf16 v[18:21], v[174:177], v[228:231], v[18:21]
	v_mfma_f32_16x16x32_bf16 v[6:9], v[154:157], v[236:239], v[6:9]
	v_mfma_f32_16x16x32_bf16 v[2:5], v[174:177], v[236:239], v[2:5]
	v_mfma_f32_16x16x32_bf16 v[60:63], v[158:161], v[206:209], v[60:63]
	v_mfma_f32_16x16x32_bf16 v[54:57], v[178:181], v[206:209], v[54:57]
	v_mfma_f32_16x16x32_bf16 v[38:41], v[158:161], v[214:217], v[38:41]
	v_mfma_f32_16x16x32_bf16 v[34:37], v[178:181], v[214:217], v[34:37]
	v_mfma_f32_16x16x32_bf16 v[22:25], v[158:161], v[232:235], v[22:25]
	v_mfma_f32_16x16x32_bf16 v[18:21], v[178:181], v[232:235], v[18:21]
	v_mfma_f32_16x16x32_bf16 v[6:9], v[158:161], v[240:243], v[6:9]
	v_mfma_f32_16x16x32_bf16 v[2:5], v[178:181], v[240:243], v[2:5]
	s_barrier
; #define PG8_STAGE(bufoff, gbase, voff) do { _Pragma("unroll") for (int _i = 0; _i < 2; ++_i) \
;         __builtin_amdgcn_global_load_lds((const unsigned*)((const char*)(gbase) + (voff)[_i]), (PG8_LAS unsigned*)(lds + (bufoff) + ldsw + _i * 8192), 16, 0, 0); } while (0)
; #define PG8_LDA(dst, b, h) do { _Pragma("unroll") for (int m = 0; m < 4; ++m) _Pragma("unroll") for (int k = 0; k < 2; ++k) dst[m][k] = *(const PG8_LAS bf16x8*)(lds + PG8_SA(b, h) + aoff + m * 2048 + k * 1024); } while (0)
; #define PG8_LDB(dst, b, h) do { _Pragma("unroll") for (int n = 0; n < 2; ++n) _Pragma("unroll") for (int k = 0; k < 2; ++k) dst[n][k] = *(const PG8_LAS bf16x8*)(lds + PG8_SB(b, h) + boff + n * 2048 + k * 1024); } while (0)
; #define PG8_MMA(ai, bj, At, Bt) do { __builtin_amdgcn_s_setprio(1); _Pragma("unroll") for (int m = 0; m < 4; ++m) _Pragma("unroll") for (int n = 0; n < 2; ++n) _Pragma("unroll") for (int k = 0; k < 2; ++k) \
;         acc[ai][bj][m][n] = __builtin_amdgcn_mfma_f32_16x16x32_bf16(Bt[n][k], At[m][k], acc[ai][bj][m][n], 0, 0, 0); __builtin_amdgcn_s_setprio(0); } while (0)
; #define PG8_WAIT_V(n) asm volatile("s_waitcnt vmcnt(" #n ")" ::: "memory")
; #define PG8_WAIT_L(n) asm volatile("s_waitcnt lgkmcnt(" #n ")" ::: "memory")
; #define PG8_BAR __builtin_amdgcn_s_barrier()
; template <class Epi, class Sched, bool ALIGN_EPI = false, bool SP2 = false>
; __device__ __forceinline__ void gemm_phase(PG8_LAS unsigned char* lds, const Gemm g, const Sched& S, const Epi& E, const int wv) {
;     ...
;         for (int t = 0; t < nt; t += 2) {
;             const bool last = (t == nt - 2);
;             const char* a1 = cA + (size_t)(t + 1) * kstep;
;             const char* a2 = last ? nA : cA + (size_t)(t + 2) * kstep; const char* b2 = last ? nB : cB + (size_t)(t + 2) * kstep;
;             const char* a3 = a2 + kstep; const char* b3 = b2 + kstep;
;     ...
;             PG8_LDB(B0, 1, 0); PG8_LDB(B1, 1, 1); PG8_SCHED; PG8_LDA(At, 1, 0); PG8_STAGE(PG8_SA(0, 1), a2 + hstepA, voffA);
;             PG8_WAIT_V(8); PG8_WAIT_L(0); PG8_BAR; PG8_MMA(0, 0, At, B0); PG8_MMA(0, 1, At, B1); PG8_BAR; PG8_SCHED;
;             PG8_LDA(At, 1, 1); PG8_STAGE(PG8_SB(1, 0), b3, voffB); PG8_STAGE(PG8_SB(1, 1), b3 + hstepB, voffB); PG8_STAGE(PG8_SA(1, 0), a3, voffA);
;             PG8_WAIT_V(8); PG8_WAIT_L(0); PG8_BAR; PG8_MMA(1, 0, At, B0); PG8_MMA(1, 1, At, B1); PG8_BAR; PG8_SCHED;
	ds_read_b128 v[64:67], v201
	ds_read_b128 v[74:77], v201 offset:1024
	ds_read_b128 v[82:85], v201 offset:2048
	ds_read_b128 v[86:89], v201 offset:3072
	ds_read_b128 v[154:157], v227
	ds_read_b128 v[158:161], v227 offset:1024
	ds_read_b128 v[174:177], v227 offset:2048
	ds_read_b128 v[178:181], v227 offset:3072
	s_mov_b32 m0, s56
	ds_read_b128 v[202:205], v200 offset:32768
	ds_read_b128 v[206:209], v200 offset:33792
	ds_read_b128 v[210:213], v200 offset:34816
	ds_read_b128 v[214:217], v200 offset:35840
	ds_read_b128 v[228:231], v200 offset:36864
	ds_read_b128 v[232:235], v200 offset:37888
	ds_read_b128 v[236:239], v200 offset:38912
	ds_read_b128 v[240:243], v200 offset:39936
	global_load_lds_dwordx4 v59, s[14:15]
	s_mov_b32 m0, s57
	s_nop 0
	global_load_lds_dwordx4 v246, s[14:15]
	s_waitcnt vmcnt(8) lgkmcnt(0)
	s_barrier
	v_mfma_f32_16x16x32_bf16 v[150:153], v[64:67], v[202:205], v[150:153]
	v_mfma_f32_16x16x32_bf16 v[146:149], v[82:85], v[202:205], v[146:149]
	v_mfma_f32_16x16x32_bf16 v[134:137], v[64:67], v[210:213], v[134:137]
	v_mfma_f32_16x16x32_bf16 v[130:133], v[82:85], v[210:213], v[130:133]
	v_mfma_f32_16x16x32_bf16 v[118:121], v[64:67], v[228:231], v[118:121]
	v_mfma_f32_16x16x32_bf16 v[114:117], v[82:85], v[228:231], v[114:117]
	v_mfma_f32_16x16x32_bf16 v[102:105], v[64:67], v[236:239], v[102:105]
	v_mfma_f32_16x16x32_bf16 v[98:101], v[82:85], v[236:239], v[98:101]
	v_mfma_f32_16x16x32_bf16 v[150:153], v[74:77], v[206:209], v[150:153]
	v_mfma_f32_16x16x32_bf16 v[146:149], v[86:89], v[206:209], v[146:149]
	v_mfma_f32_16x16x32_bf16 v[134:137], v[74:77], v[214:217], v[134:137]
	v_mfma_f32_16x16x32_bf16 v[130:133], v[86:89], v[214:217], v[130:133]
	v_mfma_f32_16x16x32_bf16 v[118:121], v[74:77], v[232:235], v[118:121]
	v_mfma_f32_16x16x32_bf16 v[114:117], v[86:89], v[232:235], v[114:117]
	v_mfma_f32_16x16x32_bf16 v[102:105], v[74:77], v[240:243], v[102:105]
	v_mfma_f32_16x16x32_bf16 v[98:101], v[86:89], v[240:243], v[98:101]
	v_mfma_f32_16x16x32_bf16 v[142:145], v[154:157], v[202:205], v[142:145]
	v_mfma_f32_16x16x32_bf16 v[138:141], v[174:177], v[202:205], v[138:141]
	v_mfma_f32_16x16x32_bf16 v[126:129], v[154:157], v[210:213], v[126:129]
	v_mfma_f32_16x16x32_bf16 v[122:125], v[174:177], v[210:213], v[122:125]
	v_mfma_f32_16x16x32_bf16 v[110:113], v[154:157], v[228:231], v[110:113]
	v_mfma_f32_16x16x32_bf16 v[106:109], v[174:177], v[228:231], v[106:109]
	v_mfma_f32_16x16x32_bf16 v[94:97], v[154:157], v[236:239], v[94:97]
	v_mfma_f32_16x16x32_bf16 v[90:93], v[174:177], v[236:239], v[90:93]
	v_mfma_f32_16x16x32_bf16 v[142:145], v[158:161], v[206:209], v[142:145]
	v_mfma_f32_16x16x32_bf16 v[138:141], v[178:181], v[206:209], v[138:141]
	v_mfma_f32_16x16x32_bf16 v[126:129], v[158:161], v[214:217], v[126:129]
	v_mfma_f32_16x16x32_bf16 v[122:125], v[178:181], v[214:217], v[122:125]
	v_mfma_f32_16x16x32_bf16 v[110:113], v[158:161], v[232:235], v[110:113]
	v_mfma_f32_16x16x32_bf16 v[106:109], v[178:181], v[232:235], v[106:109]
	v_mfma_f32_16x16x32_bf16 v[94:97], v[158:161], v[240:243], v[94:97]
	v_mfma_f32_16x16x32_bf16 v[90:93], v[178:181], v[240:243], v[90:93]
	s_barrier
	s_add_i32 m0, s53, 0x17f80
	ds_read_b128 v[202:205], v200 offset:49152
	ds_read_b128 v[206:209], v200 offset:50176
	ds_read_b128 v[210:213], v200 offset:51200
	ds_read_b128 v[214:217], v200 offset:52224
	ds_read_b128 v[228:231], v200 offset:53248
	ds_read_b128 v[232:235], v200 offset:54272
	ds_read_b128 v[236:239], v200 offset:55296
	ds_read_b128 v[240:243], v200 offset:56320
	global_load_lds_dwordx4 v[218:219], off offset:128
	s_add_i32 m0, s53, 0x19f80
	global_load_lds_dwordx4 v[244:245], off offset:128
	s_add_i32 m0, s53, 0x1bf80
	s_nop 0
	global_load_lds_dwordx4 v0, s[68:69] offset:128
	s_add_i32 m0, s53, 0x1df80
	s_nop 0
	global_load_lds_dwordx4 v166, s[68:69] offset:128
	s_add_i32 m0, s58, 0xffffff80
	s_nop 0
	global_load_lds_dwordx4 v162, s[14:15] offset:128
	s_add_i32 m0, s59, 0xffffff80
	s_nop 0
	global_load_lds_dwordx4 v164, s[14:15] offset:128
	s_waitcnt vmcnt(8) lgkmcnt(0)
	s_barrier
	v_mfma_f32_16x16x32_bf16 v[78:81], v[64:67], v[202:205], v[78:81]
	v_mfma_f32_16x16x32_bf16 v[68:71], v[82:85], v[202:205], v[70:73]
	v_mfma_f32_16x16x32_bf16 v[46:49], v[64:67], v[210:213], v[46:49]
	v_mfma_f32_16x16x32_bf16 v[42:45], v[82:85], v[210:213], v[42:45]
	v_mfma_f32_16x16x32_bf16 v[30:33], v[64:67], v[228:231], v[30:33]
	v_mfma_f32_16x16x32_bf16 v[26:29], v[82:85], v[228:231], v[26:29]
	v_mfma_f32_16x16x32_bf16 v[14:17], v[64:67], v[236:239], v[14:17]
	v_mfma_f32_16x16x32_bf16 v[10:13], v[82:85], v[236:239], v[10:13]
	v_mfma_f32_16x16x32_bf16 v[78:81], v[74:77], v[206:209], v[78:81]
	v_mfma_f32_16x16x32_bf16 v[70:73], v[86:89], v[206:209], v[68:71]
	v_mfma_f32_16x16x32_bf16 v[46:49], v[74:77], v[214:217], v[46:49]
	v_mfma_f32_16x16x32_bf16 v[42:45], v[86:89], v[214:217], v[42:45]
	v_mfma_f32_16x16x32_bf16 v[30:33], v[74:77], v[232:235], v[30:33]
	v_mfma_f32_16x16x32_bf16 v[26:29], v[86:89], v[232:235], v[26:29]
	v_mfma_f32_16x16x32_bf16 v[14:17], v[74:77], v[240:243], v[14:17]
	v_mfma_f32_16x16x32_bf16 v[10:13], v[86:89], v[240:243], v[10:13]
	v_mfma_f32_16x16x32_bf16 v[60:63], v[154:157], v[202:205], v[60:63]
	v_mfma_f32_16x16x32_bf16 v[54:57], v[174:177], v[202:205], v[54:57]
	v_mfma_f32_16x16x32_bf16 v[38:41], v[154:157], v[210:213], v[38:41]
	v_mfma_f32_16x16x32_bf16 v[34:37], v[174:177], v[210:213], v[34:37]
	v_mfma_f32_16x16x32_bf16 v[22:25], v[154:157], v[228:231], v[22:25]
	v_mfma_f32_16x16x32_bf16 v[18:21], v[174:177], v[228:231], v[18:21]
	v_mfma_f32_16x16x32_bf16 v[6:9], v[154:157], v[236:239], v[6:9]
	v_mfma_f32_16x16x32_bf16 v[2:5], v[174:177], v[236:239], v[2:5]
	v_mfma_f32_16x16x32_bf16 v[62:65], v[158:161], v[206:209], v[60:63]
	v_mfma_f32_16x16x32_bf16 v[54:57], v[178:181], v[206:209], v[54:57]
	v_mfma_f32_16x16x32_bf16 v[38:41], v[158:161], v[214:217], v[38:41]
	v_mfma_f32_16x16x32_bf16 v[34:37], v[178:181], v[214:217], v[34:37]
	v_mfma_f32_16x16x32_bf16 v[22:25], v[158:161], v[232:235], v[22:25]
	v_mfma_f32_16x16x32_bf16 v[18:21], v[178:181], v[232:235], v[18:21]
	v_mfma_f32_16x16x32_bf16 v[6:9], v[158:161], v[240:243], v[6:9]
	v_mfma_f32_16x16x32_bf16 v[2:5], v[178:181], v[240:243], v[2:5]
	s_barrier
	s_add_u32 s12, s12, 0x100
	s_addc_u32 s13, s13, 0
	s_add_u32 s42, s42, 0x100
	s_addc_u32 s43, s43, 0
	s_cmp_ge_i32 s67, s60
	s_mov_b32 s14, s67
	s_cbranch_scc0 .LBB0_176
	s_movk_i32 s68, 0x4000
	s_movk_i32 s69, 0x6000
	s_mov_b32 s70, 0x18000
	s_mov_b32 s71, 0x3f317217

;     __host__ __device__ bool next(int i, Unit& u) const { const int P = (i >> 1) * G + c; if (P >= 256) return false; u.pm = P >> 3; u.pn = (P & 7) + 8 * (i & 1); return true; }
; template <class Epi, class Sched, bool ALIGN_EPI = false, bool SP2 = false>
; __device__ __forceinline__ void gemm_phase(PG8_LAS unsigned char* lds, const Gemm g, const Sched& S, const Epi& E, const int wv) {
;     ...
;     for (;;) {
;         const bool has_next = S.next(ui + 1, nxt);
;         const char* nA = has_next ? (const char*)g.A + (size_t)nxt.pm * tstepA + (g.amod ? (size_t)(nxt.pn % g.amod) * K * 2 : (size_t)0) : cA; const char* nB = has_next ? (const char*)g.Bt + (size_t)nxt.pn * tstepB : cB;
;         for (int t = 0; t < nt; t += 2) {
;             const bool last = (t == nt - 2);
;             const char* a1 = cA + (size_t)(t + 1) * kstep;
;             const char* a2 = last ? nA : cA + (size_t)(t + 2) * kstep; const char* b2 = last ? nB : cB + (size_t)(t + 2) * kstep;
;             const char* a3 = a2 + kstep; const char* b3 = b2 + kstep;
;     ...
; #pragma unroll
;         for (int a = 0; a < 2; ++a)
; #pragma unroll
;             for (int b = 0; b < 2; ++b)
; #pragma unroll
;                 for (int m = 0; m < 4; ++m)
; #pragma unroll
;                     for (int n = 0; n < 2; ++n) acc[a][b][m][n] = (f32x4){0.f, 0.f, 0.f, 0.f};
.LBB0_334:
	v_mov_b32_e32 v141, 0
	s_andn2_b64 vcc, exec, s[34:35]
	v_mov_b32_e32 v140, v141
	v_pk_mov_b32 v[138:139], v[140:141], v[140:141]
	v_pk_mov_b32 v[144:145], v[140:141], v[140:141]
	v_pk_mov_b32 v[142:143], v[140:141], v[140:141]
	v_pk_mov_b32 v[128:129], v[140:141], v[140:141]
	v_pk_mov_b32 v[126:127], v[140:141], v[140:141]
	v_pk_mov_b32 v[124:125], v[140:141], v[140:141]
	v_pk_mov_b32 v[122:123], v[140:141], v[140:141]
	v_pk_mov_b32 v[112:113], v[140:141], v[140:141]
	v_pk_mov_b32 v[110:111], v[140:141], v[140:141]
	v_pk_mov_b32 v[108:109], v[140:141], v[140:141]
	v_pk_mov_b32 v[106:107], v[140:141], v[140:141]
	v_pk_mov_b32 v[96:97], v[140:141], v[140:141]
	v_pk_mov_b32 v[94:95], v[140:141], v[140:141]
	v_pk_mov_b32 v[92:93], v[140:141], v[140:141]
	v_pk_mov_b32 v[90:91], v[140:141], v[140:141]
	v_pk_mov_b32 v[136:137], v[140:141], v[140:141]
	v_pk_mov_b32 v[134:135], v[140:141], v[140:141]
	v_pk_mov_b32 v[132:133], v[140:141], v[140:141]
	v_pk_mov_b32 v[130:131], v[140:141], v[140:141]
	v_pk_mov_b32 v[120:121], v[140:141], v[140:141]
	v_pk_mov_b32 v[118:119], v[140:141], v[140:141]
	v_pk_mov_b32 v[116:117], v[140:141], v[140:141]
	v_pk_mov_b32 v[114:115], v[140:141], v[140:141]
	v_pk_mov_b32 v[104:105], v[140:141], v[140:141]
	v_pk_mov_b32 v[102:103], v[140:141], v[140:141]
	v_pk_mov_b32 v[100:101], v[140:141], v[140:141]
	v_pk_mov_b32 v[98:99], v[140:141], v[140:141]
	v_pk_mov_b32 v[88:89], v[140:141], v[140:141]
	v_pk_mov_b32 v[86:87], v[140:141], v[140:141]
	v_pk_mov_b32 v[84:85], v[140:141], v[140:141]
	v_pk_mov_b32 v[82:83], v[140:141], v[140:141]
	v_pk_mov_b32 v[80:81], v[140:141], v[140:141]
	v_pk_mov_b32 v[78:79], v[140:141], v[140:141]
	v_pk_mov_b32 v[76:77], v[140:141], v[140:141]
	v_pk_mov_b32 v[74:75], v[140:141], v[140:141]
	v_pk_mov_b32 v[64:65], v[140:141], v[140:141]
	v_pk_mov_b32 v[62:63], v[140:141], v[140:141]
	v_pk_mov_b32 v[60:61], v[140:141], v[140:141]
	v_pk_mov_b32 v[58:59], v[140:141], v[140:141]
	s_nop 0
	v_pk_mov_b32 v[40:41], v[140:141], v[140:141]
	v_pk_mov_b32 v[38:39], v[140:141], v[140:141]
	v_pk_mov_b32 v[36:37], v[140:141], v[140:141]
	v_pk_mov_b32 v[34:35], v[140:141], v[140:141]
	v_pk_mov_b32 v[16:17], v[140:141], v[140:141]
	v_pk_mov_b32 v[14:15], v[140:141], v[140:141]
	v_pk_mov_b32 v[12:13], v[140:141], v[140:141]
	v_pk_mov_b32 v[10:11], v[140:141], v[140:141]
	v_pk_mov_b32 v[72:73], v[140:141], v[140:141]
	v_pk_mov_b32 v[70:71], v[140:141], v[140:141]
	v_pk_mov_b32 v[68:69], v[140:141], v[140:141]
	v_pk_mov_b32 v[66:67], v[140:141], v[140:141]
	v_pk_mov_b32 v[56:57], v[140:141], v[140:141]
	v_pk_mov_b32 v[54:55], v[140:141], v[140:141]
	v_pk_mov_b32 v[52:53], v[140:141], v[140:141]
	v_pk_mov_b32 v[50:51], v[140:141], v[140:141]
	v_pk_mov_b32 v[24:25], v[140:141], v[140:141]
	v_pk_mov_b32 v[22:23], v[140:141], v[140:141]
	v_pk_mov_b32 v[20:21], v[140:141], v[140:141]
	v_pk_mov_b32 v[18:19], v[140:141], v[140:141]
	v_pk_mov_b32 v[8:9], v[140:141], v[140:141]
	v_pk_mov_b32 v[6:7], v[140:141], v[140:141]
	v_pk_mov_b32 v[4:5], v[140:141], v[140:141]
	v_pk_mov_b32 v[2:3], v[140:141], v[140:141]
	s_cbranch_vccnz .LBB0_337
	s_add_u32 s12, s40, 0x80080
	s_addc_u32 s13, s41, 0
	s_add_u32 s11, s14, 0x100
	v_mov_b32_e32 v2, 0
	s_addc_u32 s17, s15, 0
	s_mov_b32 s14, 0
	v_mov_b32_e32 v3, v2
	v_pk_mov_b32 v[4:5], v[2:3], v[2:3]
	v_pk_mov_b32 v[6:7], v[2:3], v[2:3]
	v_pk_mov_b32 v[8:9], v[2:3], v[2:3]
	v_pk_mov_b32 v[18:19], v[2:3], v[2:3]
	v_pk_mov_b32 v[20:21], v[2:3], v[2:3]
	v_pk_mov_b32 v[22:23], v[2:3], v[2:3]
	v_pk_mov_b32 v[24:25], v[2:3], v[2:3]
	v_pk_mov_b32 v[50:51], v[2:3], v[2:3]
	v_pk_mov_b32 v[52:53], v[2:3], v[2:3]
	v_pk_mov_b32 v[54:55], v[2:3], v[2:3]
	v_pk_mov_b32 v[56:57], v[2:3], v[2:3]
	v_pk_mov_b32 v[66:67], v[2:3], v[2:3]
	v_pk_mov_b32 v[68:69], v[2:3], v[2:3]
	v_pk_mov_b32 v[70:71], v[2:3], v[2:3]
	v_pk_mov_b32 v[72:73], v[2:3], v[2:3]
	v_pk_mov_b32 v[10:11], v[2:3], v[2:3]
	v_pk_mov_b32 v[12:13], v[2:3], v[2:3]
	v_pk_mov_b32 v[14:15], v[2:3], v[2:3]
	v_pk_mov_b32 v[16:17], v[2:3], v[2:3]
	v_pk_mov_b32 v[34:35], v[2:3], v[2:3]
	v_pk_mov_b32 v[36:37], v[2:3], v[2:3]
	v_pk_mov_b32 v[38:39], v[2:3], v[2:3]
	v_pk_mov_b32 v[40:41], v[2:3], v[2:3]
	v_pk_mov_b32 v[58:59], v[2:3], v[2:3]
	v_pk_mov_b32 v[60:61], v[2:3], v[2:3]
	v_pk_mov_b32 v[62:63], v[2:3], v[2:3]
	v_pk_mov_b32 v[64:65], v[2:3], v[2:3]
	v_pk_mov_b32 v[74:75], v[2:3], v[2:3]
	v_pk_mov_b32 v[76:77], v[2:3], v[2:3]
	v_pk_mov_b32 v[78:79], v[2:3], v[2:3]
	v_pk_mov_b32 v[80:81], v[2:3], v[2:3]
	v_pk_mov_b32 v[82:83], v[2:3], v[2:3]
	v_pk_mov_b32 v[84:85], v[2:3], v[2:3]
	v_pk_mov_b32 v[86:87], v[2:3], v[2:3]
	v_pk_mov_b32 v[88:89], v[2:3], v[2:3]
	v_pk_mov_b32 v[98:99], v[2:3], v[2:3]
	v_pk_mov_b32 v[100:101], v[2:3], v[2:3]
	v_pk_mov_b32 v[102:103], v[2:3], v[2:3]
	v_pk_mov_b32 v[104:105], v[2:3], v[2:3]
	v_pk_mov_b32 v[114:115], v[2:3], v[2:3]
	v_pk_mov_b32 v[116:117], v[2:3], v[2:3]
	v_pk_mov_b32 v[118:119], v[2:3], v[2:3]
	v_pk_mov_b32 v[120:121], v[2:3], v[2:3]
	v_pk_mov_b32 v[130:131], v[2:3], v[2:3]
	v_pk_mov_b32 v[132:133], v[2:3], v[2:3]
	v_pk_mov_b32 v[134:135], v[2:3], v[2:3]
	v_pk_mov_b32 v[136:137], v[2:3], v[2:3]
	v_pk_mov_b32 v[90:91], v[2:3], v[2:3]
	v_pk_mov_b32 v[92:93], v[2:3], v[2:3]
	v_pk_mov_b32 v[94:95], v[2:3], v[2:3]
	v_pk_mov_b32 v[96:97], v[2:3], v[2:3]
	v_pk_mov_b32 v[106:107], v[2:3], v[2:3]
	v_pk_mov_b32 v[108:109], v[2:3], v[2:3]
	v_pk_mov_b32 v[110:111], v[2:3], v[2:3]
	v_pk_mov_b32 v[112:113], v[2:3], v[2:3]
	v_pk_mov_b32 v[122:123], v[2:3], v[2:3]
	v_pk_mov_b32 v[124:125], v[2:3], v[2:3]
	v_pk_mov_b32 v[126:127], v[2:3], v[2:3]
	v_pk_mov_b32 v[128:129], v[2:3], v[2:3]
	v_pk_mov_b32 v[142:143], v[2:3], v[2:3]
	v_pk_mov_b32 v[144:145], v[2:3], v[2:3]
	v_pk_mov_b32 v[138:139], v[2:3], v[2:3]
	v_pk_mov_b32 v[140:141], v[2:3], v[2:3]
	v_add_u32_e32 v171, 0x10000, v197
	v_add_u32_e32 v227, 0x14000, v197
	v_add_u32_e32 v244, 0x18000, v197
	v_add_u32_e32 v245, 0x1c000, v197
	v_add_u32_e32 v246, 0x80000, v166
	v_add_u32_e32 v247, 0x80000, v164
; #define PG8_STAGE(bufoff, gbase, voff) do { _Pragma("unroll") for (int _i = 0; _i < 2; ++_i) \
;         __builtin_amdgcn_global_load_lds((const unsigned*)((const char*)(gbase) + (voff)[_i]), (PG8_LAS unsigned*)(lds + (bufoff) + ldsw + _i * 8192), 16, 0, 0); } while (0)
; #define PG8_LDA(dst, b, h) do { _Pragma("unroll") for (int m = 0; m < 4; ++m) _Pragma("unroll") for (int k = 0; k < 2; ++k) dst[m][k] = *(const PG8_LAS bf16x8*)(lds + PG8_SA(b, h) + aoff + m * 2048 + k * 1024); } while (0)
; #define PG8_LDB(dst, b, h) do { _Pragma("unroll") for (int n = 0; n < 2; ++n) _Pragma("unroll") for (int k = 0; k < 2; ++k) dst[n][k] = *(const PG8_LAS bf16x8*)(lds + PG8_SB(b, h) + boff + n * 2048 + k * 1024); } while (0)
; #define PG8_MMA(ai, bj, At, Bt) do { __builtin_amdgcn_s_setprio(1); _Pragma("unroll") for (int m = 0; m < 4; ++m) _Pragma("unroll") for (int n = 0; n < 2; ++n) _Pragma("unroll") for (int k = 0; k < 2; ++k) \
;         acc[ai][bj][m][n] = __builtin_amdgcn_mfma_f32_16x16x32_bf16(Bt[n][k], At[m][k], acc[ai][bj][m][n], 0, 0, 0); __builtin_amdgcn_s_setprio(0); } while (0)
; #define PG8_WAIT_V(n) asm volatile("s_waitcnt vmcnt(" #n ")" ::: "memory")
; #define PG8_BAR __builtin_amdgcn_s_barrier()
; template <class Epi, class Sched, bool ALIGN_EPI = false, bool SP2 = false>
; __device__ __forceinline__ void gemm_phase(PG8_LAS unsigned char* lds, const Gemm g, const Sched& S, const Epi& E, const int wv) {
;     ...
;         for (int t = 0; t < nt; t += 2) {
;             const bool last = (t == nt - 2);
;             const char* a1 = cA + (size_t)(t + 1) * kstep;
;             const char* a2 = last ? nA : cA + (size_t)(t + 2) * kstep; const char* b2 = last ? nB : cB + (size_t)(t + 2) * kstep;
;             const char* a3 = a2 + kstep; const char* b3 = b2 + kstep;
;             if (last && has_next) S.a_ready(nxt);
;             if constexpr (SP2) {
;             PG8_LDB(B0, 0, 0); PG8_LDB(B1, 0, 1); PG8_SCHED; PG8_LDA(At, 0, 0); PG8_STAGE(PG8_SA(1, 1), a1 + hstepA, voffA);
;             PG8_WAIT_V(8); PG8_WAIT_L(0); PG8_BAR; PG8_MMA(0, 0, At, B0); PG8_MMA(0, 1, At, B1); PG8_BAR; PG8_SCHED;
;             PG8_LDA(At, 0, 1); PG8_STAGE(PG8_SB(0, 0), b2, voffB); PG8_STAGE(PG8_SB(0, 1), b2 + hstepB, voffB); PG8_STAGE(PG8_SA(0, 0), a2, voffA);
;             PG8_WAIT_V(8); PG8_WAIT_L(0); PG8_BAR; PG8_MMA(1, 0, At, B0); PG8_MMA(1, 1, At, B1); PG8_BAR; PG8_SCHED;
.LBB0_336:
	s_add_i32 s40, s14, 2
	s_add_u32 s41, s12, 0xfff80080
	s_addc_u32 s15, s13, -1
	s_cmp_eq_u32 s62, s14
	s_cselect_b32 s15, s93, s15
	s_cselect_b32 s14, s92, s41
	s_cselect_b32 s45, s25, s17
	s_cselect_b32 s44, s24, s11
	ds_read_b128 v[26:29], v171
	ds_read_b128 v[30:33], v171 offset:1024
	ds_read_b128 v[42:45], v171 offset:2048
	ds_read_b128 v[46:49], v171 offset:3072
	ds_read_b128 v[146:149], v227
	ds_read_b128 v[150:153], v227 offset:1024
	ds_read_b128 v[154:157], v227 offset:2048
	ds_read_b128 v[158:161], v227 offset:3072
	s_add_i32 m0, s55, 0xc000
	ds_read_b128 v[172:175], v199
	ds_read_b128 v[176:179], v199 offset:1024
	ds_read_b128 v[180:183], v199 offset:2048
	ds_read_b128 v[200:203], v199 offset:3072
	ds_read_b128 v[204:207], v199 offset:4096
	ds_read_b128 v[208:211], v199 offset:5120
	ds_read_b128 v[212:215], v199 offset:6144
	ds_read_b128 v[216:219], v199 offset:7168
	global_load_lds_dwordx4 v168, s[12:13]
	s_add_i32 m0, s55, 0xe000
	s_nop 0
	global_load_lds_dwordx4 v170, s[12:13]
	s_waitcnt vmcnt(8) lgkmcnt(0)
	s_barrier
	v_mfma_f32_16x16x32_bf16 v[138:141], v[26:29], v[172:175], v[138:141]
	v_mfma_f32_16x16x32_bf16 v[142:145], v[42:45], v[172:175], v[142:145]
	v_mfma_f32_16x16x32_bf16 v[126:129], v[26:29], v[180:183], v[126:129]
	v_mfma_f32_16x16x32_bf16 v[122:125], v[42:45], v[180:183], v[122:125]
	v_mfma_f32_16x16x32_bf16 v[110:113], v[26:29], v[204:207], v[110:113]
	v_mfma_f32_16x16x32_bf16 v[106:109], v[42:45], v[204:207], v[106:109]
	v_mfma_f32_16x16x32_bf16 v[94:97], v[26:29], v[212:215], v[94:97]
	v_mfma_f32_16x16x32_bf16 v[90:93], v[42:45], v[212:215], v[90:93]
	v_mfma_f32_16x16x32_bf16 v[138:141], v[30:33], v[176:179], v[138:141]
	v_mfma_f32_16x16x32_bf16 v[142:145], v[46:49], v[176:179], v[142:145]
	v_mfma_f32_16x16x32_bf16 v[126:129], v[30:33], v[200:203], v[126:129]
	v_mfma_f32_16x16x32_bf16 v[122:125], v[46:49], v[200:203], v[122:125]
	v_mfma_f32_16x16x32_bf16 v[110:113], v[30:33], v[208:211], v[110:113]
	v_mfma_f32_16x16x32_bf16 v[106:109], v[46:49], v[208:211], v[106:109]
	v_mfma_f32_16x16x32_bf16 v[94:97], v[30:33], v[216:219], v[94:97]
	v_mfma_f32_16x16x32_bf16 v[90:93], v[46:49], v[216:219], v[90:93]
	v_mfma_f32_16x16x32_bf16 v[134:137], v[146:149], v[172:175], v[134:137]
	v_mfma_f32_16x16x32_bf16 v[130:133], v[154:157], v[172:175], v[130:133]
	v_mfma_f32_16x16x32_bf16 v[118:121], v[146:149], v[180:183], v[118:121]
	v_mfma_f32_16x16x32_bf16 v[114:117], v[154:157], v[180:183], v[114:117]
	v_mfma_f32_16x16x32_bf16 v[102:105], v[146:149], v[204:207], v[102:105]
	v_mfma_f32_16x16x32_bf16 v[98:101], v[154:157], v[204:207], v[98:101]
	v_mfma_f32_16x16x32_bf16 v[86:89], v[146:149], v[212:215], v[86:89]
	v_mfma_f32_16x16x32_bf16 v[82:85], v[154:157], v[212:215], v[82:85]
	v_mfma_f32_16x16x32_bf16 v[134:137], v[150:153], v[176:179], v[134:137]
	v_mfma_f32_16x16x32_bf16 v[130:133], v[158:161], v[176:179], v[130:133]
	v_mfma_f32_16x16x32_bf16 v[118:121], v[150:153], v[200:203], v[118:121]
	v_mfma_f32_16x16x32_bf16 v[114:117], v[158:161], v[200:203], v[114:117]
	v_mfma_f32_16x16x32_bf16 v[102:105], v[150:153], v[208:211], v[102:105]
	v_mfma_f32_16x16x32_bf16 v[98:101], v[158:161], v[208:211], v[98:101]
	v_mfma_f32_16x16x32_bf16 v[86:89], v[150:153], v[216:219], v[86:89]
	v_mfma_f32_16x16x32_bf16 v[82:85], v[158:161], v[216:219], v[82:85]
	s_barrier
	s_add_i32 s65, s54, 0x10000
	v_lshl_add_u64 v[184:185], s[44:45], 0, v[0:1]
	s_mov_b32 m0, s65
	ds_read_b128 v[172:175], v199 offset:16384
	ds_read_b128 v[176:179], v199 offset:17408
	ds_read_b128 v[180:183], v199 offset:18432
	ds_read_b128 v[200:203], v199 offset:19456
	ds_read_b128 v[204:207], v199 offset:20480
	ds_read_b128 v[208:211], v199 offset:21504
	ds_read_b128 v[212:215], v199 offset:22528
	ds_read_b128 v[216:219], v199 offset:23552
	global_load_lds_dwordx4 v[184:185], off
	s_add_i32 m0, s65, 0x2000
	v_lshl_add_u64 v[194:195], s[44:45], 0, v[162:163]
	s_add_u32 s44, s44, s28
	s_addc_u32 s45, s45, s29
	s_add_i32 s41, s54, 0x14000
	global_load_lds_dwordx4 v[194:195], off
	s_mov_b32 m0, s41
	global_load_lds_dwordx4 v0, s[44:45]
	s_add_i32 m0, s41, 0x2000
	global_load_lds_dwordx4 v162, s[44:45]
	s_mov_b32 m0, s55
	global_load_lds_dwordx4 v166, s[14:15]
	s_mov_b32 m0, s56
	s_nop 0
	global_load_lds_dwordx4 v164, s[14:15]
	s_waitcnt vmcnt(8) lgkmcnt(0)
	s_barrier
	v_mfma_f32_16x16x32_bf16 v[78:81], v[26:29], v[172:175], v[78:81]
	v_mfma_f32_16x16x32_bf16 v[74:77], v[42:45], v[172:175], v[74:77]
	v_mfma_f32_16x16x32_bf16 v[62:65], v[26:29], v[180:183], v[62:65]
	v_mfma_f32_16x16x32_bf16 v[58:61], v[42:45], v[180:183], v[58:61]
	v_mfma_f32_16x16x32_bf16 v[38:41], v[26:29], v[204:207], v[38:41]
	v_mfma_f32_16x16x32_bf16 v[34:37], v[42:45], v[204:207], v[34:37]
	v_mfma_f32_16x16x32_bf16 v[14:17], v[26:29], v[212:215], v[14:17]
	v_mfma_f32_16x16x32_bf16 v[10:13], v[42:45], v[212:215], v[10:13]
	v_mfma_f32_16x16x32_bf16 v[78:81], v[30:33], v[176:179], v[78:81]
	v_mfma_f32_16x16x32_bf16 v[74:77], v[46:49], v[176:179], v[74:77]
	v_mfma_f32_16x16x32_bf16 v[62:65], v[30:33], v[200:203], v[62:65]
	v_mfma_f32_16x16x32_bf16 v[58:61], v[46:49], v[200:203], v[58:61]
	v_mfma_f32_16x16x32_bf16 v[38:41], v[30:33], v[208:211], v[38:41]
	v_mfma_f32_16x16x32_bf16 v[34:37], v[46:49], v[208:211], v[34:37]
	v_mfma_f32_16x16x32_bf16 v[14:17], v[30:33], v[216:219], v[14:17]
	v_mfma_f32_16x16x32_bf16 v[10:13], v[46:49], v[216:219], v[10:13]
	v_mfma_f32_16x16x32_bf16 v[22:25], v[146:149], v[204:207], v[22:25]
	v_mfma_f32_16x16x32_bf16 v[18:21], v[154:157], v[204:207], v[18:21]
	v_mfma_f32_16x16x32_bf16 v[6:9], v[146:149], v[212:215], v[6:9]
	v_mfma_f32_16x16x32_bf16 v[2:5], v[154:157], v[212:215], v[2:5]
	v_mfma_f32_16x16x32_bf16 v[26:29], v[146:149], v[172:175], v[70:73]
	v_mfma_f32_16x16x32_bf16 v[30:33], v[154:157], v[172:175], v[66:69]
	v_mfma_f32_16x16x32_bf16 v[42:45], v[146:149], v[180:183], v[54:57]
	v_mfma_f32_16x16x32_bf16 v[46:49], v[154:157], v[180:183], v[50:53]
	v_mfma_f32_16x16x32_bf16 v[22:25], v[150:153], v[208:211], v[22:25]
	v_mfma_f32_16x16x32_bf16 v[18:21], v[158:161], v[208:211], v[18:21]
	v_mfma_f32_16x16x32_bf16 v[6:9], v[150:153], v[216:219], v[6:9]
	v_mfma_f32_16x16x32_bf16 v[2:5], v[158:161], v[216:219], v[2:5]
	v_mfma_f32_16x16x32_bf16 v[26:29], v[150:153], v[176:179], v[26:29]
	v_mfma_f32_16x16x32_bf16 v[30:33], v[158:161], v[176:179], v[30:33]
	v_mfma_f32_16x16x32_bf16 v[42:45], v[150:153], v[200:203], v[42:45]
	v_mfma_f32_16x16x32_bf16 v[46:49], v[158:161], v[200:203], v[46:49]
	s_barrier
; #define PG8_STAGE(bufoff, gbase, voff) do { _Pragma("unroll") for (int _i = 0; _i < 2; ++_i) \
;         __builtin_amdgcn_global_load_lds((const unsigned*)((const char*)(gbase) + (voff)[_i]), (PG8_LAS unsigned*)(lds + (bufoff) + ldsw + _i * 8192), 16, 0, 0); } while (0)
; #define PG8_LDA(dst, b, h) do { _Pragma("unroll") for (int m = 0; m < 4; ++m) _Pragma("unroll") for (int k = 0; k < 2; ++k) dst[m][k] = *(const PG8_LAS bf16x8*)(lds + PG8_SA(b, h) + aoff + m * 2048 + k * 1024); } while (0)
; #define PG8_LDB(dst, b, h) do { _Pragma("unroll") for (int n = 0; n < 2; ++n) _Pragma("unroll") for (int k = 0; k < 2; ++k) dst[n][k] = *(const PG8_LAS bf16x8*)(lds + PG8_SB(b, h) + boff + n * 2048 + k * 1024); } while (0)
; #define PG8_MMA(ai, bj, At, Bt) do { __builtin_amdgcn_s_setprio(1); _Pragma("unroll") for (int m = 0; m < 4; ++m) _Pragma("unroll") for (int n = 0; n < 2; ++n) _Pragma("unroll") for (int k = 0; k < 2; ++k) \
;         acc[ai][bj][m][n] = __builtin_amdgcn_mfma_f32_16x16x32_bf16(Bt[n][k], At[m][k], acc[ai][bj][m][n], 0, 0, 0); __builtin_amdgcn_s_setprio(0); } while (0)
; #define PG8_WAIT_V(n) asm volatile("s_waitcnt vmcnt(" #n ")" ::: "memory")
; #define PG8_WAIT_L(n) asm volatile("s_waitcnt lgkmcnt(" #n ")" ::: "memory")
; #define PG8_BAR __builtin_amdgcn_s_barrier()
; template <class Epi, class Sched, bool ALIGN_EPI = false, bool SP2 = false>
; __device__ __forceinline__ void gemm_phase(PG8_LAS unsigned char* lds, const Gemm g, const Sched& S, const Epi& E, const int wv) {
;     ...
;         for (int t = 0; t < nt; t += 2) {
;             const bool last = (t == nt - 2);
;             const char* a1 = cA + (size_t)(t + 1) * kstep;
;             const char* a2 = last ? nA : cA + (size_t)(t + 2) * kstep; const char* b2 = last ? nB : cB + (size_t)(t + 2) * kstep;
;             const char* a3 = a2 + kstep; const char* b3 = b2 + kstep;
;     ...
;             PG8_LDB(B0, 1, 0); PG8_LDB(B1, 1, 1); PG8_SCHED; PG8_LDA(At, 1, 0); PG8_STAGE(PG8_SA(0, 1), a2 + hstepA, voffA);
;             PG8_WAIT_V(8); PG8_WAIT_L(0); PG8_BAR; PG8_MMA(0, 0, At, B0); PG8_MMA(0, 1, At, B1); PG8_BAR; PG8_SCHED;
;             PG8_LDA(At, 1, 1); PG8_STAGE(PG8_SB(1, 0), b3, voffB); PG8_STAGE(PG8_SB(1, 1), b3 + hstepB, voffB); PG8_STAGE(PG8_SA(1, 0), a3, voffA);
;             PG8_WAIT_V(8); PG8_WAIT_L(0); PG8_BAR; PG8_MMA(1, 0, At, B0); PG8_MMA(1, 1, At, B1); PG8_BAR; PG8_SCHED;
	ds_read_b128 v[50:53], v244
	ds_read_b128 v[54:57], v244 offset:1024
	ds_read_b128 v[66:69], v244 offset:2048
	ds_read_b128 v[70:73], v244 offset:3072
	ds_read_b128 v[146:149], v245
	ds_read_b128 v[150:153], v245 offset:1024
	ds_read_b128 v[154:157], v245 offset:2048
	ds_read_b128 v[158:161], v245 offset:3072
	s_mov_b32 m0, s57
	ds_read_b128 v[172:175], v199 offset:32768
	ds_read_b128 v[176:179], v199 offset:33792
	ds_read_b128 v[180:183], v199 offset:34816
	ds_read_b128 v[200:203], v199 offset:35840
	ds_read_b128 v[204:207], v199 offset:36864
	ds_read_b128 v[208:211], v199 offset:37888
	ds_read_b128 v[212:215], v199 offset:38912
	ds_read_b128 v[216:219], v199 offset:39936
	global_load_lds_dwordx4 v246, s[14:15]
	s_mov_b32 m0, s58
	s_nop 0
	global_load_lds_dwordx4 v247, s[14:15]
	s_waitcnt vmcnt(8) lgkmcnt(0)
	s_barrier
	v_mfma_f32_16x16x32_bf16 v[138:141], v[50:53], v[172:175], v[138:141]
	v_mfma_f32_16x16x32_bf16 v[142:145], v[66:69], v[172:175], v[142:145]
	v_mfma_f32_16x16x32_bf16 v[126:129], v[50:53], v[180:183], v[126:129]
	v_mfma_f32_16x16x32_bf16 v[122:125], v[66:69], v[180:183], v[122:125]
	v_mfma_f32_16x16x32_bf16 v[110:113], v[50:53], v[204:207], v[110:113]
	v_mfma_f32_16x16x32_bf16 v[106:109], v[66:69], v[204:207], v[106:109]
	v_mfma_f32_16x16x32_bf16 v[94:97], v[50:53], v[212:215], v[94:97]
	v_mfma_f32_16x16x32_bf16 v[90:93], v[66:69], v[212:215], v[90:93]
	v_mfma_f32_16x16x32_bf16 v[138:141], v[54:57], v[176:179], v[138:141]
	v_mfma_f32_16x16x32_bf16 v[142:145], v[70:73], v[176:179], v[142:145]
	v_mfma_f32_16x16x32_bf16 v[126:129], v[54:57], v[200:203], v[126:129]
	v_mfma_f32_16x16x32_bf16 v[122:125], v[70:73], v[200:203], v[122:125]
	v_mfma_f32_16x16x32_bf16 v[110:113], v[54:57], v[208:211], v[110:113]
	v_mfma_f32_16x16x32_bf16 v[106:109], v[70:73], v[208:211], v[106:109]
	v_mfma_f32_16x16x32_bf16 v[94:97], v[54:57], v[216:219], v[94:97]
	v_mfma_f32_16x16x32_bf16 v[90:93], v[70:73], v[216:219], v[90:93]
	v_mfma_f32_16x16x32_bf16 v[134:137], v[146:149], v[172:175], v[134:137]
	v_mfma_f32_16x16x32_bf16 v[130:133], v[154:157], v[172:175], v[130:133]
	v_mfma_f32_16x16x32_bf16 v[118:121], v[146:149], v[180:183], v[118:121]
	v_mfma_f32_16x16x32_bf16 v[114:117], v[154:157], v[180:183], v[114:117]
	v_mfma_f32_16x16x32_bf16 v[102:105], v[146:149], v[204:207], v[102:105]
	v_mfma_f32_16x16x32_bf16 v[98:101], v[154:157], v[204:207], v[98:101]
	v_mfma_f32_16x16x32_bf16 v[86:89], v[146:149], v[212:215], v[86:89]
	v_mfma_f32_16x16x32_bf16 v[82:85], v[154:157], v[212:215], v[82:85]
	v_mfma_f32_16x16x32_bf16 v[134:137], v[150:153], v[176:179], v[134:137]
	v_mfma_f32_16x16x32_bf16 v[130:133], v[158:161], v[176:179], v[130:133]
	v_mfma_f32_16x16x32_bf16 v[118:121], v[150:153], v[200:203], v[118:121]
	v_mfma_f32_16x16x32_bf16 v[114:117], v[158:161], v[200:203], v[114:117]
	v_mfma_f32_16x16x32_bf16 v[102:105], v[150:153], v[208:211], v[102:105]
	v_mfma_f32_16x16x32_bf16 v[98:101], v[158:161], v[208:211], v[98:101]
	v_mfma_f32_16x16x32_bf16 v[86:89], v[150:153], v[216:219], v[86:89]
	v_mfma_f32_16x16x32_bf16 v[82:85], v[158:161], v[216:219], v[82:85]
	s_barrier
	s_add_i32 m0, s54, 0x17f80
	ds_read_b128 v[172:175], v199 offset:49152
	ds_read_b128 v[176:179], v199 offset:50176
	ds_read_b128 v[180:183], v199 offset:51200
	ds_read_b128 v[200:203], v199 offset:52224
	ds_read_b128 v[204:207], v199 offset:53248
	ds_read_b128 v[208:211], v199 offset:54272
	ds_read_b128 v[212:215], v199 offset:55296
	ds_read_b128 v[216:219], v199 offset:56320
	global_load_lds_dwordx4 v[184:185], off offset:128
	s_add_i32 m0, s54, 0x19f80
	global_load_lds_dwordx4 v[194:195], off offset:128
	s_add_i32 m0, s54, 0x1bf80
	s_nop 0
	global_load_lds_dwordx4 v0, s[44:45] offset:128
	s_add_i32 m0, s54, 0x1df80
	s_nop 0
	global_load_lds_dwordx4 v162, s[44:45] offset:128
	s_add_i32 m0, s60, 0xffffff80
	s_nop 0
	global_load_lds_dwordx4 v166, s[14:15] offset:128
	s_add_i32 m0, s61, 0xffffff80
	s_nop 0
	global_load_lds_dwordx4 v164, s[14:15] offset:128
	s_waitcnt vmcnt(8) lgkmcnt(0)
	s_barrier
	v_mfma_f32_16x16x32_bf16 v[78:81], v[50:53], v[172:175], v[78:81]
	v_mfma_f32_16x16x32_bf16 v[74:77], v[66:69], v[172:175], v[74:77]
	v_mfma_f32_16x16x32_bf16 v[62:65], v[50:53], v[180:183], v[62:65]
	v_mfma_f32_16x16x32_bf16 v[58:61], v[66:69], v[180:183], v[58:61]
	v_mfma_f32_16x16x32_bf16 v[38:41], v[50:53], v[204:207], v[38:41]
	v_mfma_f32_16x16x32_bf16 v[34:37], v[66:69], v[204:207], v[34:37]
	v_mfma_f32_16x16x32_bf16 v[14:17], v[50:53], v[212:215], v[14:17]
	v_mfma_f32_16x16x32_bf16 v[10:13], v[66:69], v[212:215], v[10:13]
	v_mfma_f32_16x16x32_bf16 v[78:81], v[54:57], v[176:179], v[78:81]
	v_mfma_f32_16x16x32_bf16 v[74:77], v[70:73], v[176:179], v[74:77]
	v_mfma_f32_16x16x32_bf16 v[62:65], v[54:57], v[200:203], v[62:65]
	v_mfma_f32_16x16x32_bf16 v[58:61], v[70:73], v[200:203], v[58:61]
	v_mfma_f32_16x16x32_bf16 v[38:41], v[54:57], v[208:211], v[38:41]
	v_mfma_f32_16x16x32_bf16 v[34:37], v[70:73], v[208:211], v[34:37]
	v_mfma_f32_16x16x32_bf16 v[14:17], v[54:57], v[216:219], v[14:17]
	v_mfma_f32_16x16x32_bf16 v[10:13], v[70:73], v[216:219], v[10:13]
	v_mfma_f32_16x16x32_bf16 v[26:29], v[146:149], v[172:175], v[26:29]
	v_mfma_f32_16x16x32_bf16 v[70:73], v[150:153], v[176:179], v[26:29]
	v_mfma_f32_16x16x32_bf16 v[26:29], v[154:157], v[172:175], v[30:33]
	v_mfma_f32_16x16x32_bf16 v[66:69], v[158:161], v[176:179], v[26:29]
	v_mfma_f32_16x16x32_bf16 v[26:29], v[146:149], v[180:183], v[42:45]
	v_mfma_f32_16x16x32_bf16 v[54:57], v[150:153], v[200:203], v[26:29]
	v_mfma_f32_16x16x32_bf16 v[26:29], v[154:157], v[180:183], v[46:49]
	v_mfma_f32_16x16x32_bf16 v[22:25], v[146:149], v[204:207], v[22:25]
	v_mfma_f32_16x16x32_bf16 v[18:21], v[154:157], v[204:207], v[18:21]
	v_mfma_f32_16x16x32_bf16 v[6:9], v[146:149], v[212:215], v[6:9]
	v_mfma_f32_16x16x32_bf16 v[2:5], v[154:157], v[212:215], v[2:5]
	v_mfma_f32_16x16x32_bf16 v[50:53], v[158:161], v[200:203], v[26:29]
	v_mfma_f32_16x16x32_bf16 v[22:25], v[150:153], v[208:211], v[22:25]
	v_mfma_f32_16x16x32_bf16 v[18:21], v[158:161], v[208:211], v[18:21]
	v_mfma_f32_16x16x32_bf16 v[6:9], v[150:153], v[216:219], v[6:9]
	v_mfma_f32_16x16x32_bf16 v[2:5], v[158:161], v[216:219], v[2:5]
	s_barrier
	s_add_u32 s12, s12, 0x100
	s_addc_u32 s13, s13, 0
	s_add_u32 s11, s11, 0x100
	s_addc_u32 s17, s17, 0
	s_cmp_ge_i32 s40, s59
	s_mov_b32 s14, s40
	s_cbranch_scc0 .LBB0_336

;     __host__ __device__ bool next(int i, Unit& u) const { const int P = (i >> 1) * G + c; if (P >= 256) return false; u.pm = P >> 3; u.pn = (P & 7) + 8 * (i & 1); return true; }
; #define PG8_STAGE(bufoff, gbase, voff) do { _Pragma("unroll") for (int _i = 0; _i < 2; ++_i) \
;         __builtin_amdgcn_global_load_lds((const unsigned*)((const char*)(gbase) + (voff)[_i]), (PG8_LAS unsigned*)(lds + (bufoff) + ldsw + _i * 8192), 16, 0, 0); } while (0)
; #define PG8_LDA(dst, b, h) do { _Pragma("unroll") for (int m = 0; m < 4; ++m) _Pragma("unroll") for (int k = 0; k < 2; ++k) dst[m][k] = *(const PG8_LAS bf16x8*)(lds + PG8_SA(b, h) + aoff + m * 2048 + k * 1024); } while (0)
; #define PG8_LDB(dst, b, h) do { _Pragma("unroll") for (int n = 0; n < 2; ++n) _Pragma("unroll") for (int k = 0; k < 2; ++k) dst[n][k] = *(const PG8_LAS bf16x8*)(lds + PG8_SB(b, h) + boff + n * 2048 + k * 1024); } while (0)
; #define PG8_WAIT_V(n) asm volatile("s_waitcnt vmcnt(" #n ")" ::: "memory")
; #define PG8_WAIT_L(n) asm volatile("s_waitcnt lgkmcnt(" #n ")" ::: "memory")
; #define PG8_BAR __builtin_amdgcn_s_barrier()
; #define PG8_SCHED __builtin_amdgcn_sched_barrier(0)
; template <class Epi, class Sched, bool ALIGN_EPI = false, bool SP2 = false>
; __device__ __forceinline__ void gemm_phase(PG8_LAS unsigned char* lds, const Gemm g, const Sched& S, const Epi& E, const int wv) {
;     ...
;     for (;;) {
;         const bool has_next = S.next(ui + 1, nxt);
;         const char* nA = has_next ? (const char*)g.A + (size_t)nxt.pm * tstepA + (g.amod ? (size_t)(nxt.pn % g.amod) * K * 2 : (size_t)0) : cA; const char* nB = has_next ? (const char*)g.Bt + (size_t)nxt.pn * tstepB : cB;
;         for (int t = 0; t < nt; t += 2) {
;             const bool last = (t == nt - 2);
;             const char* a1 = cA + (size_t)(t + 1) * kstep;
;             const char* a2 = last ? nA : cA + (size_t)(t + 2) * kstep; const char* b2 = last ? nB : cB + (size_t)(t + 2) * kstep;
;             const char* a3 = a2 + kstep; const char* b3 = b2 + kstep;
;             if (last && has_next) S.a_ready(nxt);
;             if constexpr (SP2) {
;             PG8_LDB(B0, 0, 0); PG8_LDB(B1, 0, 1); PG8_SCHED; PG8_LDA(At, 0, 0); PG8_STAGE(PG8_SA(1, 1), a1 + hstepA, voffA);
;             PG8_WAIT_V(8); PG8_WAIT_L(0); PG8_BAR; PG8_MMA(0, 0, At, B0); PG8_MMA(0, 1, At, B1); PG8_BAR; PG8_SCHED;
.LBB0_698:
	s_and_b64 s[44:45], s[44:45], exec
	s_cselect_b32 s31, s15, s55
	s_cselect_b32 s71, s14, s54
	s_add_u32 s44, s54, 0x80080
	s_addc_u32 s45, s55, 0
	s_add_u32 s56, s56, 0x100
	v_mov_b32_e32 v2, 0
	s_addc_u32 s57, s57, 0
	s_mov_b32 s54, 0
	v_mov_b32_e32 v3, v2
	v_pk_mov_b32 v[4:5], v[2:3], v[2:3]
	v_pk_mov_b32 v[6:7], v[2:3], v[2:3]
	v_pk_mov_b32 v[8:9], v[2:3], v[2:3]
	v_pk_mov_b32 v[18:19], v[2:3], v[2:3]
	v_pk_mov_b32 v[20:21], v[2:3], v[2:3]
	v_pk_mov_b32 v[22:23], v[2:3], v[2:3]
	v_pk_mov_b32 v[24:25], v[2:3], v[2:3]
	v_pk_mov_b32 v[34:35], v[2:3], v[2:3]
	v_pk_mov_b32 v[36:37], v[2:3], v[2:3]
	v_pk_mov_b32 v[38:39], v[2:3], v[2:3]
	v_pk_mov_b32 v[40:41], v[2:3], v[2:3]
	v_pk_mov_b32 v[50:51], v[2:3], v[2:3]
	v_pk_mov_b32 v[52:53], v[2:3], v[2:3]
	v_pk_mov_b32 v[54:55], v[2:3], v[2:3]
	v_pk_mov_b32 v[56:57], v[2:3], v[2:3]
	v_pk_mov_b32 v[10:11], v[2:3], v[2:3]
	v_pk_mov_b32 v[12:13], v[2:3], v[2:3]
	v_pk_mov_b32 v[14:15], v[2:3], v[2:3]
	v_pk_mov_b32 v[16:17], v[2:3], v[2:3]
	v_pk_mov_b32 v[26:27], v[2:3], v[2:3]
	v_pk_mov_b32 v[28:29], v[2:3], v[2:3]
	v_pk_mov_b32 v[30:31], v[2:3], v[2:3]
	v_pk_mov_b32 v[32:33], v[2:3], v[2:3]
	v_pk_mov_b32 v[42:43], v[2:3], v[2:3]
	v_pk_mov_b32 v[44:45], v[2:3], v[2:3]
	v_pk_mov_b32 v[46:47], v[2:3], v[2:3]
	v_pk_mov_b32 v[48:49], v[2:3], v[2:3]
	v_pk_mov_b32 v[58:59], v[2:3], v[2:3]
	v_pk_mov_b32 v[60:61], v[2:3], v[2:3]
	v_pk_mov_b32 v[62:63], v[2:3], v[2:3]
	v_pk_mov_b32 v[64:65], v[2:3], v[2:3]
	v_pk_mov_b32 v[66:67], v[2:3], v[2:3]
	v_pk_mov_b32 v[68:69], v[2:3], v[2:3]
	v_pk_mov_b32 v[70:71], v[2:3], v[2:3]
	v_pk_mov_b32 v[72:73], v[2:3], v[2:3]
	v_pk_mov_b32 v[82:83], v[2:3], v[2:3]
	v_pk_mov_b32 v[84:85], v[2:3], v[2:3]
	v_pk_mov_b32 v[86:87], v[2:3], v[2:3]
	v_pk_mov_b32 v[88:89], v[2:3], v[2:3]
	v_pk_mov_b32 v[98:99], v[2:3], v[2:3]
	v_pk_mov_b32 v[100:101], v[2:3], v[2:3]
	v_pk_mov_b32 v[102:103], v[2:3], v[2:3]
	v_pk_mov_b32 v[104:105], v[2:3], v[2:3]
	v_pk_mov_b32 v[118:119], v[2:3], v[2:3]
	v_pk_mov_b32 v[120:121], v[2:3], v[2:3]
	v_pk_mov_b32 v[122:123], v[2:3], v[2:3]
	v_pk_mov_b32 v[124:125], v[2:3], v[2:3]
	v_pk_mov_b32 v[74:75], v[2:3], v[2:3]
	v_pk_mov_b32 v[76:77], v[2:3], v[2:3]
	v_pk_mov_b32 v[78:79], v[2:3], v[2:3]
	v_pk_mov_b32 v[80:81], v[2:3], v[2:3]
	v_pk_mov_b32 v[90:91], v[2:3], v[2:3]
	v_pk_mov_b32 v[92:93], v[2:3], v[2:3]
	v_pk_mov_b32 v[94:95], v[2:3], v[2:3]
	v_pk_mov_b32 v[96:97], v[2:3], v[2:3]
	v_pk_mov_b32 v[106:107], v[2:3], v[2:3]
	v_pk_mov_b32 v[108:109], v[2:3], v[2:3]
	v_pk_mov_b32 v[110:111], v[2:3], v[2:3]
	v_pk_mov_b32 v[112:113], v[2:3], v[2:3]
	v_pk_mov_b32 v[130:131], v[2:3], v[2:3]
	v_pk_mov_b32 v[132:133], v[2:3], v[2:3]
	v_pk_mov_b32 v[134:135], v[2:3], v[2:3]
	v_pk_mov_b32 v[136:137], v[2:3], v[2:3]
	v_add_u32_e32 v190, 0x10000, v230
	v_add_u32_e32 v191, 0x14000, v230
	v_add_u32_e32 v192, 0x18000, v230
	v_add_u32_e32 v193, 0x1c000, v230
	v_add_u32_e32 v115, 0x80000, v194
	v_add_u32_e32 v201, 0x80000, v196
.LBB0_699:
	s_add_i32 s72, s54, 2
	s_add_u32 s73, s44, 0xfff80080
	s_addc_u32 s55, s45, -1
	s_cmp_eq_u32 s66, s54
	s_cselect_b32 s55, s31, s55
	s_cselect_b32 s54, s71, s73
	s_cselect_b32 s75, s13, s57
	s_cselect_b32 s74, s12, s56
	ds_read_b128 v[126:129], v190
	ds_read_b128 v[138:141], v190 offset:1024
	ds_read_b128 v[142:145], v190 offset:2048
	ds_read_b128 v[146:149], v190 offset:3072
	ds_read_b128 v[150:153], v191
	ds_read_b128 v[154:157], v191 offset:1024
	ds_read_b128 v[158:161], v191 offset:2048
	ds_read_b128 v[162:165], v191 offset:3072
	s_add_i32 m0, s59, 0xc000
	ds_read_b128 v[166:169], v235
	ds_read_b128 v[170:173], v235 offset:1024
	ds_read_b128 v[174:177], v235 offset:2048
	ds_read_b128 v[178:181], v235 offset:3072
	ds_read_b128 v[182:185], v235 offset:4096
	ds_read_b128 v[204:207], v235 offset:5120
	ds_read_b128 v[208:211], v235 offset:6144
	ds_read_b128 v[212:215], v235 offset:7168
	global_load_lds_dwordx4 v200, s[44:45]
	s_add_i32 m0, s59, 0xe000
	s_nop 0
	global_load_lds_dwordx4 v202, s[44:45]
	s_waitcnt vmcnt(8) lgkmcnt(0)
	s_barrier
	v_mfma_f32_16x16x32_bf16 v[134:137], v[126:129], v[166:169], v[134:137]
	v_mfma_f32_16x16x32_bf16 v[130:133], v[142:145], v[166:169], v[130:133]
	v_mfma_f32_16x16x32_bf16 v[110:113], v[126:129], v[174:177], v[110:113]
	v_mfma_f32_16x16x32_bf16 v[106:109], v[142:145], v[174:177], v[106:109]
	v_mfma_f32_16x16x32_bf16 v[94:97], v[126:129], v[182:185], v[94:97]
	v_mfma_f32_16x16x32_bf16 v[90:93], v[142:145], v[182:185], v[90:93]
	v_mfma_f32_16x16x32_bf16 v[78:81], v[126:129], v[208:211], v[78:81]
	v_mfma_f32_16x16x32_bf16 v[74:77], v[142:145], v[208:211], v[74:77]
	v_mfma_f32_16x16x32_bf16 v[134:137], v[138:141], v[170:173], v[134:137]
	v_mfma_f32_16x16x32_bf16 v[130:133], v[146:149], v[170:173], v[130:133]
	v_mfma_f32_16x16x32_bf16 v[110:113], v[138:141], v[178:181], v[110:113]
	v_mfma_f32_16x16x32_bf16 v[106:109], v[146:149], v[178:181], v[106:109]
	v_mfma_f32_16x16x32_bf16 v[94:97], v[138:141], v[204:207], v[94:97]
	v_mfma_f32_16x16x32_bf16 v[90:93], v[146:149], v[204:207], v[90:93]
	v_mfma_f32_16x16x32_bf16 v[78:81], v[138:141], v[212:215], v[78:81]
	v_mfma_f32_16x16x32_bf16 v[74:77], v[146:149], v[212:215], v[74:77]
	v_mfma_f32_16x16x32_bf16 v[122:125], v[150:153], v[166:169], v[122:125]
	v_mfma_f32_16x16x32_bf16 v[116:119], v[158:161], v[166:169], v[118:121]
	v_mfma_f32_16x16x32_bf16 v[102:105], v[150:153], v[174:177], v[102:105]
	v_mfma_f32_16x16x32_bf16 v[98:101], v[158:161], v[174:177], v[98:101]
	v_mfma_f32_16x16x32_bf16 v[86:89], v[150:153], v[182:185], v[86:89]
	v_mfma_f32_16x16x32_bf16 v[82:85], v[158:161], v[182:185], v[82:85]
	v_mfma_f32_16x16x32_bf16 v[70:73], v[150:153], v[208:211], v[70:73]
	v_mfma_f32_16x16x32_bf16 v[66:69], v[158:161], v[208:211], v[66:69]
	v_mfma_f32_16x16x32_bf16 v[122:125], v[154:157], v[170:173], v[122:125]
	v_mfma_f32_16x16x32_bf16 v[116:119], v[162:165], v[170:173], v[116:119]
	v_mfma_f32_16x16x32_bf16 v[102:105], v[154:157], v[178:181], v[102:105]
	v_mfma_f32_16x16x32_bf16 v[98:101], v[162:165], v[178:181], v[98:101]
	v_mfma_f32_16x16x32_bf16 v[86:89], v[154:157], v[204:207], v[86:89]
	v_mfma_f32_16x16x32_bf16 v[82:85], v[162:165], v[204:207], v[82:85]
	v_mfma_f32_16x16x32_bf16 v[70:73], v[154:157], v[212:215], v[70:73]
	v_mfma_f32_16x16x32_bf16 v[66:69], v[162:165], v[212:215], v[66:69]
	s_barrier
; #define PG8_STAGE(bufoff, gbase, voff) do { _Pragma("unroll") for (int _i = 0; _i < 2; ++_i) \
;         __builtin_amdgcn_global_load_lds((const unsigned*)((const char*)(gbase) + (voff)[_i]), (PG8_LAS unsigned*)(lds + (bufoff) + ldsw + _i * 8192), 16, 0, 0); } while (0)
; #define PG8_LDA(dst, b, h) do { _Pragma("unroll") for (int m = 0; m < 4; ++m) _Pragma("unroll") for (int k = 0; k < 2; ++k) dst[m][k] = *(const PG8_LAS bf16x8*)(lds + PG8_SA(b, h) + aoff + m * 2048 + k * 1024); } while (0)
; #define PG8_LDB(dst, b, h) do { _Pragma("unroll") for (int n = 0; n < 2; ++n) _Pragma("unroll") for (int k = 0; k < 2; ++k) dst[n][k] = *(const PG8_LAS bf16x8*)(lds + PG8_SB(b, h) + boff + n * 2048 + k * 1024); } while (0)
; #define PG8_MMA(ai, bj, At, Bt) do { __builtin_amdgcn_s_setprio(1); _Pragma("unroll") for (int m = 0; m < 4; ++m) _Pragma("unroll") for (int n = 0; n < 2; ++n) _Pragma("unroll") for (int k = 0; k < 2; ++k) \
;         acc[ai][bj][m][n] = __builtin_amdgcn_mfma_f32_16x16x32_bf16(Bt[n][k], At[m][k], acc[ai][bj][m][n], 0, 0, 0); __builtin_amdgcn_s_setprio(0); } while (0)
; #define PG8_WAIT_V(n) asm volatile("s_waitcnt vmcnt(" #n ")" ::: "memory")
; #define PG8_WAIT_L(n) asm volatile("s_waitcnt lgkmcnt(" #n ")" ::: "memory")
; #define PG8_BAR __builtin_amdgcn_s_barrier()
; #define PG8_SCHED __builtin_amdgcn_sched_barrier(0)
; template <class Epi, class Sched, bool ALIGN_EPI = false, bool SP2 = false>
; __device__ __forceinline__ void gemm_phase(PG8_LAS unsigned char* lds, const Gemm g, const Sched& S, const Epi& E, const int wv) {
;     ...
;             PG8_LDA(At, 0, 1); PG8_STAGE(PG8_SB(0, 0), b2, voffB); PG8_STAGE(PG8_SB(0, 1), b2 + hstepB, voffB); PG8_STAGE(PG8_SA(0, 0), a2, voffA);
;             PG8_WAIT_V(8); PG8_WAIT_L(0); PG8_BAR; PG8_MMA(1, 0, At, B0); PG8_MMA(1, 1, At, B1); PG8_BAR; PG8_SCHED;
;             PG8_LDB(B0, 1, 0); PG8_LDB(B1, 1, 1); PG8_SCHED; PG8_LDA(At, 1, 0); PG8_STAGE(PG8_SA(0, 1), a2 + hstepA, voffA);
	s_add_i32 s76, s53, 0x10000
	v_lshl_add_u64 v[216:217], s[74:75], 0, v[0:1]
	s_mov_b32 m0, s76
	ds_read_b128 v[166:169], v235 offset:16384
	ds_read_b128 v[170:173], v235 offset:17408
	ds_read_b128 v[174:177], v235 offset:18432
	ds_read_b128 v[178:181], v235 offset:19456
	ds_read_b128 v[182:185], v235 offset:20480
	ds_read_b128 v[204:207], v235 offset:21504
	ds_read_b128 v[208:211], v235 offset:22528
	ds_read_b128 v[212:215], v235 offset:23552
	global_load_lds_dwordx4 v[216:217], off
	s_add_i32 m0, s76, 0x2000
	v_lshl_add_u64 v[218:219], s[74:75], 0, v[198:199]
	s_add_u32 s74, s74, s34
	s_addc_u32 s75, s75, s35
	s_add_i32 s73, s53, 0x14000
	global_load_lds_dwordx4 v[218:219], off
	s_mov_b32 m0, s73
	global_load_lds_dwordx4 v0, s[74:75]
	s_add_i32 m0, s73, 0x2000
	global_load_lds_dwordx4 v198, s[74:75]
	s_mov_b32 m0, s59
	global_load_lds_dwordx4 v194, s[54:55]
	s_mov_b32 m0, s60
	s_nop 0
	global_load_lds_dwordx4 v196, s[54:55]
	s_waitcnt vmcnt(8) lgkmcnt(0)
	s_barrier
	v_mfma_f32_16x16x32_bf16 v[62:65], v[126:129], v[166:169], v[62:65]
	v_mfma_f32_16x16x32_bf16 v[58:61], v[142:145], v[166:169], v[58:61]
	v_mfma_f32_16x16x32_bf16 v[46:49], v[126:129], v[174:177], v[46:49]
	v_mfma_f32_16x16x32_bf16 v[42:45], v[142:145], v[174:177], v[42:45]
	v_mfma_f32_16x16x32_bf16 v[30:33], v[126:129], v[182:185], v[30:33]
	v_mfma_f32_16x16x32_bf16 v[26:29], v[142:145], v[182:185], v[26:29]
	v_mfma_f32_16x16x32_bf16 v[14:17], v[126:129], v[208:211], v[14:17]
	v_mfma_f32_16x16x32_bf16 v[10:13], v[142:145], v[208:211], v[10:13]
	v_mfma_f32_16x16x32_bf16 v[62:65], v[138:141], v[170:173], v[62:65]
	v_mfma_f32_16x16x32_bf16 v[58:61], v[146:149], v[170:173], v[58:61]
	v_mfma_f32_16x16x32_bf16 v[46:49], v[138:141], v[178:181], v[46:49]
	v_mfma_f32_16x16x32_bf16 v[42:45], v[146:149], v[178:181], v[42:45]
	v_mfma_f32_16x16x32_bf16 v[30:33], v[138:141], v[204:207], v[30:33]
	v_mfma_f32_16x16x32_bf16 v[26:29], v[146:149], v[204:207], v[26:29]
	v_mfma_f32_16x16x32_bf16 v[14:17], v[138:141], v[212:215], v[14:17]
	v_mfma_f32_16x16x32_bf16 v[10:13], v[146:149], v[212:215], v[10:13]
	v_mfma_f32_16x16x32_bf16 v[54:57], v[150:153], v[166:169], v[54:57]
	v_mfma_f32_16x16x32_bf16 v[50:53], v[158:161], v[166:169], v[50:53]
	v_mfma_f32_16x16x32_bf16 v[38:41], v[150:153], v[174:177], v[38:41]
	v_mfma_f32_16x16x32_bf16 v[34:37], v[158:161], v[174:177], v[34:37]
	v_mfma_f32_16x16x32_bf16 v[22:25], v[150:153], v[182:185], v[22:25]
	v_mfma_f32_16x16x32_bf16 v[18:21], v[158:161], v[182:185], v[18:21]
	v_mfma_f32_16x16x32_bf16 v[6:9], v[150:153], v[208:211], v[6:9]
	v_mfma_f32_16x16x32_bf16 v[2:5], v[158:161], v[208:211], v[2:5]
	v_mfma_f32_16x16x32_bf16 v[54:57], v[154:157], v[170:173], v[54:57]
	v_mfma_f32_16x16x32_bf16 v[50:53], v[162:165], v[170:173], v[50:53]
	v_mfma_f32_16x16x32_bf16 v[38:41], v[154:157], v[178:181], v[38:41]
	v_mfma_f32_16x16x32_bf16 v[34:37], v[162:165], v[178:181], v[34:37]
	v_mfma_f32_16x16x32_bf16 v[22:25], v[154:157], v[204:207], v[22:25]
	v_mfma_f32_16x16x32_bf16 v[18:21], v[162:165], v[204:207], v[18:21]
	v_mfma_f32_16x16x32_bf16 v[6:9], v[154:157], v[212:215], v[6:9]
	v_mfma_f32_16x16x32_bf16 v[2:5], v[162:165], v[212:215], v[2:5]
	s_barrier
	ds_read_b128 v[126:129], v192
	ds_read_b128 v[138:141], v192 offset:1024
	ds_read_b128 v[142:145], v192 offset:2048
	ds_read_b128 v[146:149], v192 offset:3072
	ds_read_b128 v[150:153], v193
	ds_read_b128 v[154:157], v193 offset:1024
	ds_read_b128 v[158:161], v193 offset:2048
	ds_read_b128 v[162:165], v193 offset:3072
	s_mov_b32 m0, s61
	ds_read_b128 v[166:169], v235 offset:32768
	ds_read_b128 v[170:173], v235 offset:33792
	ds_read_b128 v[174:177], v235 offset:34816
	ds_read_b128 v[178:181], v235 offset:35840
	ds_read_b128 v[182:185], v235 offset:36864
	ds_read_b128 v[204:207], v235 offset:37888
	ds_read_b128 v[208:211], v235 offset:38912
	ds_read_b128 v[212:215], v235 offset:39936
	global_load_lds_dwordx4 v115, s[54:55]
	s_mov_b32 m0, s62
	s_nop 0
	global_load_lds_dwordx4 v201, s[54:55]
	s_waitcnt vmcnt(8) lgkmcnt(0)
	s_barrier
; #define PG8_STAGE(bufoff, gbase, voff) do { _Pragma("unroll") for (int _i = 0; _i < 2; ++_i) \
;         __builtin_amdgcn_global_load_lds((const unsigned*)((const char*)(gbase) + (voff)[_i]), (PG8_LAS unsigned*)(lds + (bufoff) + ldsw + _i * 8192), 16, 0, 0); } while (0)
; #define PG8_LDA(dst, b, h) do { _Pragma("unroll") for (int m = 0; m < 4; ++m) _Pragma("unroll") for (int k = 0; k < 2; ++k) dst[m][k] = *(const PG8_LAS bf16x8*)(lds + PG8_SA(b, h) + aoff + m * 2048 + k * 1024); } while (0)
; #define PG8_LDB(dst, b, h) do { _Pragma("unroll") for (int n = 0; n < 2; ++n) _Pragma("unroll") for (int k = 0; k < 2; ++k) dst[n][k] = *(const PG8_LAS bf16x8*)(lds + PG8_SB(b, h) + boff + n * 2048 + k * 1024); } while (0)
; #define PG8_MMA(ai, bj, At, Bt) do { __builtin_amdgcn_s_setprio(1); _Pragma("unroll") for (int m = 0; m < 4; ++m) _Pragma("unroll") for (int n = 0; n < 2; ++n) _Pragma("unroll") for (int k = 0; k < 2; ++k) \
;         acc[ai][bj][m][n] = __builtin_amdgcn_mfma_f32_16x16x32_bf16(Bt[n][k], At[m][k], acc[ai][bj][m][n], 0, 0, 0); __builtin_amdgcn_s_setprio(0); } while (0)
; #define PG8_WAIT_V(n) asm volatile("s_waitcnt vmcnt(" #n ")" ::: "memory")
; #define PG8_WAIT_L(n) asm volatile("s_waitcnt lgkmcnt(" #n ")" ::: "memory")
; #define PG8_BAR __builtin_amdgcn_s_barrier()
; template <class Epi, class Sched, bool ALIGN_EPI = false, bool SP2 = false>
; __device__ __forceinline__ void gemm_phase(PG8_LAS unsigned char* lds, const Gemm g, const Sched& S, const Epi& E, const int wv) {
;     ...
;         for (int t = 0; t < nt; t += 2) {
;             const bool last = (t == nt - 2);
;             const char* a1 = cA + (size_t)(t + 1) * kstep;
;             const char* a2 = last ? nA : cA + (size_t)(t + 2) * kstep; const char* b2 = last ? nB : cB + (size_t)(t + 2) * kstep;
;             const char* a3 = a2 + kstep; const char* b3 = b2 + kstep;
;     ...
;             PG8_LDB(B0, 1, 0); PG8_LDB(B1, 1, 1); PG8_SCHED; PG8_LDA(At, 1, 0); PG8_STAGE(PG8_SA(0, 1), a2 + hstepA, voffA);
;             PG8_WAIT_V(8); PG8_WAIT_L(0); PG8_BAR; PG8_MMA(0, 0, At, B0); PG8_MMA(0, 1, At, B1); PG8_BAR; PG8_SCHED;
;             PG8_LDA(At, 1, 1); PG8_STAGE(PG8_SB(1, 0), b3, voffB); PG8_STAGE(PG8_SB(1, 1), b3 + hstepB, voffB); PG8_STAGE(PG8_SA(1, 0), a3, voffA);
;             PG8_WAIT_V(8); PG8_WAIT_L(0); PG8_BAR; PG8_MMA(1, 0, At, B0); PG8_MMA(1, 1, At, B1); PG8_BAR; PG8_SCHED;
	v_mfma_f32_16x16x32_bf16 v[134:137], v[126:129], v[166:169], v[134:137]
	v_mfma_f32_16x16x32_bf16 v[130:133], v[142:145], v[166:169], v[130:133]
	v_mfma_f32_16x16x32_bf16 v[110:113], v[126:129], v[174:177], v[110:113]
	v_mfma_f32_16x16x32_bf16 v[106:109], v[142:145], v[174:177], v[106:109]
	v_mfma_f32_16x16x32_bf16 v[94:97], v[126:129], v[182:185], v[94:97]
	v_mfma_f32_16x16x32_bf16 v[90:93], v[142:145], v[182:185], v[90:93]
	v_mfma_f32_16x16x32_bf16 v[78:81], v[126:129], v[208:211], v[78:81]
	v_mfma_f32_16x16x32_bf16 v[74:77], v[142:145], v[208:211], v[74:77]
	v_mfma_f32_16x16x32_bf16 v[134:137], v[138:141], v[170:173], v[134:137]
	v_mfma_f32_16x16x32_bf16 v[130:133], v[146:149], v[170:173], v[130:133]
	v_mfma_f32_16x16x32_bf16 v[110:113], v[138:141], v[178:181], v[110:113]
	v_mfma_f32_16x16x32_bf16 v[106:109], v[146:149], v[178:181], v[106:109]
	v_mfma_f32_16x16x32_bf16 v[94:97], v[138:141], v[204:207], v[94:97]
	v_mfma_f32_16x16x32_bf16 v[90:93], v[146:149], v[204:207], v[90:93]
	v_mfma_f32_16x16x32_bf16 v[78:81], v[138:141], v[212:215], v[78:81]
	v_mfma_f32_16x16x32_bf16 v[74:77], v[146:149], v[212:215], v[74:77]
	v_mfma_f32_16x16x32_bf16 v[120:123], v[150:153], v[166:169], v[122:125]
	v_mfma_f32_16x16x32_bf16 v[116:119], v[158:161], v[166:169], v[116:119]
	v_mfma_f32_16x16x32_bf16 v[102:105], v[150:153], v[174:177], v[102:105]
	v_mfma_f32_16x16x32_bf16 v[98:101], v[158:161], v[174:177], v[98:101]
	v_mfma_f32_16x16x32_bf16 v[86:89], v[150:153], v[182:185], v[86:89]
	v_mfma_f32_16x16x32_bf16 v[82:85], v[158:161], v[182:185], v[82:85]
	v_mfma_f32_16x16x32_bf16 v[70:73], v[150:153], v[208:211], v[70:73]
	v_mfma_f32_16x16x32_bf16 v[66:69], v[158:161], v[208:211], v[66:69]
	v_mfma_f32_16x16x32_bf16 v[122:125], v[154:157], v[170:173], v[120:123]
	v_mfma_f32_16x16x32_bf16 v[118:121], v[162:165], v[170:173], v[116:119]
	v_mfma_f32_16x16x32_bf16 v[102:105], v[154:157], v[178:181], v[102:105]
	v_mfma_f32_16x16x32_bf16 v[98:101], v[162:165], v[178:181], v[98:101]
	v_mfma_f32_16x16x32_bf16 v[86:89], v[154:157], v[204:207], v[86:89]
	v_mfma_f32_16x16x32_bf16 v[82:85], v[162:165], v[204:207], v[82:85]
	v_mfma_f32_16x16x32_bf16 v[70:73], v[154:157], v[212:215], v[70:73]
	v_mfma_f32_16x16x32_bf16 v[66:69], v[162:165], v[212:215], v[66:69]
	s_barrier
	s_add_i32 m0, s53, 0x17f80
	ds_read_b128 v[166:169], v235 offset:49152
	ds_read_b128 v[170:173], v235 offset:50176
	ds_read_b128 v[174:177], v235 offset:51200
	ds_read_b128 v[178:181], v235 offset:52224
	ds_read_b128 v[182:185], v235 offset:53248
	ds_read_b128 v[204:207], v235 offset:54272
	ds_read_b128 v[208:211], v235 offset:55296
	ds_read_b128 v[212:215], v235 offset:56320
	global_load_lds_dwordx4 v[216:217], off offset:128
	s_add_i32 m0, s53, 0x19f80
	global_load_lds_dwordx4 v[218:219], off offset:128
	s_add_i32 m0, s53, 0x1bf80
	s_nop 0
	global_load_lds_dwordx4 v0, s[74:75] offset:128
	s_add_i32 m0, s53, 0x1df80
	s_nop 0
	global_load_lds_dwordx4 v198, s[74:75] offset:128
	s_add_i32 m0, s64, 0xffffff80
	s_nop 0
	global_load_lds_dwordx4 v194, s[54:55] offset:128
	s_add_i32 m0, s65, 0xffffff80
	s_nop 0
	global_load_lds_dwordx4 v196, s[54:55] offset:128
	s_waitcnt vmcnt(8) lgkmcnt(0)
	s_barrier
	v_mfma_f32_16x16x32_bf16 v[62:65], v[126:129], v[166:169], v[62:65]
	v_mfma_f32_16x16x32_bf16 v[58:61], v[142:145], v[166:169], v[58:61]
	v_mfma_f32_16x16x32_bf16 v[46:49], v[126:129], v[174:177], v[46:49]
	v_mfma_f32_16x16x32_bf16 v[42:45], v[142:145], v[174:177], v[42:45]
	v_mfma_f32_16x16x32_bf16 v[30:33], v[126:129], v[182:185], v[30:33]
	v_mfma_f32_16x16x32_bf16 v[26:29], v[142:145], v[182:185], v[26:29]
	v_mfma_f32_16x16x32_bf16 v[14:17], v[126:129], v[208:211], v[14:17]
	v_mfma_f32_16x16x32_bf16 v[10:13], v[142:145], v[208:211], v[10:13]
	v_mfma_f32_16x16x32_bf16 v[62:65], v[138:141], v[170:173], v[62:65]
	v_mfma_f32_16x16x32_bf16 v[58:61], v[146:149], v[170:173], v[58:61]
	v_mfma_f32_16x16x32_bf16 v[46:49], v[138:141], v[178:181], v[46:49]
	v_mfma_f32_16x16x32_bf16 v[42:45], v[146:149], v[178:181], v[42:45]
	v_mfma_f32_16x16x32_bf16 v[30:33], v[138:141], v[204:207], v[30:33]
	v_mfma_f32_16x16x32_bf16 v[26:29], v[146:149], v[204:207], v[26:29]
	v_mfma_f32_16x16x32_bf16 v[14:17], v[138:141], v[212:215], v[14:17]
	v_mfma_f32_16x16x32_bf16 v[10:13], v[146:149], v[212:215], v[10:13]
	v_mfma_f32_16x16x32_bf16 v[54:57], v[150:153], v[166:169], v[54:57]
	v_mfma_f32_16x16x32_bf16 v[50:53], v[158:161], v[166:169], v[50:53]
	v_mfma_f32_16x16x32_bf16 v[38:41], v[150:153], v[174:177], v[38:41]
	v_mfma_f32_16x16x32_bf16 v[34:37], v[158:161], v[174:177], v[34:37]
	v_mfma_f32_16x16x32_bf16 v[22:25], v[150:153], v[182:185], v[22:25]
	v_mfma_f32_16x16x32_bf16 v[18:21], v[158:161], v[182:185], v[18:21]
	v_mfma_f32_16x16x32_bf16 v[6:9], v[150:153], v[208:211], v[6:9]
	v_mfma_f32_16x16x32_bf16 v[2:5], v[158:161], v[208:211], v[2:5]
	v_mfma_f32_16x16x32_bf16 v[54:57], v[154:157], v[170:173], v[54:57]
	v_mfma_f32_16x16x32_bf16 v[50:53], v[162:165], v[170:173], v[50:53]
	v_mfma_f32_16x16x32_bf16 v[38:41], v[154:157], v[178:181], v[38:41]
	v_mfma_f32_16x16x32_bf16 v[34:37], v[162:165], v[178:181], v[34:37]
	v_mfma_f32_16x16x32_bf16 v[22:25], v[154:157], v[204:207], v[22:25]
	v_mfma_f32_16x16x32_bf16 v[18:21], v[162:165], v[204:207], v[18:21]
	v_mfma_f32_16x16x32_bf16 v[6:9], v[154:157], v[212:215], v[6:9]
	v_mfma_f32_16x16x32_bf16 v[2:5], v[162:165], v[212:215], v[2:5]
	s_barrier
	s_add_u32 s44, s44, 0x100
	s_addc_u32 s45, s45, 0
	s_add_u32 s56, s56, 0x100
	s_addc_u32 s57, s57, 0
	s_cmp_ge_i32 s72, s63
	s_mov_b32 s54, s72
	s_cbranch_scc0 .LBB0_699
	s_movk_i32 s75, 0x2000
	s_mov_b32 s72, 0x10000
	s_mov_b32 s73, 0x12000
	s_mov_b32 s74, 0x14000
	s_mov_b32 s71, 0x3f317217
	s_and_b64 vcc, exec, s[48:49]
	s_cbranch_vccz .LBB0_673

;     __host__ __device__ bool next(int i, Unit& u) const { const int P = (i >> 1) * G + c; if (P >= 256) return false; u.pm = P >> 3; u.pn = (P & 7) + 8 * (i & 1); return true; }
; #define PG8_STAGE(bufoff, gbase, voff) do { _Pragma("unroll") for (int _i = 0; _i < 2; ++_i) \
;         __builtin_amdgcn_global_load_lds((const unsigned*)((const char*)(gbase) + (voff)[_i]), (PG8_LAS unsigned*)(lds + (bufoff) + ldsw + _i * 8192), 16, 0, 0); } while (0)
; #define PG8_LDA(dst, b, h) do { _Pragma("unroll") for (int m = 0; m < 4; ++m) _Pragma("unroll") for (int k = 0; k < 2; ++k) dst[m][k] = *(const PG8_LAS bf16x8*)(lds + PG8_SA(b, h) + aoff + m * 2048 + k * 1024); } while (0)
; #define PG8_LDB(dst, b, h) do { _Pragma("unroll") for (int n = 0; n < 2; ++n) _Pragma("unroll") for (int k = 0; k < 2; ++k) dst[n][k] = *(const PG8_LAS bf16x8*)(lds + PG8_SB(b, h) + boff + n * 2048 + k * 1024); } while (0)
; #define PG8_WAIT_V(n) asm volatile("s_waitcnt vmcnt(" #n ")" ::: "memory")
; #define PG8_WAIT_L(n) asm volatile("s_waitcnt lgkmcnt(" #n ")" ::: "memory")
; #define PG8_BAR __builtin_amdgcn_s_barrier()
; #define PG8_SCHED __builtin_amdgcn_sched_barrier(0)
; template <class Epi, class Sched, bool ALIGN_EPI = false, bool SP2 = false>
; __device__ __forceinline__ void gemm_phase(PG8_LAS unsigned char* lds, const Gemm g, const Sched& S, const Epi& E, const int wv) {
;     ...
;     for (;;) {
;         const bool has_next = S.next(ui + 1, nxt);
;         const char* nA = has_next ? (const char*)g.A + (size_t)nxt.pm * tstepA + (g.amod ? (size_t)(nxt.pn % g.amod) * K * 2 : (size_t)0) : cA; const char* nB = has_next ? (const char*)g.Bt + (size_t)nxt.pn * tstepB : cB;
;         for (int t = 0; t < nt; t += 2) {
;             const bool last = (t == nt - 2);
;             const char* a1 = cA + (size_t)(t + 1) * kstep;
;             const char* a2 = last ? nA : cA + (size_t)(t + 2) * kstep; const char* b2 = last ? nB : cB + (size_t)(t + 2) * kstep;
;             const char* a3 = a2 + kstep; const char* b3 = b2 + kstep;
;             if (last && has_next) S.a_ready(nxt);
;             if constexpr (SP2) {
;             PG8_LDB(B0, 0, 0); PG8_LDB(B1, 0, 1); PG8_SCHED; PG8_LDA(At, 0, 0); PG8_STAGE(PG8_SA(1, 1), a1 + hstepA, voffA);
;             PG8_WAIT_V(8); PG8_WAIT_L(0); PG8_BAR; PG8_MMA(0, 0, At, B0); PG8_MMA(0, 1, At, B1); PG8_BAR; PG8_SCHED;
.LBB0_808:
	s_and_b64 s[14:15], s[46:47], exec
	s_cselect_b32 s11, s91, s49
	s_cselect_b32 s13, s90, s48
	s_add_u32 s35, s52, 0x100
	v_mov_b32_e32 v18, 0
	s_addc_u32 s51, s53, 0
	s_mov_b32 s46, 0
	v_mov_b32_e32 v19, v18
	v_pk_mov_b32 v[20:21], v[18:19], v[18:19]
	v_pk_mov_b32 v[90:91], v[18:19], v[18:19]
	v_pk_mov_b32 v[92:93], v[18:19], v[18:19]
	v_pk_mov_b32 v[22:23], v[18:19], v[18:19]
	v_pk_mov_b32 v[24:25], v[18:19], v[18:19]
	v_pk_mov_b32 v[94:95], v[18:19], v[18:19]
	v_pk_mov_b32 v[96:97], v[18:19], v[18:19]
	v_pk_mov_b32 v[2:3], v[18:19], v[18:19]
	v_pk_mov_b32 v[4:5], v[18:19], v[18:19]
	v_pk_mov_b32 v[66:67], v[18:19], v[18:19]
	v_pk_mov_b32 v[68:69], v[18:19], v[18:19]
	v_pk_mov_b32 v[10:11], v[18:19], v[18:19]
	v_pk_mov_b32 v[12:13], v[18:19], v[18:19]
	v_pk_mov_b32 v[82:83], v[18:19], v[18:19]
	v_pk_mov_b32 v[84:85], v[18:19], v[18:19]
	v_pk_mov_b32 v[26:27], v[18:19], v[18:19]
	v_pk_mov_b32 v[28:29], v[18:19], v[18:19]
	v_pk_mov_b32 v[98:99], v[18:19], v[18:19]
	v_pk_mov_b32 v[100:101], v[18:19], v[18:19]
	v_pk_mov_b32 v[30:31], v[18:19], v[18:19]
	v_pk_mov_b32 v[32:33], v[18:19], v[18:19]
	v_pk_mov_b32 v[102:103], v[18:19], v[18:19]
	v_pk_mov_b32 v[104:105], v[18:19], v[18:19]
	v_pk_mov_b32 v[6:7], v[18:19], v[18:19]
	v_pk_mov_b32 v[8:9], v[18:19], v[18:19]
	v_pk_mov_b32 v[70:71], v[18:19], v[18:19]
	v_pk_mov_b32 v[72:73], v[18:19], v[18:19]
	v_pk_mov_b32 v[14:15], v[18:19], v[18:19]
	v_pk_mov_b32 v[16:17], v[18:19], v[18:19]
	v_pk_mov_b32 v[86:87], v[18:19], v[18:19]
	v_pk_mov_b32 v[88:89], v[18:19], v[18:19]
	v_pk_mov_b32 v[50:51], v[18:19], v[18:19]
	v_pk_mov_b32 v[52:53], v[18:19], v[18:19]
	v_pk_mov_b32 v[122:123], v[18:19], v[18:19]
	v_pk_mov_b32 v[124:125], v[18:19], v[18:19]
	v_pk_mov_b32 v[54:55], v[18:19], v[18:19]
	v_pk_mov_b32 v[56:57], v[18:19], v[18:19]
	v_pk_mov_b32 v[126:127], v[18:19], v[18:19]
	v_pk_mov_b32 v[128:129], v[18:19], v[18:19]
	v_pk_mov_b32 v[34:35], v[18:19], v[18:19]
	v_pk_mov_b32 v[36:37], v[18:19], v[18:19]
	v_pk_mov_b32 v[106:107], v[18:19], v[18:19]
	v_pk_mov_b32 v[108:109], v[18:19], v[18:19]
	v_pk_mov_b32 v[42:43], v[18:19], v[18:19]
	v_pk_mov_b32 v[44:45], v[18:19], v[18:19]
	v_pk_mov_b32 v[114:115], v[18:19], v[18:19]
	v_pk_mov_b32 v[116:117], v[18:19], v[18:19]
	v_pk_mov_b32 v[58:59], v[18:19], v[18:19]
	v_pk_mov_b32 v[60:61], v[18:19], v[18:19]
	v_pk_mov_b32 v[130:131], v[18:19], v[18:19]
	v_pk_mov_b32 v[132:133], v[18:19], v[18:19]
	v_pk_mov_b32 v[62:63], v[18:19], v[18:19]
	v_pk_mov_b32 v[64:65], v[18:19], v[18:19]
	v_pk_mov_b32 v[134:135], v[18:19], v[18:19]
	v_pk_mov_b32 v[136:137], v[18:19], v[18:19]
	v_pk_mov_b32 v[38:39], v[18:19], v[18:19]
	v_pk_mov_b32 v[40:41], v[18:19], v[18:19]
	v_pk_mov_b32 v[110:111], v[18:19], v[18:19]
	v_pk_mov_b32 v[112:113], v[18:19], v[18:19]
	v_pk_mov_b32 v[46:47], v[18:19], v[18:19]
	v_pk_mov_b32 v[48:49], v[18:19], v[18:19]
	v_pk_mov_b32 v[118:119], v[18:19], v[18:19]
	v_pk_mov_b32 v[120:121], v[18:19], v[18:19]
	v_add_u32_e32 v192, 0x10000, v208
	v_add_u32_e32 v193, 0x14000, v208
	v_add_u32_e32 v213, 0x18000, v208
	v_add_u32_e32 v227, 0x1c000, v208
	v_add_u32_e32 v218, 0x80000, v170
	v_add_u32_e32 v219, 0x80000, v172
.LBB0_809:
	s_add_i32 s52, s46, 2
	s_add_u32 s14, s48, 0x100
	s_addc_u32 s15, s49, 0
	s_cmp_eq_u32 s71, s46
	s_cselect_b32 s47, s11, s15
	s_cselect_b32 s46, s13, s14
	s_cselect_b32 s77, s87, s51
	s_cselect_b32 s76, s86, s35
	ds_read_b128 v[138:141], v192
	ds_read_b128 v[142:145], v192 offset:1024
	ds_read_b128 v[146:149], v192 offset:2048
	ds_read_b128 v[150:153], v192 offset:3072
	ds_read_b128 v[154:157], v193
	ds_read_b128 v[158:161], v193 offset:1024
	ds_read_b128 v[162:165], v193 offset:2048
	ds_read_b128 v[166:169], v193 offset:3072
	s_add_i32 m0, s63, 0xc000
	ds_read_b128 v[194:197], v211
	ds_read_b128 v[198:201], v211 offset:1024
	ds_read_b128 v[202:205], v211 offset:2048
	ds_read_b128 v[214:217], v211 offset:3072
	ds_read_b128 v[228:231], v211 offset:4096
	ds_read_b128 v[232:235], v211 offset:5120
	ds_read_b128 v[236:239], v211 offset:6144
	ds_read_b128 v[240:243], v211 offset:7168
	global_load_lds_dwordx4 v182, s[48:49]
	v_lshl_add_u64 v[190:191], s[48:49], 0, v[184:185]
	s_add_i32 m0, s63, 0xe000
	s_nop 0
	global_load_lds_dwordx4 v[190:191], off
	s_waitcnt vmcnt(8) lgkmcnt(0)
	s_barrier
	v_mfma_f32_16x16x32_bf16 v[118:121], v[138:141], v[194:197], v[118:121]
	v_mfma_f32_16x16x32_bf16 v[46:49], v[146:149], v[194:197], v[46:49]
	v_mfma_f32_16x16x32_bf16 v[110:113], v[138:141], v[202:205], v[110:113]
	v_mfma_f32_16x16x32_bf16 v[38:41], v[146:149], v[202:205], v[38:41]
	v_mfma_f32_16x16x32_bf16 v[134:137], v[138:141], v[228:231], v[134:137]
	v_mfma_f32_16x16x32_bf16 v[62:65], v[146:149], v[228:231], v[62:65]
	v_mfma_f32_16x16x32_bf16 v[130:133], v[138:141], v[236:239], v[130:133]
	v_mfma_f32_16x16x32_bf16 v[58:61], v[146:149], v[236:239], v[58:61]
	v_mfma_f32_16x16x32_bf16 v[118:121], v[142:145], v[198:201], v[118:121]
	v_mfma_f32_16x16x32_bf16 v[46:49], v[150:153], v[198:201], v[46:49]
	v_mfma_f32_16x16x32_bf16 v[110:113], v[142:145], v[214:217], v[110:113]
	v_mfma_f32_16x16x32_bf16 v[38:41], v[150:153], v[214:217], v[38:41]
	v_mfma_f32_16x16x32_bf16 v[134:137], v[142:145], v[232:235], v[134:137]
	v_mfma_f32_16x16x32_bf16 v[62:65], v[150:153], v[232:235], v[62:65]
	v_mfma_f32_16x16x32_bf16 v[130:133], v[142:145], v[240:243], v[130:133]
	v_mfma_f32_16x16x32_bf16 v[58:61], v[150:153], v[240:243], v[58:61]
	v_mfma_f32_16x16x32_bf16 v[114:117], v[154:157], v[194:197], v[114:117]
	v_mfma_f32_16x16x32_bf16 v[42:45], v[162:165], v[194:197], v[42:45]
	v_mfma_f32_16x16x32_bf16 v[106:109], v[154:157], v[202:205], v[106:109]
	v_mfma_f32_16x16x32_bf16 v[34:37], v[162:165], v[202:205], v[34:37]
	v_mfma_f32_16x16x32_bf16 v[126:129], v[154:157], v[228:231], v[126:129]
	v_mfma_f32_16x16x32_bf16 v[54:57], v[162:165], v[228:231], v[54:57]
	v_mfma_f32_16x16x32_bf16 v[122:125], v[154:157], v[236:239], v[122:125]
	v_mfma_f32_16x16x32_bf16 v[50:53], v[162:165], v[236:239], v[50:53]
	v_mfma_f32_16x16x32_bf16 v[114:117], v[158:161], v[198:201], v[114:117]
	v_mfma_f32_16x16x32_bf16 v[42:45], v[166:169], v[198:201], v[42:45]
	v_mfma_f32_16x16x32_bf16 v[106:109], v[158:161], v[214:217], v[106:109]
	v_mfma_f32_16x16x32_bf16 v[34:37], v[166:169], v[214:217], v[34:37]
	v_mfma_f32_16x16x32_bf16 v[126:129], v[158:161], v[232:235], v[126:129]
	v_mfma_f32_16x16x32_bf16 v[54:57], v[166:169], v[232:235], v[54:57]
	v_mfma_f32_16x16x32_bf16 v[122:125], v[158:161], v[240:243], v[122:125]
	v_mfma_f32_16x16x32_bf16 v[50:53], v[166:169], v[240:243], v[50:53]
	s_barrier
; #define PG8_STAGE(bufoff, gbase, voff) do { _Pragma("unroll") for (int _i = 0; _i < 2; ++_i) \
;         __builtin_amdgcn_global_load_lds((const unsigned*)((const char*)(gbase) + (voff)[_i]), (PG8_LAS unsigned*)(lds + (bufoff) + ldsw + _i * 8192), 16, 0, 0); } while (0)
; #define PG8_LDA(dst, b, h) do { _Pragma("unroll") for (int m = 0; m < 4; ++m) _Pragma("unroll") for (int k = 0; k < 2; ++k) dst[m][k] = *(const PG8_LAS bf16x8*)(lds + PG8_SA(b, h) + aoff + m * 2048 + k * 1024); } while (0)
; #define PG8_LDB(dst, b, h) do { _Pragma("unroll") for (int n = 0; n < 2; ++n) _Pragma("unroll") for (int k = 0; k < 2; ++k) dst[n][k] = *(const PG8_LAS bf16x8*)(lds + PG8_SB(b, h) + boff + n * 2048 + k * 1024); } while (0)
; #define PG8_MMA(ai, bj, At, Bt) do { __builtin_amdgcn_s_setprio(1); _Pragma("unroll") for (int m = 0; m < 4; ++m) _Pragma("unroll") for (int n = 0; n < 2; ++n) _Pragma("unroll") for (int k = 0; k < 2; ++k) \
;         acc[ai][bj][m][n] = __builtin_amdgcn_mfma_f32_16x16x32_bf16(Bt[n][k], At[m][k], acc[ai][bj][m][n], 0, 0, 0); __builtin_amdgcn_s_setprio(0); } while (0)
; #define PG8_WAIT_V(n) asm volatile("s_waitcnt vmcnt(" #n ")" ::: "memory")
; #define PG8_WAIT_L(n) asm volatile("s_waitcnt lgkmcnt(" #n ")" ::: "memory")
; #define PG8_BAR __builtin_amdgcn_s_barrier()
; #define PG8_SCHED __builtin_amdgcn_sched_barrier(0)
; template <class Epi, class Sched, bool ALIGN_EPI = false, bool SP2 = false>
; __device__ __forceinline__ void gemm_phase(PG8_LAS unsigned char* lds, const Gemm g, const Sched& S, const Epi& E, const int wv) {
;     ...
;             PG8_LDA(At, 0, 1); PG8_STAGE(PG8_SB(0, 0), b2, voffB); PG8_STAGE(PG8_SB(0, 1), b2 + hstepB, voffB); PG8_STAGE(PG8_SA(0, 0), a2, voffA);
;             PG8_WAIT_V(8); PG8_WAIT_L(0); PG8_BAR; PG8_MMA(1, 0, At, B0); PG8_MMA(1, 1, At, B1); PG8_BAR; PG8_SCHED;
;             PG8_LDB(B0, 1, 0); PG8_LDB(B1, 1, 1); PG8_SCHED; PG8_LDA(At, 1, 0); PG8_STAGE(PG8_SA(0, 1), a2 + hstepA, voffA);
	s_add_i32 s48, s62, 0x10000
	s_mov_b32 m0, s48
	ds_read_b128 v[194:197], v211 offset:16384
	ds_read_b128 v[198:201], v211 offset:17408
	ds_read_b128 v[202:205], v211 offset:18432
	ds_read_b128 v[214:217], v211 offset:19456
	ds_read_b128 v[228:231], v211 offset:20480
	ds_read_b128 v[232:235], v211 offset:21504
	ds_read_b128 v[236:239], v211 offset:22528
	ds_read_b128 v[240:243], v211 offset:23552
	global_load_lds_dwordx4 v0, s[76:77]
	s_add_i32 m0, s48, 0x2000
	s_add_u32 s48, s76, s16
	s_addc_u32 s49, s77, s17
	s_add_i32 s53, s62, 0x14000
	global_load_lds_dwordx4 v174, s[76:77]
	s_mov_b32 m0, s53
	global_load_lds_dwordx4 v0, s[48:49]
	s_add_i32 m0, s53, 0x2000
	global_load_lds_dwordx4 v174, s[48:49]
	s_mov_b32 m0, s63
	global_load_lds_dwordx4 v170, s[46:47]
	s_mov_b32 m0, s64
	s_nop 0
	global_load_lds_dwordx4 v172, s[46:47]
	s_waitcnt vmcnt(8) lgkmcnt(0)
	s_barrier
	v_mfma_f32_16x16x32_bf16 v[86:89], v[138:141], v[194:197], v[86:89]
	v_mfma_f32_16x16x32_bf16 v[14:17], v[146:149], v[194:197], v[14:17]
	v_mfma_f32_16x16x32_bf16 v[70:73], v[138:141], v[202:205], v[70:73]
	v_mfma_f32_16x16x32_bf16 v[6:9], v[146:149], v[202:205], v[6:9]
	v_mfma_f32_16x16x32_bf16 v[102:105], v[138:141], v[228:231], v[102:105]
	v_mfma_f32_16x16x32_bf16 v[30:33], v[146:149], v[228:231], v[30:33]
	v_mfma_f32_16x16x32_bf16 v[98:101], v[138:141], v[236:239], v[98:101]
	v_mfma_f32_16x16x32_bf16 v[26:29], v[146:149], v[236:239], v[26:29]
	v_mfma_f32_16x16x32_bf16 v[86:89], v[142:145], v[198:201], v[86:89]
	v_mfma_f32_16x16x32_bf16 v[14:17], v[150:153], v[198:201], v[14:17]
	v_mfma_f32_16x16x32_bf16 v[70:73], v[142:145], v[214:217], v[70:73]
	v_mfma_f32_16x16x32_bf16 v[6:9], v[150:153], v[214:217], v[6:9]
	v_mfma_f32_16x16x32_bf16 v[102:105], v[142:145], v[232:235], v[102:105]
	v_mfma_f32_16x16x32_bf16 v[30:33], v[150:153], v[232:235], v[30:33]
	v_mfma_f32_16x16x32_bf16 v[98:101], v[142:145], v[240:243], v[98:101]
	v_mfma_f32_16x16x32_bf16 v[26:29], v[150:153], v[240:243], v[26:29]
	v_mfma_f32_16x16x32_bf16 v[82:85], v[154:157], v[194:197], v[82:85]
	v_mfma_f32_16x16x32_bf16 v[10:13], v[162:165], v[194:197], v[10:13]
	v_mfma_f32_16x16x32_bf16 v[66:69], v[154:157], v[202:205], v[66:69]
	v_mfma_f32_16x16x32_bf16 v[2:5], v[162:165], v[202:205], v[2:5]
	v_mfma_f32_16x16x32_bf16 v[94:97], v[154:157], v[228:231], v[94:97]
	v_mfma_f32_16x16x32_bf16 v[22:25], v[162:165], v[228:231], v[22:25]
	v_mfma_f32_16x16x32_bf16 v[90:93], v[154:157], v[236:239], v[90:93]
	v_mfma_f32_16x16x32_bf16 v[18:21], v[162:165], v[236:239], v[18:21]
	v_mfma_f32_16x16x32_bf16 v[82:85], v[158:161], v[198:201], v[82:85]
	v_mfma_f32_16x16x32_bf16 v[10:13], v[166:169], v[198:201], v[10:13]
	v_mfma_f32_16x16x32_bf16 v[66:69], v[158:161], v[214:217], v[66:69]
	v_mfma_f32_16x16x32_bf16 v[2:5], v[166:169], v[214:217], v[2:5]
	v_mfma_f32_16x16x32_bf16 v[94:97], v[158:161], v[232:235], v[94:97]
	v_mfma_f32_16x16x32_bf16 v[22:25], v[166:169], v[232:235], v[22:25]
	v_mfma_f32_16x16x32_bf16 v[90:93], v[158:161], v[240:243], v[90:93]
	v_mfma_f32_16x16x32_bf16 v[18:21], v[166:169], v[240:243], v[18:21]
	s_barrier
	ds_read_b128 v[138:141], v213
	ds_read_b128 v[142:145], v213 offset:1024
	ds_read_b128 v[146:149], v213 offset:2048
	ds_read_b128 v[150:153], v213 offset:3072
	ds_read_b128 v[154:157], v227
	ds_read_b128 v[158:161], v227 offset:1024
	ds_read_b128 v[162:165], v227 offset:2048
	ds_read_b128 v[166:169], v227 offset:3072
	s_mov_b32 m0, s65
	ds_read_b128 v[194:197], v211 offset:32768
	ds_read_b128 v[198:201], v211 offset:33792
	ds_read_b128 v[202:205], v211 offset:34816
	ds_read_b128 v[214:217], v211 offset:35840
	ds_read_b128 v[228:231], v211 offset:36864
	ds_read_b128 v[232:235], v211 offset:37888
	ds_read_b128 v[236:239], v211 offset:38912
	ds_read_b128 v[240:243], v211 offset:39936
	global_load_lds_dwordx4 v218, s[46:47]
	s_mov_b32 m0, s66
	s_nop 0
	global_load_lds_dwordx4 v219, s[46:47]
	s_waitcnt vmcnt(8) lgkmcnt(0)
	s_barrier
; #define PG8_STAGE(bufoff, gbase, voff) do { _Pragma("unroll") for (int _i = 0; _i < 2; ++_i) \
;         __builtin_amdgcn_global_load_lds((const unsigned*)((const char*)(gbase) + (voff)[_i]), (PG8_LAS unsigned*)(lds + (bufoff) + ldsw + _i * 8192), 16, 0, 0); } while (0)
; #define PG8_LDA(dst, b, h) do { _Pragma("unroll") for (int m = 0; m < 4; ++m) _Pragma("unroll") for (int k = 0; k < 2; ++k) dst[m][k] = *(const PG8_LAS bf16x8*)(lds + PG8_SA(b, h) + aoff + m * 2048 + k * 1024); } while (0)
; #define PG8_LDB(dst, b, h) do { _Pragma("unroll") for (int n = 0; n < 2; ++n) _Pragma("unroll") for (int k = 0; k < 2; ++k) dst[n][k] = *(const PG8_LAS bf16x8*)(lds + PG8_SB(b, h) + boff + n * 2048 + k * 1024); } while (0)
; #define PG8_MMA(ai, bj, At, Bt) do { __builtin_amdgcn_s_setprio(1); _Pragma("unroll") for (int m = 0; m < 4; ++m) _Pragma("unroll") for (int n = 0; n < 2; ++n) _Pragma("unroll") for (int k = 0; k < 2; ++k) \
;         acc[ai][bj][m][n] = __builtin_amdgcn_mfma_f32_16x16x32_bf16(Bt[n][k], At[m][k], acc[ai][bj][m][n], 0, 0, 0); __builtin_amdgcn_s_setprio(0); } while (0)
; #define PG8_WAIT_V(n) asm volatile("s_waitcnt vmcnt(" #n ")" ::: "memory")
; #define PG8_WAIT_L(n) asm volatile("s_waitcnt lgkmcnt(" #n ")" ::: "memory")
; #define PG8_BAR __builtin_amdgcn_s_barrier()
; template <class Epi, class Sched, bool ALIGN_EPI = false, bool SP2 = false>
; __device__ __forceinline__ void gemm_phase(PG8_LAS unsigned char* lds, const Gemm g, const Sched& S, const Epi& E, const int wv) {
;     ...
;         for (int t = 0; t < nt; t += 2) {
;             const bool last = (t == nt - 2);
;             const char* a1 = cA + (size_t)(t + 1) * kstep;
;             const char* a2 = last ? nA : cA + (size_t)(t + 2) * kstep; const char* b2 = last ? nB : cB + (size_t)(t + 2) * kstep;
;             const char* a3 = a2 + kstep; const char* b3 = b2 + kstep;
;     ...
;             PG8_LDB(B0, 1, 0); PG8_LDB(B1, 1, 1); PG8_SCHED; PG8_LDA(At, 1, 0); PG8_STAGE(PG8_SA(0, 1), a2 + hstepA, voffA);
;             PG8_WAIT_V(8); PG8_WAIT_L(0); PG8_BAR; PG8_MMA(0, 0, At, B0); PG8_MMA(0, 1, At, B1); PG8_BAR; PG8_SCHED;
;             PG8_LDA(At, 1, 1); PG8_STAGE(PG8_SB(1, 0), b3, voffB); PG8_STAGE(PG8_SB(1, 1), b3 + hstepB, voffB); PG8_STAGE(PG8_SA(1, 0), a3, voffA);
;             PG8_WAIT_V(8); PG8_WAIT_L(0); PG8_BAR; PG8_MMA(1, 0, At, B0); PG8_MMA(1, 1, At, B1); PG8_BAR; PG8_SCHED;
	v_mfma_f32_16x16x32_bf16 v[118:121], v[138:141], v[194:197], v[118:121]
	v_mfma_f32_16x16x32_bf16 v[46:49], v[146:149], v[194:197], v[46:49]
	v_mfma_f32_16x16x32_bf16 v[110:113], v[138:141], v[202:205], v[110:113]
	v_mfma_f32_16x16x32_bf16 v[38:41], v[146:149], v[202:205], v[38:41]
	v_mfma_f32_16x16x32_bf16 v[134:137], v[138:141], v[228:231], v[134:137]
	v_mfma_f32_16x16x32_bf16 v[62:65], v[146:149], v[228:231], v[62:65]
	v_mfma_f32_16x16x32_bf16 v[130:133], v[138:141], v[236:239], v[130:133]
	v_mfma_f32_16x16x32_bf16 v[58:61], v[146:149], v[236:239], v[58:61]
	v_mfma_f32_16x16x32_bf16 v[118:121], v[142:145], v[198:201], v[118:121]
	v_mfma_f32_16x16x32_bf16 v[46:49], v[150:153], v[198:201], v[46:49]
	v_mfma_f32_16x16x32_bf16 v[110:113], v[142:145], v[214:217], v[110:113]
	v_mfma_f32_16x16x32_bf16 v[38:41], v[150:153], v[214:217], v[38:41]
	v_mfma_f32_16x16x32_bf16 v[134:137], v[142:145], v[232:235], v[134:137]
	v_mfma_f32_16x16x32_bf16 v[62:65], v[150:153], v[232:235], v[62:65]
	v_mfma_f32_16x16x32_bf16 v[130:133], v[142:145], v[240:243], v[130:133]
	v_mfma_f32_16x16x32_bf16 v[58:61], v[150:153], v[240:243], v[58:61]
	v_mfma_f32_16x16x32_bf16 v[114:117], v[154:157], v[194:197], v[114:117]
	v_mfma_f32_16x16x32_bf16 v[42:45], v[162:165], v[194:197], v[42:45]
	v_mfma_f32_16x16x32_bf16 v[106:109], v[154:157], v[202:205], v[106:109]
	v_mfma_f32_16x16x32_bf16 v[34:37], v[162:165], v[202:205], v[34:37]
	v_mfma_f32_16x16x32_bf16 v[126:129], v[154:157], v[228:231], v[126:129]
	v_mfma_f32_16x16x32_bf16 v[54:57], v[162:165], v[228:231], v[54:57]
	v_mfma_f32_16x16x32_bf16 v[122:125], v[154:157], v[236:239], v[122:125]
	v_mfma_f32_16x16x32_bf16 v[50:53], v[162:165], v[236:239], v[50:53]
	v_mfma_f32_16x16x32_bf16 v[114:117], v[158:161], v[198:201], v[114:117]
	v_mfma_f32_16x16x32_bf16 v[42:45], v[166:169], v[198:201], v[42:45]
	v_mfma_f32_16x16x32_bf16 v[106:109], v[158:161], v[214:217], v[106:109]
	v_mfma_f32_16x16x32_bf16 v[34:37], v[166:169], v[214:217], v[34:37]
	v_mfma_f32_16x16x32_bf16 v[126:129], v[158:161], v[232:235], v[126:129]
	v_mfma_f32_16x16x32_bf16 v[54:57], v[166:169], v[232:235], v[54:57]
	v_mfma_f32_16x16x32_bf16 v[122:125], v[158:161], v[240:243], v[122:125]
	v_mfma_f32_16x16x32_bf16 v[50:53], v[166:169], v[240:243], v[50:53]
	s_barrier
	s_add_i32 m0, s62, 0x17f80
	ds_read_b128 v[194:197], v211 offset:49152
	ds_read_b128 v[198:201], v211 offset:50176
	ds_read_b128 v[202:205], v211 offset:51200
	ds_read_b128 v[214:217], v211 offset:52224
	ds_read_b128 v[228:231], v211 offset:53248
	ds_read_b128 v[232:235], v211 offset:54272
	ds_read_b128 v[236:239], v211 offset:55296
	ds_read_b128 v[240:243], v211 offset:56320
	global_load_lds_dwordx4 v0, s[76:77] offset:128
	s_add_i32 m0, s62, 0x19f80
	global_load_lds_dwordx4 v174, s[76:77] offset:128
	s_add_i32 m0, s62, 0x1bf80
	s_nop 0
	global_load_lds_dwordx4 v0, s[48:49] offset:128
	s_add_i32 m0, s62, 0x1df80
	s_nop 0
	global_load_lds_dwordx4 v174, s[48:49] offset:128
	s_add_i32 m0, s69, 0xffffff80
	s_nop 0
	global_load_lds_dwordx4 v170, s[46:47] offset:128
	s_add_i32 m0, s70, 0xffffff80
	s_nop 0
	global_load_lds_dwordx4 v172, s[46:47] offset:128
	s_waitcnt vmcnt(8) lgkmcnt(0)
	s_barrier
	v_mfma_f32_16x16x32_bf16 v[86:89], v[138:141], v[194:197], v[86:89]
	v_mfma_f32_16x16x32_bf16 v[14:17], v[146:149], v[194:197], v[14:17]
	v_mfma_f32_16x16x32_bf16 v[70:73], v[138:141], v[202:205], v[70:73]
	v_mfma_f32_16x16x32_bf16 v[6:9], v[146:149], v[202:205], v[6:9]
	v_mfma_f32_16x16x32_bf16 v[102:105], v[138:141], v[228:231], v[102:105]
	v_mfma_f32_16x16x32_bf16 v[30:33], v[146:149], v[228:231], v[30:33]
	v_mfma_f32_16x16x32_bf16 v[98:101], v[138:141], v[236:239], v[98:101]
	v_mfma_f32_16x16x32_bf16 v[26:29], v[146:149], v[236:239], v[26:29]
	v_mfma_f32_16x16x32_bf16 v[86:89], v[142:145], v[198:201], v[86:89]
	v_mfma_f32_16x16x32_bf16 v[14:17], v[150:153], v[198:201], v[14:17]
	v_mfma_f32_16x16x32_bf16 v[70:73], v[142:145], v[214:217], v[70:73]
	v_mfma_f32_16x16x32_bf16 v[6:9], v[150:153], v[214:217], v[6:9]
	v_mfma_f32_16x16x32_bf16 v[102:105], v[142:145], v[232:235], v[102:105]
	v_mfma_f32_16x16x32_bf16 v[30:33], v[150:153], v[232:235], v[30:33]
	v_mfma_f32_16x16x32_bf16 v[98:101], v[142:145], v[240:243], v[98:101]
	v_mfma_f32_16x16x32_bf16 v[26:29], v[150:153], v[240:243], v[26:29]
	v_mfma_f32_16x16x32_bf16 v[82:85], v[154:157], v[194:197], v[82:85]
	v_mfma_f32_16x16x32_bf16 v[10:13], v[162:165], v[194:197], v[10:13]
	v_mfma_f32_16x16x32_bf16 v[66:69], v[154:157], v[202:205], v[66:69]
	v_mfma_f32_16x16x32_bf16 v[2:5], v[162:165], v[202:205], v[2:5]
	v_mfma_f32_16x16x32_bf16 v[94:97], v[154:157], v[228:231], v[94:97]
	v_mfma_f32_16x16x32_bf16 v[22:25], v[162:165], v[228:231], v[22:25]
	v_mfma_f32_16x16x32_bf16 v[90:93], v[154:157], v[236:239], v[90:93]
	v_mfma_f32_16x16x32_bf16 v[18:21], v[162:165], v[236:239], v[18:21]
	v_mfma_f32_16x16x32_bf16 v[82:85], v[158:161], v[198:201], v[82:85]
	v_mfma_f32_16x16x32_bf16 v[10:13], v[166:169], v[198:201], v[10:13]
	v_mfma_f32_16x16x32_bf16 v[66:69], v[158:161], v[214:217], v[66:69]
	v_mfma_f32_16x16x32_bf16 v[2:5], v[166:169], v[214:217], v[2:5]
	v_mfma_f32_16x16x32_bf16 v[94:97], v[158:161], v[232:235], v[94:97]
	v_mfma_f32_16x16x32_bf16 v[22:25], v[166:169], v[232:235], v[22:25]
	v_mfma_f32_16x16x32_bf16 v[90:93], v[158:161], v[240:243], v[90:93]
	v_mfma_f32_16x16x32_bf16 v[18:21], v[166:169], v[240:243], v[18:21]
	s_barrier
	s_add_u32 s35, s35, 0x100
	s_addc_u32 s51, s51, 0
	s_cmp_ge_i32 s52, s67
	s_mov_b64 s[48:49], s[14:15]
	s_mov_b32 s46, s52
	s_cbranch_scc0 .LBB0_809
	s_movk_i32 s75, 0x2000
	s_movk_i32 s76, 0x3000
	s_and_b64 vcc, exec, s[30:31]
	s_cbranch_vccz .LBB0_784

;     __host__ __device__ bool next(int i, Unit& u) const { const int P = (i >> 1) * G + c; if (P >= 256) return false; u.pm = P >> 3; u.pn = (P & 7) + 8 * (i & 1); return true; }
; template <class Epi, class Sched, bool ALIGN_EPI = false, bool SP2 = false>
; __device__ __forceinline__ void gemm_phase(PG8_LAS unsigned char* lds, const Gemm g, const Sched& S, const Epi& E, const int wv) {
;     ...
;     for (;;) {
;         const bool has_next = S.next(ui + 1, nxt);
;         const char* nA = has_next ? (const char*)g.A + (size_t)nxt.pm * tstepA + (g.amod ? (size_t)(nxt.pn % g.amod) * K * 2 : (size_t)0) : cA; const char* nB = has_next ? (const char*)g.Bt + (size_t)nxt.pn * tstepB : cB;
;     ...
; #pragma unroll
;         for (int a = 0; a < 2; ++a)
; #pragma unroll
;             for (int b = 0; b < 2; ++b)
; #pragma unroll
;                 for (int m = 0; m < 4; ++m)
; #pragma unroll
;                     for (int n = 0; n < 2; ++n) acc[a][b][m][n] = (f32x4){0.f, 0.f, 0.f, 0.f};
.LBB0_1072:
	s_ashr_i32 s17, s16, 31
	s_lshl_b64 s[24:25], s[16:17], 20
	s_add_u32 s24, s43, s24
	v_mov_b32_e32 v133, 0
	s_addc_u32 s25, s44, s25
	s_andn2_b64 vcc, exec, s[12:13]
	v_mov_b32_e32 v132, v133
	v_pk_mov_b32 v[130:131], v[132:133], v[132:133]
	v_pk_mov_b32 v[128:129], v[132:133], v[132:133]
	v_pk_mov_b32 v[126:127], v[132:133], v[132:133]
	v_pk_mov_b32 v[116:117], v[132:133], v[132:133]
	v_pk_mov_b32 v[114:115], v[132:133], v[132:133]
	v_pk_mov_b32 v[112:113], v[132:133], v[132:133]
	v_pk_mov_b32 v[110:111], v[132:133], v[132:133]
	v_pk_mov_b32 v[100:101], v[132:133], v[132:133]
	v_pk_mov_b32 v[98:99], v[132:133], v[132:133]
	s_nop 0
	v_pk_mov_b32 v[96:97], v[132:133], v[132:133]
	v_pk_mov_b32 v[94:95], v[132:133], v[132:133]
	v_pk_mov_b32 v[84:85], v[132:133], v[132:133]
	v_pk_mov_b32 v[82:83], v[132:133], v[132:133]
	v_pk_mov_b32 v[80:81], v[132:133], v[132:133]
	v_pk_mov_b32 v[78:79], v[132:133], v[132:133]
	v_pk_mov_b32 v[124:125], v[132:133], v[132:133]
	v_pk_mov_b32 v[122:123], v[132:133], v[132:133]
	v_pk_mov_b32 v[120:121], v[132:133], v[132:133]
	v_pk_mov_b32 v[118:119], v[132:133], v[132:133]
	v_pk_mov_b32 v[108:109], v[132:133], v[132:133]
	v_pk_mov_b32 v[106:107], v[132:133], v[132:133]
	v_pk_mov_b32 v[104:105], v[132:133], v[132:133]
	v_pk_mov_b32 v[102:103], v[132:133], v[132:133]
	v_pk_mov_b32 v[92:93], v[132:133], v[132:133]
	v_pk_mov_b32 v[90:91], v[132:133], v[132:133]
	v_pk_mov_b32 v[88:89], v[132:133], v[132:133]
	v_pk_mov_b32 v[86:87], v[132:133], v[132:133]
	v_pk_mov_b32 v[76:77], v[132:133], v[132:133]
	v_pk_mov_b32 v[74:75], v[132:133], v[132:133]
	v_pk_mov_b32 v[72:73], v[132:133], v[132:133]
	v_pk_mov_b32 v[70:71], v[132:133], v[132:133]
	v_pk_mov_b32 v[68:69], v[132:133], v[132:133]
	v_pk_mov_b32 v[66:67], v[132:133], v[132:133]
	v_pk_mov_b32 v[64:65], v[132:133], v[132:133]
	v_pk_mov_b32 v[62:63], v[132:133], v[132:133]
	v_pk_mov_b32 v[52:53], v[132:133], v[132:133]
	v_pk_mov_b32 v[50:51], v[132:133], v[132:133]
	v_pk_mov_b32 v[48:49], v[132:133], v[132:133]
	v_pk_mov_b32 v[46:47], v[132:133], v[132:133]
	v_pk_mov_b32 v[36:37], v[132:133], v[132:133]
	v_pk_mov_b32 v[34:35], v[132:133], v[132:133]
	v_pk_mov_b32 v[32:33], v[132:133], v[132:133]
	v_pk_mov_b32 v[30:31], v[132:133], v[132:133]
	v_pk_mov_b32 v[20:21], v[132:133], v[132:133]
	v_pk_mov_b32 v[18:19], v[132:133], v[132:133]
	v_pk_mov_b32 v[16:17], v[132:133], v[132:133]
	v_pk_mov_b32 v[14:15], v[132:133], v[132:133]
	v_pk_mov_b32 v[60:61], v[132:133], v[132:133]
	v_pk_mov_b32 v[58:59], v[132:133], v[132:133]
	v_pk_mov_b32 v[56:57], v[132:133], v[132:133]
	v_pk_mov_b32 v[54:55], v[132:133], v[132:133]
	v_pk_mov_b32 v[44:45], v[132:133], v[132:133]
	v_pk_mov_b32 v[42:43], v[132:133], v[132:133]
	v_pk_mov_b32 v[40:41], v[132:133], v[132:133]
	v_pk_mov_b32 v[38:39], v[132:133], v[132:133]
	v_pk_mov_b32 v[28:29], v[132:133], v[132:133]
	v_pk_mov_b32 v[26:27], v[132:133], v[132:133]
	v_pk_mov_b32 v[24:25], v[132:133], v[132:133]
	v_pk_mov_b32 v[22:23], v[132:133], v[132:133]
	v_pk_mov_b32 v[12:13], v[132:133], v[132:133]
	v_pk_mov_b32 v[10:11], v[132:133], v[132:133]
	v_pk_mov_b32 v[8:9], v[132:133], v[132:133]
	v_pk_mov_b32 v[6:7], v[132:133], v[132:133]
	s_cbranch_vccnz .LBB0_1076
	s_and_b64 s[40:41], s[40:41], exec
	s_cselect_b32 s17, s25, s29
	s_cselect_b32 s40, s24, s28
	s_add_u32 s28, s28, 0x80080
	s_addc_u32 s29, s29, 0
	s_add_u32 s41, s30, 0x100
	v_mov_b32_e32 v6, 0
	s_addc_u32 s62, s31, 0
	s_mov_b32 s30, 0
	v_mov_b32_e32 v7, v6
	v_pk_mov_b32 v[8:9], v[6:7], v[6:7]
	v_pk_mov_b32 v[10:11], v[6:7], v[6:7]
	v_pk_mov_b32 v[12:13], v[6:7], v[6:7]
	v_pk_mov_b32 v[22:23], v[6:7], v[6:7]
	v_pk_mov_b32 v[24:25], v[6:7], v[6:7]
	v_pk_mov_b32 v[26:27], v[6:7], v[6:7]
	v_pk_mov_b32 v[28:29], v[6:7], v[6:7]
	v_pk_mov_b32 v[38:39], v[6:7], v[6:7]
	v_pk_mov_b32 v[40:41], v[6:7], v[6:7]
	v_pk_mov_b32 v[42:43], v[6:7], v[6:7]
	v_pk_mov_b32 v[44:45], v[6:7], v[6:7]
	v_pk_mov_b32 v[54:55], v[6:7], v[6:7]
	v_pk_mov_b32 v[56:57], v[6:7], v[6:7]
	v_pk_mov_b32 v[58:59], v[6:7], v[6:7]
	v_pk_mov_b32 v[60:61], v[6:7], v[6:7]
	v_pk_mov_b32 v[14:15], v[6:7], v[6:7]
	v_pk_mov_b32 v[16:17], v[6:7], v[6:7]
	v_pk_mov_b32 v[18:19], v[6:7], v[6:7]
	v_pk_mov_b32 v[20:21], v[6:7], v[6:7]
	v_pk_mov_b32 v[30:31], v[6:7], v[6:7]
	v_pk_mov_b32 v[32:33], v[6:7], v[6:7]
	v_pk_mov_b32 v[34:35], v[6:7], v[6:7]
	v_pk_mov_b32 v[36:37], v[6:7], v[6:7]
	v_pk_mov_b32 v[46:47], v[6:7], v[6:7]
	v_pk_mov_b32 v[48:49], v[6:7], v[6:7]
	v_pk_mov_b32 v[50:51], v[6:7], v[6:7]
	v_pk_mov_b32 v[52:53], v[6:7], v[6:7]
	v_pk_mov_b32 v[62:63], v[6:7], v[6:7]
	v_pk_mov_b32 v[64:65], v[6:7], v[6:7]
	v_pk_mov_b32 v[66:67], v[6:7], v[6:7]
	v_pk_mov_b32 v[68:69], v[6:7], v[6:7]
	v_pk_mov_b32 v[70:71], v[6:7], v[6:7]
	v_pk_mov_b32 v[72:73], v[6:7], v[6:7]
	v_pk_mov_b32 v[74:75], v[6:7], v[6:7]
	v_pk_mov_b32 v[76:77], v[6:7], v[6:7]
	v_pk_mov_b32 v[86:87], v[6:7], v[6:7]
	v_pk_mov_b32 v[88:89], v[6:7], v[6:7]
	v_pk_mov_b32 v[90:91], v[6:7], v[6:7]
	v_pk_mov_b32 v[92:93], v[6:7], v[6:7]
	v_pk_mov_b32 v[102:103], v[6:7], v[6:7]
	v_pk_mov_b32 v[104:105], v[6:7], v[6:7]
	v_pk_mov_b32 v[106:107], v[6:7], v[6:7]
	v_pk_mov_b32 v[108:109], v[6:7], v[6:7]
	v_pk_mov_b32 v[118:119], v[6:7], v[6:7]
	v_pk_mov_b32 v[120:121], v[6:7], v[6:7]
	v_pk_mov_b32 v[122:123], v[6:7], v[6:7]
	v_pk_mov_b32 v[124:125], v[6:7], v[6:7]
	v_pk_mov_b32 v[78:79], v[6:7], v[6:7]
	v_pk_mov_b32 v[80:81], v[6:7], v[6:7]
	v_pk_mov_b32 v[82:83], v[6:7], v[6:7]
	v_pk_mov_b32 v[84:85], v[6:7], v[6:7]
	v_pk_mov_b32 v[94:95], v[6:7], v[6:7]
	v_pk_mov_b32 v[96:97], v[6:7], v[6:7]
	v_pk_mov_b32 v[98:99], v[6:7], v[6:7]
	v_pk_mov_b32 v[100:101], v[6:7], v[6:7]
	v_pk_mov_b32 v[110:111], v[6:7], v[6:7]
	v_pk_mov_b32 v[112:113], v[6:7], v[6:7]
	v_pk_mov_b32 v[114:115], v[6:7], v[6:7]
	v_pk_mov_b32 v[116:117], v[6:7], v[6:7]
	v_pk_mov_b32 v[126:127], v[6:7], v[6:7]
	v_pk_mov_b32 v[128:129], v[6:7], v[6:7]
	v_pk_mov_b32 v[130:131], v[6:7], v[6:7]
	v_pk_mov_b32 v[132:133], v[6:7], v[6:7]
	v_add_u32_e32 v147, 0x10000, v157
	v_add_u32_e32 v149, 0x14000, v157
	v_add_u32_e32 v152, 0x18000, v157
	v_add_u32_e32 v154, 0x1c000, v157
	v_add_u32_e32 v0, 0x80000, v140
	v_add_u32_e32 v156, 0x80000, v136
; #define PG8_STAGE(bufoff, gbase, voff) do { _Pragma("unroll") for (int _i = 0; _i < 2; ++_i) \
;         __builtin_amdgcn_global_load_lds((const unsigned*)((const char*)(gbase) + (voff)[_i]), (PG8_LAS unsigned*)(lds + (bufoff) + ldsw + _i * 8192), 16, 0, 0); } while (0)
; #define PG8_LDA(dst, b, h) do { _Pragma("unroll") for (int m = 0; m < 4; ++m) _Pragma("unroll") for (int k = 0; k < 2; ++k) dst[m][k] = *(const PG8_LAS bf16x8*)(lds + PG8_SA(b, h) + aoff + m * 2048 + k * 1024); } while (0)
; #define PG8_LDB(dst, b, h) do { _Pragma("unroll") for (int n = 0; n < 2; ++n) _Pragma("unroll") for (int k = 0; k < 2; ++k) dst[n][k] = *(const PG8_LAS bf16x8*)(lds + PG8_SB(b, h) + boff + n * 2048 + k * 1024); } while (0)
; #define PG8_MMA(ai, bj, At, Bt) do { __builtin_amdgcn_s_setprio(1); _Pragma("unroll") for (int m = 0; m < 4; ++m) _Pragma("unroll") for (int n = 0; n < 2; ++n) _Pragma("unroll") for (int k = 0; k < 2; ++k) \
;         acc[ai][bj][m][n] = __builtin_amdgcn_mfma_f32_16x16x32_bf16(Bt[n][k], At[m][k], acc[ai][bj][m][n], 0, 0, 0); __builtin_amdgcn_s_setprio(0); } while (0)
; #define PG8_WAIT_V(n) asm volatile("s_waitcnt vmcnt(" #n ")" ::: "memory")
; #define PG8_WAIT_L(n) asm volatile("s_waitcnt lgkmcnt(" #n ")" ::: "memory")
; template <class Epi, class Sched, bool ALIGN_EPI = false, bool SP2 = false>
; __device__ __forceinline__ void gemm_phase(PG8_LAS unsigned char* lds, const Gemm g, const Sched& S, const Epi& E, const int wv) {
;     ...
;             const bool last = (t == nt - 2);
;             const char* a1 = cA + (size_t)(t + 1) * kstep;
;             const char* a2 = last ? nA : cA + (size_t)(t + 2) * kstep; const char* b2 = last ? nB : cB + (size_t)(t + 2) * kstep;
;             const char* a3 = a2 + kstep; const char* b3 = b2 + kstep;
;             if (last && has_next) S.a_ready(nxt);
;             if constexpr (SP2) {
;             PG8_LDB(B0, 0, 0); PG8_LDB(B1, 0, 1); PG8_SCHED; PG8_LDA(At, 0, 0); PG8_STAGE(PG8_SA(1, 1), a1 + hstepA, voffA);
;             PG8_WAIT_V(8); PG8_WAIT_L(0); PG8_BAR; PG8_MMA(0, 0, At, B0); PG8_MMA(0, 1, At, B1); PG8_BAR; PG8_SCHED;
;             PG8_LDA(At, 0, 1); PG8_STAGE(PG8_SB(0, 0), b2, voffB); PG8_STAGE(PG8_SB(0, 1), b2 + hstepB, voffB); PG8_STAGE(PG8_SA(0, 0), a2, voffA);
;             PG8_WAIT_V(8); PG8_WAIT_L(0); PG8_BAR; PG8_MMA(1, 0, At, B0); PG8_MMA(1, 1, At, B1); PG8_BAR; PG8_SCHED;
.LBB0_1074:
	s_add_i32 s63, s30, 2
	s_add_u32 s64, s28, 0xfff80080
	s_addc_u32 s31, s29, -1
	s_cmp_eq_u32 s57, s30
	s_cselect_b32 s31, s17, s31
	s_cselect_b32 s30, s40, s64
	s_cselect_b32 s65, s19, s62
	s_cselect_b32 s64, s18, s41
	ds_read_b128 v[164:167], v147
	ds_read_b128 v[168:171], v147 offset:1024
	ds_read_b128 v[172:175], v147 offset:2048
	ds_read_b128 v[176:179], v147 offset:3072
	ds_read_b128 v[180:183], v149
	ds_read_b128 v[194:197], v149 offset:1024
	ds_read_b128 v[198:201], v149 offset:2048
	ds_read_b128 v[202:205], v149 offset:3072
	s_add_i32 m0, s47, 0xc000
	ds_read_b128 v[206:209], v163
	ds_read_b128 v[210:213], v163 offset:1024
	ds_read_b128 v[214:217], v163 offset:2048
	ds_read_b128 v[228:231], v163 offset:3072
	ds_read_b128 v[232:235], v163 offset:4096
	ds_read_b128 v[236:239], v163 offset:5120
	ds_read_b128 v[240:243], v163 offset:6144
	ds_read_b128 v[244:247], v163 offset:7168
	global_load_lds_dwordx4 v146, s[28:29]
	s_add_i32 m0, s47, 0xe000
	s_nop 0
	global_load_lds_dwordx4 v148, s[28:29]
	s_waitcnt vmcnt(8) lgkmcnt(0)
	s_barrier
	v_mfma_f32_16x16x32_bf16 v[130:133], v[164:167], v[206:209], v[130:133]
	v_mfma_f32_16x16x32_bf16 v[126:129], v[172:175], v[206:209], v[126:129]
	v_mfma_f32_16x16x32_bf16 v[114:117], v[164:167], v[214:217], v[114:117]
	v_mfma_f32_16x16x32_bf16 v[110:113], v[172:175], v[214:217], v[110:113]
	v_mfma_f32_16x16x32_bf16 v[98:101], v[164:167], v[232:235], v[98:101]
	v_mfma_f32_16x16x32_bf16 v[94:97], v[172:175], v[232:235], v[94:97]
	v_mfma_f32_16x16x32_bf16 v[82:85], v[164:167], v[240:243], v[82:85]
	v_mfma_f32_16x16x32_bf16 v[78:81], v[172:175], v[240:243], v[78:81]
	v_mfma_f32_16x16x32_bf16 v[130:133], v[168:171], v[210:213], v[130:133]
	v_mfma_f32_16x16x32_bf16 v[126:129], v[176:179], v[210:213], v[126:129]
	v_mfma_f32_16x16x32_bf16 v[114:117], v[168:171], v[228:231], v[114:117]
	v_mfma_f32_16x16x32_bf16 v[110:113], v[176:179], v[228:231], v[110:113]
	v_mfma_f32_16x16x32_bf16 v[98:101], v[168:171], v[236:239], v[98:101]
	v_mfma_f32_16x16x32_bf16 v[94:97], v[176:179], v[236:239], v[94:97]
	v_mfma_f32_16x16x32_bf16 v[82:85], v[168:171], v[244:247], v[82:85]
	v_mfma_f32_16x16x32_bf16 v[78:81], v[176:179], v[244:247], v[78:81]
	v_mfma_f32_16x16x32_bf16 v[122:125], v[180:183], v[206:209], v[122:125]
	v_mfma_f32_16x16x32_bf16 v[118:121], v[198:201], v[206:209], v[118:121]
	v_mfma_f32_16x16x32_bf16 v[106:109], v[180:183], v[214:217], v[106:109]
	v_mfma_f32_16x16x32_bf16 v[102:105], v[198:201], v[214:217], v[102:105]
	v_mfma_f32_16x16x32_bf16 v[90:93], v[180:183], v[232:235], v[90:93]
	v_mfma_f32_16x16x32_bf16 v[86:89], v[198:201], v[232:235], v[86:89]
	v_mfma_f32_16x16x32_bf16 v[74:77], v[180:183], v[240:243], v[74:77]
	v_mfma_f32_16x16x32_bf16 v[70:73], v[198:201], v[240:243], v[70:73]
	v_mfma_f32_16x16x32_bf16 v[122:125], v[194:197], v[210:213], v[122:125]
	v_mfma_f32_16x16x32_bf16 v[118:121], v[202:205], v[210:213], v[118:121]
	v_mfma_f32_16x16x32_bf16 v[106:109], v[194:197], v[228:231], v[106:109]
	v_mfma_f32_16x16x32_bf16 v[102:105], v[202:205], v[228:231], v[102:105]
	v_mfma_f32_16x16x32_bf16 v[90:93], v[194:197], v[236:239], v[90:93]
	v_mfma_f32_16x16x32_bf16 v[86:89], v[202:205], v[236:239], v[86:89]
	v_mfma_f32_16x16x32_bf16 v[74:77], v[194:197], v[244:247], v[74:77]
	v_mfma_f32_16x16x32_bf16 v[70:73], v[202:205], v[244:247], v[70:73]
	s_barrier
	s_add_i32 s66, s45, 0x10000
	v_lshl_add_u64 v[150:151], s[64:65], 0, v[138:139]
	s_mov_b32 m0, s66
	ds_read_b128 v[206:209], v163 offset:16384
	ds_read_b128 v[210:213], v163 offset:17408
	ds_read_b128 v[214:217], v163 offset:18432
	ds_read_b128 v[228:231], v163 offset:19456
	ds_read_b128 v[232:235], v163 offset:20480
	ds_read_b128 v[236:239], v163 offset:21504
	ds_read_b128 v[240:243], v163 offset:22528
	ds_read_b128 v[244:247], v163 offset:23552
	global_load_lds_dwordx4 v[150:151], off
	s_add_i32 m0, s66, 0x2000
	v_lshl_add_u64 v[184:185], s[64:65], 0, v[134:135]
	s_add_u32 s64, s64, s0
	s_addc_u32 s65, s65, s1
	s_add_i32 s66, s45, 0x14000
	global_load_lds_dwordx4 v[184:185], off
	s_mov_b32 m0, s66
	global_load_lds_dwordx4 v138, s[64:65]
	s_add_i32 m0, s66, 0x2000
	global_load_lds_dwordx4 v134, s[64:65]
	s_mov_b32 m0, s47
	global_load_lds_dwordx4 v140, s[30:31]
	s_mov_b32 m0, s48
	s_nop 0
	global_load_lds_dwordx4 v136, s[30:31]
	s_waitcnt vmcnt(8) lgkmcnt(0)
	s_barrier
	v_mfma_f32_16x16x32_bf16 v[66:69], v[164:167], v[206:209], v[66:69]
	v_mfma_f32_16x16x32_bf16 v[62:65], v[172:175], v[206:209], v[62:65]
	v_mfma_f32_16x16x32_bf16 v[50:53], v[164:167], v[214:217], v[50:53]
	v_mfma_f32_16x16x32_bf16 v[46:49], v[172:175], v[214:217], v[46:49]
	v_mfma_f32_16x16x32_bf16 v[34:37], v[164:167], v[232:235], v[34:37]
	v_mfma_f32_16x16x32_bf16 v[30:33], v[172:175], v[232:235], v[30:33]
	v_mfma_f32_16x16x32_bf16 v[18:21], v[164:167], v[240:243], v[18:21]
	v_mfma_f32_16x16x32_bf16 v[14:17], v[172:175], v[240:243], v[14:17]
	v_mfma_f32_16x16x32_bf16 v[66:69], v[168:171], v[210:213], v[66:69]
	v_mfma_f32_16x16x32_bf16 v[62:65], v[176:179], v[210:213], v[62:65]
	v_mfma_f32_16x16x32_bf16 v[50:53], v[168:171], v[228:231], v[50:53]
	v_mfma_f32_16x16x32_bf16 v[46:49], v[176:179], v[228:231], v[46:49]
	v_mfma_f32_16x16x32_bf16 v[34:37], v[168:171], v[236:239], v[34:37]
	v_mfma_f32_16x16x32_bf16 v[30:33], v[176:179], v[236:239], v[30:33]
	v_mfma_f32_16x16x32_bf16 v[18:21], v[168:171], v[244:247], v[18:21]
	v_mfma_f32_16x16x32_bf16 v[14:17], v[176:179], v[244:247], v[14:17]
	v_mfma_f32_16x16x32_bf16 v[58:61], v[180:183], v[206:209], v[58:61]
	v_mfma_f32_16x16x32_bf16 v[54:57], v[198:201], v[206:209], v[54:57]
	v_mfma_f32_16x16x32_bf16 v[42:45], v[180:183], v[214:217], v[42:45]
	v_mfma_f32_16x16x32_bf16 v[38:41], v[198:201], v[214:217], v[38:41]
	v_mfma_f32_16x16x32_bf16 v[26:29], v[180:183], v[232:235], v[26:29]
	v_mfma_f32_16x16x32_bf16 v[22:25], v[198:201], v[232:235], v[22:25]
	v_mfma_f32_16x16x32_bf16 v[10:13], v[180:183], v[240:243], v[10:13]
	v_mfma_f32_16x16x32_bf16 v[6:9], v[198:201], v[240:243], v[6:9]
	v_mfma_f32_16x16x32_bf16 v[58:61], v[194:197], v[210:213], v[58:61]
	v_mfma_f32_16x16x32_bf16 v[54:57], v[202:205], v[210:213], v[54:57]
	v_mfma_f32_16x16x32_bf16 v[42:45], v[194:197], v[228:231], v[42:45]
	v_mfma_f32_16x16x32_bf16 v[38:41], v[202:205], v[228:231], v[38:41]
	v_mfma_f32_16x16x32_bf16 v[26:29], v[194:197], v[236:239], v[26:29]
	v_mfma_f32_16x16x32_bf16 v[22:25], v[202:205], v[236:239], v[22:25]
	v_mfma_f32_16x16x32_bf16 v[10:13], v[194:197], v[244:247], v[10:13]
	v_mfma_f32_16x16x32_bf16 v[6:9], v[202:205], v[244:247], v[6:9]
	s_barrier
; #define PG8_STAGE(bufoff, gbase, voff) do { _Pragma("unroll") for (int _i = 0; _i < 2; ++_i) \
;         __builtin_amdgcn_global_load_lds((const unsigned*)((const char*)(gbase) + (voff)[_i]), (PG8_LAS unsigned*)(lds + (bufoff) + ldsw + _i * 8192), 16, 0, 0); } while (0)
; #define PG8_LDA(dst, b, h) do { _Pragma("unroll") for (int m = 0; m < 4; ++m) _Pragma("unroll") for (int k = 0; k < 2; ++k) dst[m][k] = *(const PG8_LAS bf16x8*)(lds + PG8_SA(b, h) + aoff + m * 2048 + k * 1024); } while (0)
; #define PG8_LDB(dst, b, h) do { _Pragma("unroll") for (int n = 0; n < 2; ++n) _Pragma("unroll") for (int k = 0; k < 2; ++k) dst[n][k] = *(const PG8_LAS bf16x8*)(lds + PG8_SB(b, h) + boff + n * 2048 + k * 1024); } while (0)
; #define PG8_MMA(ai, bj, At, Bt) do { __builtin_amdgcn_s_setprio(1); _Pragma("unroll") for (int m = 0; m < 4; ++m) _Pragma("unroll") for (int n = 0; n < 2; ++n) _Pragma("unroll") for (int k = 0; k < 2; ++k) \
;         acc[ai][bj][m][n] = __builtin_amdgcn_mfma_f32_16x16x32_bf16(Bt[n][k], At[m][k], acc[ai][bj][m][n], 0, 0, 0); __builtin_amdgcn_s_setprio(0); } while (0)
; #define PG8_WAIT_V(n) asm volatile("s_waitcnt vmcnt(" #n ")" ::: "memory")
; #define PG8_WAIT_L(n) asm volatile("s_waitcnt lgkmcnt(" #n ")" ::: "memory")
; #define PG8_BAR __builtin_amdgcn_s_barrier()
; #define PG8_SCHED __builtin_amdgcn_sched_barrier(0)
; template <class Epi, class Sched, bool ALIGN_EPI = false, bool SP2 = false>
; __device__ __forceinline__ void gemm_phase(PG8_LAS unsigned char* lds, const Gemm g, const Sched& S, const Epi& E, const int wv) {
;     ...
;             PG8_LDB(B0, 1, 0); PG8_LDB(B1, 1, 1); PG8_SCHED; PG8_LDA(At, 1, 0); PG8_STAGE(PG8_SA(0, 1), a2 + hstepA, voffA);
;             PG8_WAIT_V(8); PG8_WAIT_L(0); PG8_BAR; PG8_MMA(0, 0, At, B0); PG8_MMA(0, 1, At, B1); PG8_BAR; PG8_SCHED;
;             PG8_LDA(At, 1, 1); PG8_STAGE(PG8_SB(1, 0), b3, voffB); PG8_STAGE(PG8_SB(1, 1), b3 + hstepB, voffB); PG8_STAGE(PG8_SA(1, 0), a3, voffA);
;             PG8_WAIT_V(8); PG8_WAIT_L(0); PG8_BAR; PG8_MMA(1, 0, At, B0); PG8_MMA(1, 1, At, B1); PG8_BAR; PG8_SCHED;
	ds_read_b128 v[164:167], v152
	ds_read_b128 v[168:171], v152 offset:1024
	ds_read_b128 v[172:175], v152 offset:2048
	ds_read_b128 v[176:179], v152 offset:3072
	ds_read_b128 v[180:183], v154
	ds_read_b128 v[194:197], v154 offset:1024
	ds_read_b128 v[198:201], v154 offset:2048
	ds_read_b128 v[202:205], v154 offset:3072
	s_mov_b32 m0, s49
	ds_read_b128 v[206:209], v163 offset:32768
	ds_read_b128 v[210:213], v163 offset:33792
	ds_read_b128 v[214:217], v163 offset:34816
	ds_read_b128 v[228:231], v163 offset:35840
	ds_read_b128 v[232:235], v163 offset:36864
	ds_read_b128 v[236:239], v163 offset:37888
	ds_read_b128 v[240:243], v163 offset:38912
	ds_read_b128 v[244:247], v163 offset:39936
	global_load_lds_dwordx4 v0, s[30:31]
	s_mov_b32 m0, s50
	s_nop 0
	global_load_lds_dwordx4 v156, s[30:31]
	s_waitcnt vmcnt(8) lgkmcnt(0)
	s_barrier
	v_mfma_f32_16x16x32_bf16 v[130:133], v[164:167], v[206:209], v[130:133]
	v_mfma_f32_16x16x32_bf16 v[126:129], v[172:175], v[206:209], v[126:129]
	v_mfma_f32_16x16x32_bf16 v[114:117], v[164:167], v[214:217], v[114:117]
	v_mfma_f32_16x16x32_bf16 v[110:113], v[172:175], v[214:217], v[110:113]
	v_mfma_f32_16x16x32_bf16 v[98:101], v[164:167], v[232:235], v[98:101]
	v_mfma_f32_16x16x32_bf16 v[94:97], v[172:175], v[232:235], v[94:97]
	v_mfma_f32_16x16x32_bf16 v[82:85], v[164:167], v[240:243], v[82:85]
	v_mfma_f32_16x16x32_bf16 v[78:81], v[172:175], v[240:243], v[78:81]
	v_mfma_f32_16x16x32_bf16 v[130:133], v[168:171], v[210:213], v[130:133]
	v_mfma_f32_16x16x32_bf16 v[126:129], v[176:179], v[210:213], v[126:129]
	v_mfma_f32_16x16x32_bf16 v[114:117], v[168:171], v[228:231], v[114:117]
	v_mfma_f32_16x16x32_bf16 v[110:113], v[176:179], v[228:231], v[110:113]
	v_mfma_f32_16x16x32_bf16 v[98:101], v[168:171], v[236:239], v[98:101]
	v_mfma_f32_16x16x32_bf16 v[94:97], v[176:179], v[236:239], v[94:97]
	v_mfma_f32_16x16x32_bf16 v[82:85], v[168:171], v[244:247], v[82:85]
	v_mfma_f32_16x16x32_bf16 v[78:81], v[176:179], v[244:247], v[78:81]
	v_mfma_f32_16x16x32_bf16 v[122:125], v[180:183], v[206:209], v[122:125]
	v_mfma_f32_16x16x32_bf16 v[118:121], v[198:201], v[206:209], v[118:121]
	v_mfma_f32_16x16x32_bf16 v[106:109], v[180:183], v[214:217], v[106:109]
	v_mfma_f32_16x16x32_bf16 v[102:105], v[198:201], v[214:217], v[102:105]
	v_mfma_f32_16x16x32_bf16 v[90:93], v[180:183], v[232:235], v[90:93]
	v_mfma_f32_16x16x32_bf16 v[86:89], v[198:201], v[232:235], v[86:89]
	v_mfma_f32_16x16x32_bf16 v[74:77], v[180:183], v[240:243], v[74:77]
	v_mfma_f32_16x16x32_bf16 v[70:73], v[198:201], v[240:243], v[70:73]
	v_mfma_f32_16x16x32_bf16 v[122:125], v[194:197], v[210:213], v[122:125]
	v_mfma_f32_16x16x32_bf16 v[118:121], v[202:205], v[210:213], v[118:121]
	v_mfma_f32_16x16x32_bf16 v[106:109], v[194:197], v[228:231], v[106:109]
	v_mfma_f32_16x16x32_bf16 v[102:105], v[202:205], v[228:231], v[102:105]
	v_mfma_f32_16x16x32_bf16 v[90:93], v[194:197], v[236:239], v[90:93]
	v_mfma_f32_16x16x32_bf16 v[86:89], v[202:205], v[236:239], v[86:89]
	v_mfma_f32_16x16x32_bf16 v[74:77], v[194:197], v[244:247], v[74:77]
	v_mfma_f32_16x16x32_bf16 v[70:73], v[202:205], v[244:247], v[70:73]
	s_barrier
	s_add_i32 m0, s45, 0x17f80
	ds_read_b128 v[206:209], v163 offset:49152
	ds_read_b128 v[210:213], v163 offset:50176
	ds_read_b128 v[214:217], v163 offset:51200
	ds_read_b128 v[228:231], v163 offset:52224
	ds_read_b128 v[232:235], v163 offset:53248
	ds_read_b128 v[236:239], v163 offset:54272
	ds_read_b128 v[240:243], v163 offset:55296
	ds_read_b128 v[244:247], v163 offset:56320
	global_load_lds_dwordx4 v[150:151], off offset:128
	s_add_i32 m0, s45, 0x19f80
	global_load_lds_dwordx4 v[184:185], off offset:128
	s_add_i32 m0, s45, 0x1bf80
	s_nop 0
	global_load_lds_dwordx4 v138, s[64:65] offset:128
	s_add_i32 m0, s45, 0x1df80
	s_nop 0
	global_load_lds_dwordx4 v134, s[64:65] offset:128
	s_add_i32 m0, s53, 0xffffff80
	s_nop 0
	global_load_lds_dwordx4 v140, s[30:31] offset:128
	s_add_i32 m0, s54, 0xffffff80
	s_nop 0
	global_load_lds_dwordx4 v136, s[30:31] offset:128
	s_waitcnt vmcnt(8) lgkmcnt(0)
	s_barrier
	v_mfma_f32_16x16x32_bf16 v[66:69], v[164:167], v[206:209], v[66:69]
	v_mfma_f32_16x16x32_bf16 v[62:65], v[172:175], v[206:209], v[62:65]
	v_mfma_f32_16x16x32_bf16 v[50:53], v[164:167], v[214:217], v[50:53]
	v_mfma_f32_16x16x32_bf16 v[46:49], v[172:175], v[214:217], v[46:49]
	v_mfma_f32_16x16x32_bf16 v[34:37], v[164:167], v[232:235], v[34:37]
	v_mfma_f32_16x16x32_bf16 v[30:33], v[172:175], v[232:235], v[30:33]
	v_mfma_f32_16x16x32_bf16 v[18:21], v[164:167], v[240:243], v[18:21]
	v_mfma_f32_16x16x32_bf16 v[14:17], v[172:175], v[240:243], v[14:17]
	v_mfma_f32_16x16x32_bf16 v[66:69], v[168:171], v[210:213], v[66:69]
	v_mfma_f32_16x16x32_bf16 v[62:65], v[176:179], v[210:213], v[62:65]
	v_mfma_f32_16x16x32_bf16 v[50:53], v[168:171], v[228:231], v[50:53]
	v_mfma_f32_16x16x32_bf16 v[46:49], v[176:179], v[228:231], v[46:49]
	v_mfma_f32_16x16x32_bf16 v[34:37], v[168:171], v[236:239], v[34:37]
	v_mfma_f32_16x16x32_bf16 v[30:33], v[176:179], v[236:239], v[30:33]
	v_mfma_f32_16x16x32_bf16 v[18:21], v[168:171], v[244:247], v[18:21]
	v_mfma_f32_16x16x32_bf16 v[14:17], v[176:179], v[244:247], v[14:17]
	v_mfma_f32_16x16x32_bf16 v[58:61], v[180:183], v[206:209], v[58:61]
	v_mfma_f32_16x16x32_bf16 v[54:57], v[198:201], v[206:209], v[54:57]
	v_mfma_f32_16x16x32_bf16 v[42:45], v[180:183], v[214:217], v[42:45]
	v_mfma_f32_16x16x32_bf16 v[38:41], v[198:201], v[214:217], v[38:41]
	v_mfma_f32_16x16x32_bf16 v[26:29], v[180:183], v[232:235], v[26:29]
	v_mfma_f32_16x16x32_bf16 v[22:25], v[198:201], v[232:235], v[22:25]
	v_mfma_f32_16x16x32_bf16 v[10:13], v[180:183], v[240:243], v[10:13]
	v_mfma_f32_16x16x32_bf16 v[6:9], v[198:201], v[240:243], v[6:9]
	v_mfma_f32_16x16x32_bf16 v[58:61], v[194:197], v[210:213], v[58:61]
	v_mfma_f32_16x16x32_bf16 v[54:57], v[202:205], v[210:213], v[54:57]
	v_mfma_f32_16x16x32_bf16 v[42:45], v[194:197], v[228:231], v[42:45]
	v_mfma_f32_16x16x32_bf16 v[38:41], v[202:205], v[228:231], v[38:41]
	v_mfma_f32_16x16x32_bf16 v[26:29], v[194:197], v[236:239], v[26:29]
	v_mfma_f32_16x16x32_bf16 v[22:25], v[202:205], v[236:239], v[22:25]
	v_mfma_f32_16x16x32_bf16 v[10:13], v[194:197], v[244:247], v[10:13]
	v_mfma_f32_16x16x32_bf16 v[6:9], v[202:205], v[244:247], v[6:9]
	s_barrier
	s_add_u32 s28, s28, 0x100
	s_addc_u32 s29, s29, 0
	s_add_u32 s41, s41, 0x100
	s_addc_u32 s62, s62, 0
	s_cmp_ge_i32 s63, s55
	s_mov_b32 s30, s63
	s_cbranch_scc0 .LBB0_1074
	v_readlane_b32 s67, v255, 30

; #define PG8_STAGE(bufoff, gbase, voff) do { _Pragma("unroll") for (int _i = 0; _i < 2; ++_i) \
;         __builtin_amdgcn_global_load_lds((const unsigned*)((const char*)(gbase) + (voff)[_i]), (PG8_LAS unsigned*)(lds + (bufoff) + ldsw + _i * 8192), 16, 0, 0); } while (0)
; #define PG8_LDA(dst, b, h) do { _Pragma("unroll") for (int m = 0; m < 4; ++m) _Pragma("unroll") for (int k = 0; k < 2; ++k) dst[m][k] = *(const PG8_LAS bf16x8*)(lds + PG8_SA(b, h) + aoff + m * 2048 + k * 1024); } while (0)
; #define PG8_LDB(dst, b, h) do { _Pragma("unroll") for (int n = 0; n < 2; ++n) _Pragma("unroll") for (int k = 0; k < 2; ++k) dst[n][k] = *(const PG8_LAS bf16x8*)(lds + PG8_SB(b, h) + boff + n * 2048 + k * 1024); } while (0)
; #define PG8_MMA(ai, bj, At, Bt) do { __builtin_amdgcn_s_setprio(1); _Pragma("unroll") for (int m = 0; m < 4; ++m) _Pragma("unroll") for (int n = 0; n < 2; ++n) _Pragma("unroll") for (int k = 0; k < 2; ++k) \
;         acc[ai][bj][m][n] = __builtin_amdgcn_mfma_f32_16x16x32_bf16(Bt[n][k], At[m][k], acc[ai][bj][m][n], 0, 0, 0); __builtin_amdgcn_s_setprio(0); } while (0)
; #define PG8_WAIT_V(n) asm volatile("s_waitcnt vmcnt(" #n ")" ::: "memory")
; template <class Epi, class Sched, bool ALIGN_EPI = false, bool SP2 = false>
; __device__ __forceinline__ void gemm_phase(PG8_LAS unsigned char* lds, const Gemm g, const Sched& S, const Epi& E, const int wv) {
;     ...
;             const bool last = (t == nt - 2);
;             const char* a1 = cA + (size_t)(t + 1) * kstep;
;             const char* a2 = last ? nA : cA + (size_t)(t + 2) * kstep; const char* b2 = last ? nB : cB + (size_t)(t + 2) * kstep;
;             const char* a3 = a2 + kstep; const char* b3 = b2 + kstep;
;             if (last && has_next) S.a_ready(nxt);
;             if constexpr (SP2) {
;             PG8_LDB(B0, 0, 0); PG8_LDB(B1, 0, 1); PG8_SCHED; PG8_LDA(At, 0, 0); PG8_STAGE(PG8_SA(1, 1), a1 + hstepA, voffA);
;             PG8_WAIT_V(8); PG8_WAIT_L(0); PG8_BAR; PG8_MMA(0, 0, At, B0); PG8_MMA(0, 1, At, B1); PG8_BAR; PG8_SCHED;
;     ...
; #pragma unroll
;         for (int a = 0; a < 2; ++a)
; #pragma unroll
;             for (int b = 0; b < 2; ++b)
; #pragma unroll
;                 for (int m = 0; m < 4; ++m)
; #pragma unroll
;                     for (int n = 0; n < 2; ++n) acc[a][b][m][n] = (f32x4){0.f, 0.f, 0.f, 0.f};
;         cur = nxt; cA = nA; cB = nB; ++ui;
.LBB0_1384:
	s_and_b64 s[44:45], s[44:45], exec
	s_cselect_b32 s13, s49, s53
	s_cselect_b32 s19, s48, s52
	s_add_u32 s44, s52, 0x40080
	s_addc_u32 s45, s53, 0
	s_add_u32 s54, s54, 0x100
	v_mov_b32_e32 v2, 0
	s_addc_u32 s55, s55, 0
	s_mov_b32 s52, 0
	v_mov_b32_e32 v3, v2
	v_pk_mov_b32 v[4:5], v[2:3], v[2:3]
	v_pk_mov_b32 v[6:7], v[2:3], v[2:3]
	v_pk_mov_b32 v[8:9], v[2:3], v[2:3]
	v_pk_mov_b32 v[18:19], v[2:3], v[2:3]
	v_pk_mov_b32 v[20:21], v[2:3], v[2:3]
	v_pk_mov_b32 v[22:23], v[2:3], v[2:3]
	v_pk_mov_b32 v[24:25], v[2:3], v[2:3]
	v_pk_mov_b32 v[34:35], v[2:3], v[2:3]
	v_pk_mov_b32 v[36:37], v[2:3], v[2:3]
	v_pk_mov_b32 v[38:39], v[2:3], v[2:3]
	v_pk_mov_b32 v[40:41], v[2:3], v[2:3]
	v_pk_mov_b32 v[50:51], v[2:3], v[2:3]
	v_pk_mov_b32 v[52:53], v[2:3], v[2:3]
	v_pk_mov_b32 v[54:55], v[2:3], v[2:3]
	v_pk_mov_b32 v[56:57], v[2:3], v[2:3]
	v_pk_mov_b32 v[10:11], v[2:3], v[2:3]
	v_pk_mov_b32 v[12:13], v[2:3], v[2:3]
	v_pk_mov_b32 v[14:15], v[2:3], v[2:3]
	v_pk_mov_b32 v[16:17], v[2:3], v[2:3]
	v_pk_mov_b32 v[26:27], v[2:3], v[2:3]
	v_pk_mov_b32 v[28:29], v[2:3], v[2:3]
	v_pk_mov_b32 v[30:31], v[2:3], v[2:3]
	v_pk_mov_b32 v[32:33], v[2:3], v[2:3]
	v_pk_mov_b32 v[42:43], v[2:3], v[2:3]
	v_pk_mov_b32 v[44:45], v[2:3], v[2:3]
	v_pk_mov_b32 v[46:47], v[2:3], v[2:3]
	v_pk_mov_b32 v[48:49], v[2:3], v[2:3]
	v_pk_mov_b32 v[58:59], v[2:3], v[2:3]
	v_pk_mov_b32 v[60:61], v[2:3], v[2:3]
	v_pk_mov_b32 v[62:63], v[2:3], v[2:3]
	v_pk_mov_b32 v[64:65], v[2:3], v[2:3]
	v_pk_mov_b32 v[66:67], v[2:3], v[2:3]
	v_pk_mov_b32 v[68:69], v[2:3], v[2:3]
	v_pk_mov_b32 v[70:71], v[2:3], v[2:3]
	v_pk_mov_b32 v[72:73], v[2:3], v[2:3]
	v_pk_mov_b32 v[82:83], v[2:3], v[2:3]
	v_pk_mov_b32 v[84:85], v[2:3], v[2:3]
	v_pk_mov_b32 v[86:87], v[2:3], v[2:3]
	v_pk_mov_b32 v[88:89], v[2:3], v[2:3]
	v_pk_mov_b32 v[98:99], v[2:3], v[2:3]
	v_pk_mov_b32 v[100:101], v[2:3], v[2:3]
	v_pk_mov_b32 v[102:103], v[2:3], v[2:3]
	v_pk_mov_b32 v[104:105], v[2:3], v[2:3]
	v_pk_mov_b32 v[118:119], v[2:3], v[2:3]
	v_pk_mov_b32 v[120:121], v[2:3], v[2:3]
	v_pk_mov_b32 v[122:123], v[2:3], v[2:3]
	v_pk_mov_b32 v[124:125], v[2:3], v[2:3]
	v_pk_mov_b32 v[74:75], v[2:3], v[2:3]
	v_pk_mov_b32 v[76:77], v[2:3], v[2:3]
	v_pk_mov_b32 v[78:79], v[2:3], v[2:3]
	v_pk_mov_b32 v[80:81], v[2:3], v[2:3]
	v_pk_mov_b32 v[90:91], v[2:3], v[2:3]
	v_pk_mov_b32 v[92:93], v[2:3], v[2:3]
	v_pk_mov_b32 v[94:95], v[2:3], v[2:3]
	v_pk_mov_b32 v[96:97], v[2:3], v[2:3]
	v_pk_mov_b32 v[106:107], v[2:3], v[2:3]
	v_pk_mov_b32 v[108:109], v[2:3], v[2:3]
	v_pk_mov_b32 v[110:111], v[2:3], v[2:3]
	v_pk_mov_b32 v[112:113], v[2:3], v[2:3]
	v_pk_mov_b32 v[130:131], v[2:3], v[2:3]
	v_pk_mov_b32 v[132:133], v[2:3], v[2:3]
	v_pk_mov_b32 v[134:135], v[2:3], v[2:3]
	v_pk_mov_b32 v[136:137], v[2:3], v[2:3]
	v_add_u32_e32 v201, 0x10000, v230
	v_add_u32_e32 v203, 0x14000, v230
	v_add_u32_e32 v236, 0x18000, v230
	v_add_u32_e32 v237, 0x1c000, v230
	v_add_u32_e32 v212, 0x40000, v194
	v_add_u32_e32 v213, 0x40000, v196
.LBB0_1385:
	s_add_i32 s70, s52, 2
	s_add_u32 s71, s44, 0xfffc0080
	s_addc_u32 s53, s45, -1
	s_cmp_eq_u32 s65, s52
	s_cselect_b32 s53, s13, s53
	s_cselect_b32 s52, s19, s71
	s_cselect_b32 s73, s15, s55
	s_cselect_b32 s72, s14, s54
	ds_read_b128 v[114:117], v201
	ds_read_b128 v[126:129], v201 offset:1024
	ds_read_b128 v[138:141], v201 offset:2048
	ds_read_b128 v[142:145], v201 offset:3072
	ds_read_b128 v[146:149], v203
	ds_read_b128 v[150:153], v203 offset:1024
	ds_read_b128 v[154:157], v203 offset:2048
	ds_read_b128 v[158:161], v203 offset:3072
	s_add_i32 m0, s51, 0xc000
	ds_read_b128 v[162:165], v235
	ds_read_b128 v[166:169], v235 offset:1024
	ds_read_b128 v[170:173], v235 offset:2048
	ds_read_b128 v[174:177], v235 offset:3072
	ds_read_b128 v[178:181], v235 offset:4096
	ds_read_b128 v[182:185], v235 offset:5120
	ds_read_b128 v[204:207], v235 offset:6144
	ds_read_b128 v[208:211], v235 offset:7168
	global_load_lds_dwordx4 v200, s[44:45]
	s_add_i32 m0, s51, 0xe000
	s_nop 0
	global_load_lds_dwordx4 v202, s[44:45]
	s_waitcnt vmcnt(8) lgkmcnt(0)
	s_barrier
	v_mfma_f32_16x16x32_bf16 v[134:137], v[114:117], v[162:165], v[134:137]
	v_mfma_f32_16x16x32_bf16 v[130:133], v[138:141], v[162:165], v[130:133]
	v_mfma_f32_16x16x32_bf16 v[110:113], v[114:117], v[170:173], v[110:113]
	v_mfma_f32_16x16x32_bf16 v[106:109], v[138:141], v[170:173], v[106:109]
	v_mfma_f32_16x16x32_bf16 v[94:97], v[114:117], v[178:181], v[94:97]
	v_mfma_f32_16x16x32_bf16 v[90:93], v[138:141], v[178:181], v[90:93]
	v_mfma_f32_16x16x32_bf16 v[78:81], v[114:117], v[204:207], v[78:81]
	v_mfma_f32_16x16x32_bf16 v[74:77], v[138:141], v[204:207], v[74:77]
	v_mfma_f32_16x16x32_bf16 v[134:137], v[126:129], v[166:169], v[134:137]
	v_mfma_f32_16x16x32_bf16 v[130:133], v[142:145], v[166:169], v[130:133]
	v_mfma_f32_16x16x32_bf16 v[110:113], v[126:129], v[174:177], v[110:113]
	v_mfma_f32_16x16x32_bf16 v[106:109], v[142:145], v[174:177], v[106:109]
	v_mfma_f32_16x16x32_bf16 v[94:97], v[126:129], v[182:185], v[94:97]
	v_mfma_f32_16x16x32_bf16 v[90:93], v[142:145], v[182:185], v[90:93]
	v_mfma_f32_16x16x32_bf16 v[78:81], v[126:129], v[208:211], v[78:81]
	v_mfma_f32_16x16x32_bf16 v[74:77], v[142:145], v[208:211], v[74:77]
	v_mfma_f32_16x16x32_bf16 v[122:125], v[146:149], v[162:165], v[122:125]
	v_mfma_f32_16x16x32_bf16 v[118:121], v[154:157], v[162:165], v[118:121]
	v_mfma_f32_16x16x32_bf16 v[102:105], v[146:149], v[170:173], v[102:105]
	v_mfma_f32_16x16x32_bf16 v[98:101], v[154:157], v[170:173], v[98:101]
	v_mfma_f32_16x16x32_bf16 v[86:89], v[146:149], v[178:181], v[86:89]
	v_mfma_f32_16x16x32_bf16 v[82:85], v[154:157], v[178:181], v[82:85]
	v_mfma_f32_16x16x32_bf16 v[70:73], v[146:149], v[204:207], v[70:73]
	v_mfma_f32_16x16x32_bf16 v[66:69], v[154:157], v[204:207], v[66:69]
	v_mfma_f32_16x16x32_bf16 v[122:125], v[150:153], v[166:169], v[122:125]
	v_mfma_f32_16x16x32_bf16 v[118:121], v[158:161], v[166:169], v[118:121]
	v_mfma_f32_16x16x32_bf16 v[102:105], v[150:153], v[174:177], v[102:105]
	v_mfma_f32_16x16x32_bf16 v[98:101], v[158:161], v[174:177], v[98:101]
	v_mfma_f32_16x16x32_bf16 v[86:89], v[150:153], v[182:185], v[86:89]
	v_mfma_f32_16x16x32_bf16 v[82:85], v[158:161], v[182:185], v[82:85]
	v_mfma_f32_16x16x32_bf16 v[70:73], v[150:153], v[208:211], v[70:73]
	v_mfma_f32_16x16x32_bf16 v[66:69], v[158:161], v[208:211], v[66:69]
	s_barrier
; #define PG8_STAGE(bufoff, gbase, voff) do { _Pragma("unroll") for (int _i = 0; _i < 2; ++_i) \
;         __builtin_amdgcn_global_load_lds((const unsigned*)((const char*)(gbase) + (voff)[_i]), (PG8_LAS unsigned*)(lds + (bufoff) + ldsw + _i * 8192), 16, 0, 0); } while (0)
; #define PG8_LDA(dst, b, h) do { _Pragma("unroll") for (int m = 0; m < 4; ++m) _Pragma("unroll") for (int k = 0; k < 2; ++k) dst[m][k] = *(const PG8_LAS bf16x8*)(lds + PG8_SA(b, h) + aoff + m * 2048 + k * 1024); } while (0)
; #define PG8_LDB(dst, b, h) do { _Pragma("unroll") for (int n = 0; n < 2; ++n) _Pragma("unroll") for (int k = 0; k < 2; ++k) dst[n][k] = *(const PG8_LAS bf16x8*)(lds + PG8_SB(b, h) + boff + n * 2048 + k * 1024); } while (0)
; #define PG8_MMA(ai, bj, At, Bt) do { __builtin_amdgcn_s_setprio(1); _Pragma("unroll") for (int m = 0; m < 4; ++m) _Pragma("unroll") for (int n = 0; n < 2; ++n) _Pragma("unroll") for (int k = 0; k < 2; ++k) \
;         acc[ai][bj][m][n] = __builtin_amdgcn_mfma_f32_16x16x32_bf16(Bt[n][k], At[m][k], acc[ai][bj][m][n], 0, 0, 0); __builtin_amdgcn_s_setprio(0); } while (0)
; #define PG8_WAIT_V(n) asm volatile("s_waitcnt vmcnt(" #n ")" ::: "memory")
; #define PG8_WAIT_L(n) asm volatile("s_waitcnt lgkmcnt(" #n ")" ::: "memory")
; #define PG8_BAR __builtin_amdgcn_s_barrier()
; #define PG8_SCHED __builtin_amdgcn_sched_barrier(0)
; template <class Epi, class Sched, bool ALIGN_EPI = false, bool SP2 = false>
; __device__ __forceinline__ void gemm_phase(PG8_LAS unsigned char* lds, const Gemm g, const Sched& S, const Epi& E, const int wv) {
;     ...
;             PG8_LDA(At, 0, 1); PG8_STAGE(PG8_SB(0, 0), b2, voffB); PG8_STAGE(PG8_SB(0, 1), b2 + hstepB, voffB); PG8_STAGE(PG8_SA(0, 0), a2, voffA);
;             PG8_WAIT_V(8); PG8_WAIT_L(0); PG8_BAR; PG8_MMA(1, 0, At, B0); PG8_MMA(1, 1, At, B1); PG8_BAR; PG8_SCHED;
;             PG8_LDB(B0, 1, 0); PG8_LDB(B1, 1, 1); PG8_SCHED; PG8_LDA(At, 1, 0); PG8_STAGE(PG8_SA(0, 1), a2 + hstepA, voffA);
	s_add_i32 s74, s3, 0x10000
	v_lshl_add_u64 v[190:191], s[72:73], 0, v[0:1]
	s_mov_b32 m0, s74
	ds_read_b128 v[162:165], v235 offset:16384
	ds_read_b128 v[166:169], v235 offset:17408
	ds_read_b128 v[170:173], v235 offset:18432
	ds_read_b128 v[174:177], v235 offset:19456
	ds_read_b128 v[178:181], v235 offset:20480
	ds_read_b128 v[182:185], v235 offset:21504
	ds_read_b128 v[204:207], v235 offset:22528
	ds_read_b128 v[208:211], v235 offset:23552
	global_load_lds_dwordx4 v[190:191], off
	s_add_i32 m0, s74, 0x2000
	v_lshl_add_u64 v[192:193], s[72:73], 0, v[198:199]
	s_add_u32 s72, s72, s24
	s_addc_u32 s73, s73, s25
	s_add_i32 s71, s3, 0x14000
	global_load_lds_dwordx4 v[192:193], off
	s_mov_b32 m0, s71
	global_load_lds_dwordx4 v0, s[72:73]
	s_add_i32 m0, s71, 0x2000
	global_load_lds_dwordx4 v198, s[72:73]
	s_mov_b32 m0, s51
	global_load_lds_dwordx4 v194, s[52:53]
	s_mov_b32 m0, s59
	s_nop 0
	global_load_lds_dwordx4 v196, s[52:53]
	s_waitcnt vmcnt(8) lgkmcnt(0)
	s_barrier
	v_mfma_f32_16x16x32_bf16 v[62:65], v[114:117], v[162:165], v[62:65]
	v_mfma_f32_16x16x32_bf16 v[58:61], v[138:141], v[162:165], v[58:61]
	v_mfma_f32_16x16x32_bf16 v[46:49], v[114:117], v[170:173], v[46:49]
	v_mfma_f32_16x16x32_bf16 v[42:45], v[138:141], v[170:173], v[42:45]
	v_mfma_f32_16x16x32_bf16 v[30:33], v[114:117], v[178:181], v[30:33]
	v_mfma_f32_16x16x32_bf16 v[26:29], v[138:141], v[178:181], v[26:29]
	v_mfma_f32_16x16x32_bf16 v[14:17], v[114:117], v[204:207], v[14:17]
	v_mfma_f32_16x16x32_bf16 v[10:13], v[138:141], v[204:207], v[10:13]
	v_mfma_f32_16x16x32_bf16 v[62:65], v[126:129], v[166:169], v[62:65]
	v_mfma_f32_16x16x32_bf16 v[58:61], v[142:145], v[166:169], v[58:61]
	v_mfma_f32_16x16x32_bf16 v[46:49], v[126:129], v[174:177], v[46:49]
	v_mfma_f32_16x16x32_bf16 v[42:45], v[142:145], v[174:177], v[42:45]
	v_mfma_f32_16x16x32_bf16 v[30:33], v[126:129], v[182:185], v[30:33]
	v_mfma_f32_16x16x32_bf16 v[26:29], v[142:145], v[182:185], v[26:29]
	v_mfma_f32_16x16x32_bf16 v[14:17], v[126:129], v[208:211], v[14:17]
	v_mfma_f32_16x16x32_bf16 v[10:13], v[142:145], v[208:211], v[10:13]
	v_mfma_f32_16x16x32_bf16 v[54:57], v[146:149], v[162:165], v[54:57]
	v_mfma_f32_16x16x32_bf16 v[50:53], v[154:157], v[162:165], v[50:53]
	v_mfma_f32_16x16x32_bf16 v[38:41], v[146:149], v[170:173], v[38:41]
	v_mfma_f32_16x16x32_bf16 v[34:37], v[154:157], v[170:173], v[34:37]
	v_mfma_f32_16x16x32_bf16 v[22:25], v[146:149], v[178:181], v[22:25]
	v_mfma_f32_16x16x32_bf16 v[18:21], v[154:157], v[178:181], v[18:21]
	v_mfma_f32_16x16x32_bf16 v[6:9], v[146:149], v[204:207], v[6:9]
	v_mfma_f32_16x16x32_bf16 v[2:5], v[154:157], v[204:207], v[2:5]
	v_mfma_f32_16x16x32_bf16 v[54:57], v[150:153], v[166:169], v[54:57]
	v_mfma_f32_16x16x32_bf16 v[50:53], v[158:161], v[166:169], v[50:53]
	v_mfma_f32_16x16x32_bf16 v[38:41], v[150:153], v[174:177], v[38:41]
	v_mfma_f32_16x16x32_bf16 v[34:37], v[158:161], v[174:177], v[34:37]
	v_mfma_f32_16x16x32_bf16 v[22:25], v[150:153], v[182:185], v[22:25]
	v_mfma_f32_16x16x32_bf16 v[18:21], v[158:161], v[182:185], v[18:21]
	v_mfma_f32_16x16x32_bf16 v[6:9], v[150:153], v[208:211], v[6:9]
	v_mfma_f32_16x16x32_bf16 v[2:5], v[158:161], v[208:211], v[2:5]
	s_barrier
	ds_read_b128 v[114:117], v236
	ds_read_b128 v[126:129], v236 offset:1024
	ds_read_b128 v[138:141], v236 offset:2048
	ds_read_b128 v[142:145], v236 offset:3072
	ds_read_b128 v[146:149], v237
	ds_read_b128 v[150:153], v237 offset:1024
	ds_read_b128 v[154:157], v237 offset:2048
	ds_read_b128 v[158:161], v237 offset:3072
	s_mov_b32 m0, s60
	ds_read_b128 v[162:165], v235 offset:32768
	ds_read_b128 v[166:169], v235 offset:33792
	ds_read_b128 v[170:173], v235 offset:34816
	ds_read_b128 v[174:177], v235 offset:35840
	ds_read_b128 v[178:181], v235 offset:36864
	ds_read_b128 v[182:185], v235 offset:37888
	ds_read_b128 v[204:207], v235 offset:38912
	ds_read_b128 v[208:211], v235 offset:39936
	global_load_lds_dwordx4 v212, s[52:53]
	s_mov_b32 m0, s61
	s_nop 0
	global_load_lds_dwordx4 v213, s[52:53]
	s_waitcnt vmcnt(8) lgkmcnt(0)
	s_barrier
; #define PG8_STAGE(bufoff, gbase, voff) do { _Pragma("unroll") for (int _i = 0; _i < 2; ++_i) \
;         __builtin_amdgcn_global_load_lds((const unsigned*)((const char*)(gbase) + (voff)[_i]), (PG8_LAS unsigned*)(lds + (bufoff) + ldsw + _i * 8192), 16, 0, 0); } while (0)
; #define PG8_LDA(dst, b, h) do { _Pragma("unroll") for (int m = 0; m < 4; ++m) _Pragma("unroll") for (int k = 0; k < 2; ++k) dst[m][k] = *(const PG8_LAS bf16x8*)(lds + PG8_SA(b, h) + aoff + m * 2048 + k * 1024); } while (0)
; #define PG8_MMA(ai, bj, At, Bt) do { __builtin_amdgcn_s_setprio(1); _Pragma("unroll") for (int m = 0; m < 4; ++m) _Pragma("unroll") for (int n = 0; n < 2; ++n) _Pragma("unroll") for (int k = 0; k < 2; ++k) \
;         acc[ai][bj][m][n] = __builtin_amdgcn_mfma_f32_16x16x32_bf16(Bt[n][k], At[m][k], acc[ai][bj][m][n], 0, 0, 0); __builtin_amdgcn_s_setprio(0); } while (0)
; #define PG8_WAIT_V(n) asm volatile("s_waitcnt vmcnt(" #n ")" ::: "memory")
; #define PG8_WAIT_L(n) asm volatile("s_waitcnt lgkmcnt(" #n ")" ::: "memory")
; #define PG8_BAR __builtin_amdgcn_s_barrier()
; #define PG8_SCHED __builtin_amdgcn_sched_barrier(0)
; template <class Epi, class Sched, bool ALIGN_EPI = false, bool SP2 = false>
; __device__ __forceinline__ void gemm_phase(PG8_LAS unsigned char* lds, const Gemm g, const Sched& S, const Epi& E, const int wv) {
;     ...
;             PG8_WAIT_V(8); PG8_WAIT_L(0); PG8_BAR; PG8_MMA(0, 0, At, B0); PG8_MMA(0, 1, At, B1); PG8_BAR; PG8_SCHED;
;             PG8_LDA(At, 1, 1); PG8_STAGE(PG8_SB(1, 0), b3, voffB); PG8_STAGE(PG8_SB(1, 1), b3 + hstepB, voffB); PG8_STAGE(PG8_SA(1, 0), a3, voffA);
;             PG8_WAIT_V(8); PG8_WAIT_L(0); PG8_BAR; PG8_MMA(1, 0, At, B0); PG8_MMA(1, 1, At, B1); PG8_BAR; PG8_SCHED;
	v_mfma_f32_16x16x32_bf16 v[134:137], v[114:117], v[162:165], v[134:137]
	v_mfma_f32_16x16x32_bf16 v[130:133], v[138:141], v[162:165], v[130:133]
	v_mfma_f32_16x16x32_bf16 v[110:113], v[114:117], v[170:173], v[110:113]
	v_mfma_f32_16x16x32_bf16 v[106:109], v[138:141], v[170:173], v[106:109]
	v_mfma_f32_16x16x32_bf16 v[94:97], v[114:117], v[178:181], v[94:97]
	v_mfma_f32_16x16x32_bf16 v[90:93], v[138:141], v[178:181], v[90:93]
	v_mfma_f32_16x16x32_bf16 v[78:81], v[114:117], v[204:207], v[78:81]
	v_mfma_f32_16x16x32_bf16 v[74:77], v[138:141], v[204:207], v[74:77]
	v_mfma_f32_16x16x32_bf16 v[134:137], v[126:129], v[166:169], v[134:137]
	v_mfma_f32_16x16x32_bf16 v[130:133], v[142:145], v[166:169], v[130:133]
	v_mfma_f32_16x16x32_bf16 v[110:113], v[126:129], v[174:177], v[110:113]
	v_mfma_f32_16x16x32_bf16 v[106:109], v[142:145], v[174:177], v[106:109]
	v_mfma_f32_16x16x32_bf16 v[94:97], v[126:129], v[182:185], v[94:97]
	v_mfma_f32_16x16x32_bf16 v[90:93], v[142:145], v[182:185], v[90:93]
	v_mfma_f32_16x16x32_bf16 v[78:81], v[126:129], v[208:211], v[78:81]
	v_mfma_f32_16x16x32_bf16 v[74:77], v[142:145], v[208:211], v[74:77]
	v_mfma_f32_16x16x32_bf16 v[122:125], v[146:149], v[162:165], v[122:125]
	v_mfma_f32_16x16x32_bf16 v[118:121], v[154:157], v[162:165], v[118:121]
	v_mfma_f32_16x16x32_bf16 v[102:105], v[146:149], v[170:173], v[102:105]
	v_mfma_f32_16x16x32_bf16 v[98:101], v[154:157], v[170:173], v[98:101]
	v_mfma_f32_16x16x32_bf16 v[86:89], v[146:149], v[178:181], v[86:89]
	v_mfma_f32_16x16x32_bf16 v[82:85], v[154:157], v[178:181], v[82:85]
	v_mfma_f32_16x16x32_bf16 v[70:73], v[146:149], v[204:207], v[70:73]
	v_mfma_f32_16x16x32_bf16 v[66:69], v[154:157], v[204:207], v[66:69]
	v_mfma_f32_16x16x32_bf16 v[122:125], v[150:153], v[166:169], v[122:125]
	v_mfma_f32_16x16x32_bf16 v[118:121], v[158:161], v[166:169], v[118:121]
	v_mfma_f32_16x16x32_bf16 v[102:105], v[150:153], v[174:177], v[102:105]
	v_mfma_f32_16x16x32_bf16 v[98:101], v[158:161], v[174:177], v[98:101]
	v_mfma_f32_16x16x32_bf16 v[86:89], v[150:153], v[182:185], v[86:89]
	v_mfma_f32_16x16x32_bf16 v[82:85], v[158:161], v[182:185], v[82:85]
	v_mfma_f32_16x16x32_bf16 v[70:73], v[150:153], v[208:211], v[70:73]
	v_mfma_f32_16x16x32_bf16 v[66:69], v[158:161], v[208:211], v[66:69]
	s_barrier
	s_add_i32 m0, s3, 0x17f80
	ds_read_b128 v[162:165], v235 offset:49152
	ds_read_b128 v[166:169], v235 offset:50176
	ds_read_b128 v[170:173], v235 offset:51200
	ds_read_b128 v[174:177], v235 offset:52224
	ds_read_b128 v[178:181], v235 offset:53248
	ds_read_b128 v[182:185], v235 offset:54272
	ds_read_b128 v[204:207], v235 offset:55296
	ds_read_b128 v[208:211], v235 offset:56320
	global_load_lds_dwordx4 v[190:191], off offset:128
	s_add_i32 m0, s3, 0x19f80
	global_load_lds_dwordx4 v[192:193], off offset:128
	s_add_i32 m0, s3, 0x1bf80
	s_nop 0
	global_load_lds_dwordx4 v0, s[72:73] offset:128
	s_add_i32 m0, s3, 0x1df80
	s_nop 0
	global_load_lds_dwordx4 v198, s[72:73] offset:128
	s_add_i32 m0, s63, 0xffffff80
	s_nop 0
	global_load_lds_dwordx4 v194, s[52:53] offset:128
	s_add_i32 m0, s64, 0xffffff80
	s_nop 0
	global_load_lds_dwordx4 v196, s[52:53] offset:128
	s_waitcnt vmcnt(8) lgkmcnt(0)
	s_barrier
	v_mfma_f32_16x16x32_bf16 v[62:65], v[114:117], v[162:165], v[62:65]
	v_mfma_f32_16x16x32_bf16 v[58:61], v[138:141], v[162:165], v[58:61]
	v_mfma_f32_16x16x32_bf16 v[46:49], v[114:117], v[170:173], v[46:49]
	v_mfma_f32_16x16x32_bf16 v[42:45], v[138:141], v[170:173], v[42:45]
	v_mfma_f32_16x16x32_bf16 v[30:33], v[114:117], v[178:181], v[30:33]
	v_mfma_f32_16x16x32_bf16 v[26:29], v[138:141], v[178:181], v[26:29]
	v_mfma_f32_16x16x32_bf16 v[14:17], v[114:117], v[204:207], v[14:17]
	v_mfma_f32_16x16x32_bf16 v[10:13], v[138:141], v[204:207], v[10:13]
	v_mfma_f32_16x16x32_bf16 v[62:65], v[126:129], v[166:169], v[62:65]
	v_mfma_f32_16x16x32_bf16 v[58:61], v[142:145], v[166:169], v[58:61]
	v_mfma_f32_16x16x32_bf16 v[46:49], v[126:129], v[174:177], v[46:49]
	v_mfma_f32_16x16x32_bf16 v[42:45], v[142:145], v[174:177], v[42:45]
	v_mfma_f32_16x16x32_bf16 v[30:33], v[126:129], v[182:185], v[30:33]
	v_mfma_f32_16x16x32_bf16 v[26:29], v[142:145], v[182:185], v[26:29]
	v_mfma_f32_16x16x32_bf16 v[14:17], v[126:129], v[208:211], v[14:17]
	v_mfma_f32_16x16x32_bf16 v[10:13], v[142:145], v[208:211], v[10:13]
	v_mfma_f32_16x16x32_bf16 v[54:57], v[146:149], v[162:165], v[54:57]
	v_mfma_f32_16x16x32_bf16 v[50:53], v[154:157], v[162:165], v[50:53]
	v_mfma_f32_16x16x32_bf16 v[38:41], v[146:149], v[170:173], v[38:41]
	v_mfma_f32_16x16x32_bf16 v[34:37], v[154:157], v[170:173], v[34:37]
	v_mfma_f32_16x16x32_bf16 v[22:25], v[146:149], v[178:181], v[22:25]
	v_mfma_f32_16x16x32_bf16 v[18:21], v[154:157], v[178:181], v[18:21]
	v_mfma_f32_16x16x32_bf16 v[6:9], v[146:149], v[204:207], v[6:9]
	v_mfma_f32_16x16x32_bf16 v[2:5], v[154:157], v[204:207], v[2:5]
	v_mfma_f32_16x16x32_bf16 v[54:57], v[150:153], v[166:169], v[54:57]
	v_mfma_f32_16x16x32_bf16 v[50:53], v[158:161], v[166:169], v[50:53]
	v_mfma_f32_16x16x32_bf16 v[38:41], v[150:153], v[174:177], v[38:41]
	v_mfma_f32_16x16x32_bf16 v[34:37], v[158:161], v[174:177], v[34:37]
	v_mfma_f32_16x16x32_bf16 v[22:25], v[150:153], v[182:185], v[22:25]
	v_mfma_f32_16x16x32_bf16 v[18:21], v[158:161], v[182:185], v[18:21]
	v_mfma_f32_16x16x32_bf16 v[6:9], v[150:153], v[208:211], v[6:9]
	v_mfma_f32_16x16x32_bf16 v[2:5], v[158:161], v[208:211], v[2:5]
	s_barrier
	s_add_u32 s44, s44, 0x100
	s_addc_u32 s45, s45, 0
	s_add_u32 s54, s54, 0x100
	s_addc_u32 s55, s55, 0
	s_cmp_ge_i32 s70, s62
	s_mov_b32 s52, s70
	s_cbranch_scc0 .LBB0_1385
	s_mov_b32 s72, 0x10000
	s_mov_b32 s73, 0x12000
	s_mov_b32 s74, 0x14000
	s_mov_b32 s70, 0x18000
	s_mov_b32 s71, 0x3f317217
	s_and_b64 vcc, exec, s[46:47]
	s_cbranch_vccz .LBB0_1361

; #define PG8_STAGE(bufoff, gbase, voff) do { _Pragma("unroll") for (int _i = 0; _i < 2; ++_i) \
;         __builtin_amdgcn_global_load_lds((const unsigned*)((const char*)(gbase) + (voff)[_i]), (PG8_LAS unsigned*)(lds + (bufoff) + ldsw + _i * 8192), 16, 0, 0); } while (0)
; #define PG8_LDA(dst, b, h) do { _Pragma("unroll") for (int m = 0; m < 4; ++m) _Pragma("unroll") for (int k = 0; k < 2; ++k) dst[m][k] = *(const PG8_LAS bf16x8*)(lds + PG8_SA(b, h) + aoff + m * 2048 + k * 1024); } while (0)
; #define PG8_LDB(dst, b, h) do { _Pragma("unroll") for (int n = 0; n < 2; ++n) _Pragma("unroll") for (int k = 0; k < 2; ++k) dst[n][k] = *(const PG8_LAS bf16x8*)(lds + PG8_SB(b, h) + boff + n * 2048 + k * 1024); } while (0)
; #define PG8_MMA(ai, bj, At, Bt) do { __builtin_amdgcn_s_setprio(1); _Pragma("unroll") for (int m = 0; m < 4; ++m) _Pragma("unroll") for (int n = 0; n < 2; ++n) _Pragma("unroll") for (int k = 0; k < 2; ++k) \
;         acc[ai][bj][m][n] = __builtin_amdgcn_mfma_f32_16x16x32_bf16(Bt[n][k], At[m][k], acc[ai][bj][m][n], 0, 0, 0); __builtin_amdgcn_s_setprio(0); } while (0)
; #define PG8_WAIT_V(n) asm volatile("s_waitcnt vmcnt(" #n ")" ::: "memory")
; #define PG8_WAIT_L(n) asm volatile("s_waitcnt lgkmcnt(" #n ")" ::: "memory")
; template <class Epi, class Sched, bool ALIGN_EPI = false, bool SP2 = false>
; __device__ __forceinline__ void gemm_phase(PG8_LAS unsigned char* lds, const Gemm g, const Sched& S, const Epi& E, const int wv) {
;     ...
;             const bool last = (t == nt - 2);
;             const char* a1 = cA + (size_t)(t + 1) * kstep;
;             const char* a2 = last ? nA : cA + (size_t)(t + 2) * kstep; const char* b2 = last ? nB : cB + (size_t)(t + 2) * kstep;
;             const char* a3 = a2 + kstep; const char* b3 = b2 + kstep;
;             if (last && has_next) S.a_ready(nxt);
;             if constexpr (SP2) {
;             PG8_LDB(B0, 0, 0); PG8_LDB(B1, 0, 1); PG8_SCHED; PG8_LDA(At, 0, 0); PG8_STAGE(PG8_SA(1, 1), a1 + hstepA, voffA);
;             PG8_WAIT_V(8); PG8_WAIT_L(0); PG8_BAR; PG8_MMA(0, 0, At, B0); PG8_MMA(0, 1, At, B1); PG8_BAR; PG8_SCHED;
;             PG8_LDA(At, 0, 1); PG8_STAGE(PG8_SB(0, 0), b2, voffB); PG8_STAGE(PG8_SB(0, 1), b2 + hstepB, voffB); PG8_STAGE(PG8_SA(0, 0), a2, voffA);
;             PG8_WAIT_V(8); PG8_WAIT_L(0); PG8_BAR; PG8_MMA(1, 0, At, B0); PG8_MMA(1, 1, At, B1); PG8_BAR; PG8_SCHED;
.LBB0_1495:
	s_add_i32 s52, s46, 2
	s_add_u32 s14, s48, 0x100
	s_addc_u32 s15, s49, 0
	s_cmp_eq_u32 s72, s46
	s_cselect_b32 s47, s11, s15
	s_cselect_b32 s46, s13, s14
	s_cselect_b32 s77, s87, s51
	s_cselect_b32 s76, s86, s35
	ds_read_b128 v[138:141], v192
	ds_read_b128 v[142:145], v192 offset:1024
	ds_read_b128 v[146:149], v192 offset:2048
	ds_read_b128 v[150:153], v192 offset:3072
	ds_read_b128 v[154:157], v193
	ds_read_b128 v[158:161], v193 offset:1024
	ds_read_b128 v[162:165], v193 offset:2048
	ds_read_b128 v[166:169], v193 offset:3072
	s_add_i32 m0, s64, 0xc000
	ds_read_b128 v[194:197], v211
	ds_read_b128 v[198:201], v211 offset:1024
	ds_read_b128 v[202:205], v211 offset:2048
	ds_read_b128 v[214:217], v211 offset:3072
	ds_read_b128 v[228:231], v211 offset:4096
	ds_read_b128 v[232:235], v211 offset:5120
	ds_read_b128 v[236:239], v211 offset:6144
	ds_read_b128 v[240:243], v211 offset:7168
	global_load_lds_dwordx4 v182, s[48:49]
	v_lshl_add_u64 v[190:191], s[48:49], 0, v[184:185]
	s_add_i32 m0, s64, 0xe000
	s_nop 0
	global_load_lds_dwordx4 v[190:191], off
	s_waitcnt vmcnt(8) lgkmcnt(0)
	s_barrier
	v_mfma_f32_16x16x32_bf16 v[118:121], v[138:141], v[194:197], v[118:121]
	v_mfma_f32_16x16x32_bf16 v[46:49], v[146:149], v[194:197], v[46:49]
	v_mfma_f32_16x16x32_bf16 v[110:113], v[138:141], v[202:205], v[110:113]
	v_mfma_f32_16x16x32_bf16 v[38:41], v[146:149], v[202:205], v[38:41]
	v_mfma_f32_16x16x32_bf16 v[134:137], v[138:141], v[228:231], v[134:137]
	v_mfma_f32_16x16x32_bf16 v[62:65], v[146:149], v[228:231], v[62:65]
	v_mfma_f32_16x16x32_bf16 v[130:133], v[138:141], v[236:239], v[130:133]
	v_mfma_f32_16x16x32_bf16 v[58:61], v[146:149], v[236:239], v[58:61]
	v_mfma_f32_16x16x32_bf16 v[118:121], v[142:145], v[198:201], v[118:121]
	v_mfma_f32_16x16x32_bf16 v[46:49], v[150:153], v[198:201], v[46:49]
	v_mfma_f32_16x16x32_bf16 v[110:113], v[142:145], v[214:217], v[110:113]
	v_mfma_f32_16x16x32_bf16 v[38:41], v[150:153], v[214:217], v[38:41]
	v_mfma_f32_16x16x32_bf16 v[134:137], v[142:145], v[232:235], v[134:137]
	v_mfma_f32_16x16x32_bf16 v[62:65], v[150:153], v[232:235], v[62:65]
	v_mfma_f32_16x16x32_bf16 v[130:133], v[142:145], v[240:243], v[130:133]
	v_mfma_f32_16x16x32_bf16 v[58:61], v[150:153], v[240:243], v[58:61]
	v_mfma_f32_16x16x32_bf16 v[114:117], v[154:157], v[194:197], v[114:117]
	v_mfma_f32_16x16x32_bf16 v[42:45], v[162:165], v[194:197], v[42:45]
	v_mfma_f32_16x16x32_bf16 v[106:109], v[154:157], v[202:205], v[106:109]
	v_mfma_f32_16x16x32_bf16 v[34:37], v[162:165], v[202:205], v[34:37]
	v_mfma_f32_16x16x32_bf16 v[126:129], v[154:157], v[228:231], v[126:129]
	v_mfma_f32_16x16x32_bf16 v[54:57], v[162:165], v[228:231], v[54:57]
	v_mfma_f32_16x16x32_bf16 v[122:125], v[154:157], v[236:239], v[122:125]
	v_mfma_f32_16x16x32_bf16 v[50:53], v[162:165], v[236:239], v[50:53]
	v_mfma_f32_16x16x32_bf16 v[114:117], v[158:161], v[198:201], v[114:117]
	v_mfma_f32_16x16x32_bf16 v[42:45], v[166:169], v[198:201], v[42:45]
	v_mfma_f32_16x16x32_bf16 v[106:109], v[158:161], v[214:217], v[106:109]
	v_mfma_f32_16x16x32_bf16 v[34:37], v[166:169], v[214:217], v[34:37]
	v_mfma_f32_16x16x32_bf16 v[126:129], v[158:161], v[232:235], v[126:129]
	v_mfma_f32_16x16x32_bf16 v[54:57], v[166:169], v[232:235], v[54:57]
	v_mfma_f32_16x16x32_bf16 v[122:125], v[158:161], v[240:243], v[122:125]
	v_mfma_f32_16x16x32_bf16 v[50:53], v[166:169], v[240:243], v[50:53]
	s_barrier
	s_add_i32 s48, s63, 0x10000
	s_mov_b32 m0, s48
	ds_read_b128 v[194:197], v211 offset:16384
	ds_read_b128 v[198:201], v211 offset:17408
	ds_read_b128 v[202:205], v211 offset:18432
	ds_read_b128 v[214:217], v211 offset:19456
	ds_read_b128 v[228:231], v211 offset:20480
	ds_read_b128 v[232:235], v211 offset:21504
	ds_read_b128 v[236:239], v211 offset:22528
	ds_read_b128 v[240:243], v211 offset:23552
	global_load_lds_dwordx4 v0, s[76:77]
	s_add_i32 m0, s48, 0x2000
	s_add_u32 s48, s76, s16
	s_addc_u32 s49, s77, s17
	s_add_i32 s53, s63, 0x14000
	global_load_lds_dwordx4 v174, s[76:77]
	s_mov_b32 m0, s53
	global_load_lds_dwordx4 v0, s[48:49]
	s_add_i32 m0, s53, 0x2000
	global_load_lds_dwordx4 v174, s[48:49]
	s_mov_b32 m0, s64
	global_load_lds_dwordx4 v170, s[46:47]
	s_mov_b32 m0, s65
	s_nop 0
	global_load_lds_dwordx4 v172, s[46:47]
	s_waitcnt vmcnt(8) lgkmcnt(0)
	s_barrier
	v_mfma_f32_16x16x32_bf16 v[86:89], v[138:141], v[194:197], v[86:89]
	v_mfma_f32_16x16x32_bf16 v[14:17], v[146:149], v[194:197], v[14:17]
	v_mfma_f32_16x16x32_bf16 v[70:73], v[138:141], v[202:205], v[70:73]
	v_mfma_f32_16x16x32_bf16 v[6:9], v[146:149], v[202:205], v[6:9]
	v_mfma_f32_16x16x32_bf16 v[102:105], v[138:141], v[228:231], v[102:105]
	v_mfma_f32_16x16x32_bf16 v[30:33], v[146:149], v[228:231], v[30:33]
	v_mfma_f32_16x16x32_bf16 v[98:101], v[138:141], v[236:239], v[98:101]
	v_mfma_f32_16x16x32_bf16 v[26:29], v[146:149], v[236:239], v[26:29]
	v_mfma_f32_16x16x32_bf16 v[86:89], v[142:145], v[198:201], v[86:89]
	v_mfma_f32_16x16x32_bf16 v[14:17], v[150:153], v[198:201], v[14:17]
	v_mfma_f32_16x16x32_bf16 v[70:73], v[142:145], v[214:217], v[70:73]
	v_mfma_f32_16x16x32_bf16 v[6:9], v[150:153], v[214:217], v[6:9]
	v_mfma_f32_16x16x32_bf16 v[102:105], v[142:145], v[232:235], v[102:105]
	v_mfma_f32_16x16x32_bf16 v[30:33], v[150:153], v[232:235], v[30:33]
	v_mfma_f32_16x16x32_bf16 v[98:101], v[142:145], v[240:243], v[98:101]
	v_mfma_f32_16x16x32_bf16 v[26:29], v[150:153], v[240:243], v[26:29]
	v_mfma_f32_16x16x32_bf16 v[82:85], v[154:157], v[194:197], v[82:85]
	v_mfma_f32_16x16x32_bf16 v[10:13], v[162:165], v[194:197], v[10:13]
	v_mfma_f32_16x16x32_bf16 v[66:69], v[154:157], v[202:205], v[66:69]
	v_mfma_f32_16x16x32_bf16 v[2:5], v[162:165], v[202:205], v[2:5]
	v_mfma_f32_16x16x32_bf16 v[94:97], v[154:157], v[228:231], v[94:97]
	v_mfma_f32_16x16x32_bf16 v[22:25], v[162:165], v[228:231], v[22:25]
	v_mfma_f32_16x16x32_bf16 v[90:93], v[154:157], v[236:239], v[90:93]
	v_mfma_f32_16x16x32_bf16 v[18:21], v[162:165], v[236:239], v[18:21]
	v_mfma_f32_16x16x32_bf16 v[82:85], v[158:161], v[198:201], v[82:85]
	v_mfma_f32_16x16x32_bf16 v[10:13], v[166:169], v[198:201], v[10:13]
	v_mfma_f32_16x16x32_bf16 v[66:69], v[158:161], v[214:217], v[66:69]
	v_mfma_f32_16x16x32_bf16 v[2:5], v[166:169], v[214:217], v[2:5]
	v_mfma_f32_16x16x32_bf16 v[94:97], v[158:161], v[232:235], v[94:97]
	v_mfma_f32_16x16x32_bf16 v[22:25], v[166:169], v[232:235], v[22:25]
	v_mfma_f32_16x16x32_bf16 v[90:93], v[158:161], v[240:243], v[90:93]
	v_mfma_f32_16x16x32_bf16 v[18:21], v[166:169], v[240:243], v[18:21]
	s_barrier
; #define PG8_STAGE(bufoff, gbase, voff) do { _Pragma("unroll") for (int _i = 0; _i < 2; ++_i) \
;         __builtin_amdgcn_global_load_lds((const unsigned*)((const char*)(gbase) + (voff)[_i]), (PG8_LAS unsigned*)(lds + (bufoff) + ldsw + _i * 8192), 16, 0, 0); } while (0)
; #define PG8_LDA(dst, b, h) do { _Pragma("unroll") for (int m = 0; m < 4; ++m) _Pragma("unroll") for (int k = 0; k < 2; ++k) dst[m][k] = *(const PG8_LAS bf16x8*)(lds + PG8_SA(b, h) + aoff + m * 2048 + k * 1024); } while (0)
; #define PG8_LDB(dst, b, h) do { _Pragma("unroll") for (int n = 0; n < 2; ++n) _Pragma("unroll") for (int k = 0; k < 2; ++k) dst[n][k] = *(const PG8_LAS bf16x8*)(lds + PG8_SB(b, h) + boff + n * 2048 + k * 1024); } while (0)
; #define PG8_MMA(ai, bj, At, Bt) do { __builtin_amdgcn_s_setprio(1); _Pragma("unroll") for (int m = 0; m < 4; ++m) _Pragma("unroll") for (int n = 0; n < 2; ++n) _Pragma("unroll") for (int k = 0; k < 2; ++k) \
;         acc[ai][bj][m][n] = __builtin_amdgcn_mfma_f32_16x16x32_bf16(Bt[n][k], At[m][k], acc[ai][bj][m][n], 0, 0, 0); __builtin_amdgcn_s_setprio(0); } while (0)
; #define PG8_WAIT_V(n) asm volatile("s_waitcnt vmcnt(" #n ")" ::: "memory")
; #define PG8_WAIT_L(n) asm volatile("s_waitcnt lgkmcnt(" #n ")" ::: "memory")
; #define PG8_BAR __builtin_amdgcn_s_barrier()
; #define PG8_SCHED __builtin_amdgcn_sched_barrier(0)
; template <class Epi, class Sched, bool ALIGN_EPI = false, bool SP2 = false>
; __device__ __forceinline__ void gemm_phase(PG8_LAS unsigned char* lds, const Gemm g, const Sched& S, const Epi& E, const int wv) {
;     ...
;             PG8_LDB(B0, 1, 0); PG8_LDB(B1, 1, 1); PG8_SCHED; PG8_LDA(At, 1, 0); PG8_STAGE(PG8_SA(0, 1), a2 + hstepA, voffA);
;             PG8_WAIT_V(8); PG8_WAIT_L(0); PG8_BAR; PG8_MMA(0, 0, At, B0); PG8_MMA(0, 1, At, B1); PG8_BAR; PG8_SCHED;
;             PG8_LDA(At, 1, 1); PG8_STAGE(PG8_SB(1, 0), b3, voffB); PG8_STAGE(PG8_SB(1, 1), b3 + hstepB, voffB); PG8_STAGE(PG8_SA(1, 0), a3, voffA);
;             PG8_WAIT_V(8); PG8_WAIT_L(0); PG8_BAR; PG8_MMA(1, 0, At, B0); PG8_MMA(1, 1, At, B1); PG8_BAR; PG8_SCHED;
	ds_read_b128 v[138:141], v213
	ds_read_b128 v[142:145], v213 offset:1024
	ds_read_b128 v[146:149], v213 offset:2048
	ds_read_b128 v[150:153], v213 offset:3072
	ds_read_b128 v[154:157], v227
	ds_read_b128 v[158:161], v227 offset:1024
	ds_read_b128 v[162:165], v227 offset:2048
	ds_read_b128 v[166:169], v227 offset:3072
	s_mov_b32 m0, s66
	ds_read_b128 v[194:197], v211 offset:32768
	ds_read_b128 v[198:201], v211 offset:33792
	ds_read_b128 v[202:205], v211 offset:34816
	ds_read_b128 v[214:217], v211 offset:35840
	ds_read_b128 v[228:231], v211 offset:36864
	ds_read_b128 v[232:235], v211 offset:37888
	ds_read_b128 v[236:239], v211 offset:38912
	ds_read_b128 v[240:243], v211 offset:39936
	global_load_lds_dwordx4 v218, s[46:47]
	s_mov_b32 m0, s67
	s_nop 0
	global_load_lds_dwordx4 v219, s[46:47]
	s_waitcnt vmcnt(8) lgkmcnt(0)
	s_barrier
	v_mfma_f32_16x16x32_bf16 v[118:121], v[138:141], v[194:197], v[118:121]
	v_mfma_f32_16x16x32_bf16 v[46:49], v[146:149], v[194:197], v[46:49]
	v_mfma_f32_16x16x32_bf16 v[110:113], v[138:141], v[202:205], v[110:113]
	v_mfma_f32_16x16x32_bf16 v[38:41], v[146:149], v[202:205], v[38:41]
	v_mfma_f32_16x16x32_bf16 v[134:137], v[138:141], v[228:231], v[134:137]
	v_mfma_f32_16x16x32_bf16 v[62:65], v[146:149], v[228:231], v[62:65]
	v_mfma_f32_16x16x32_bf16 v[130:133], v[138:141], v[236:239], v[130:133]
	v_mfma_f32_16x16x32_bf16 v[58:61], v[146:149], v[236:239], v[58:61]
	v_mfma_f32_16x16x32_bf16 v[118:121], v[142:145], v[198:201], v[118:121]
	v_mfma_f32_16x16x32_bf16 v[46:49], v[150:153], v[198:201], v[46:49]
	v_mfma_f32_16x16x32_bf16 v[110:113], v[142:145], v[214:217], v[110:113]
	v_mfma_f32_16x16x32_bf16 v[38:41], v[150:153], v[214:217], v[38:41]
	v_mfma_f32_16x16x32_bf16 v[134:137], v[142:145], v[232:235], v[134:137]
	v_mfma_f32_16x16x32_bf16 v[62:65], v[150:153], v[232:235], v[62:65]
	v_mfma_f32_16x16x32_bf16 v[130:133], v[142:145], v[240:243], v[130:133]
	v_mfma_f32_16x16x32_bf16 v[58:61], v[150:153], v[240:243], v[58:61]
	v_mfma_f32_16x16x32_bf16 v[114:117], v[154:157], v[194:197], v[114:117]
	v_mfma_f32_16x16x32_bf16 v[42:45], v[162:165], v[194:197], v[42:45]
	v_mfma_f32_16x16x32_bf16 v[106:109], v[154:157], v[202:205], v[106:109]
	v_mfma_f32_16x16x32_bf16 v[34:37], v[162:165], v[202:205], v[34:37]
	v_mfma_f32_16x16x32_bf16 v[126:129], v[154:157], v[228:231], v[126:129]
	v_mfma_f32_16x16x32_bf16 v[54:57], v[162:165], v[228:231], v[54:57]
	v_mfma_f32_16x16x32_bf16 v[122:125], v[154:157], v[236:239], v[122:125]
	v_mfma_f32_16x16x32_bf16 v[50:53], v[162:165], v[236:239], v[50:53]
	v_mfma_f32_16x16x32_bf16 v[114:117], v[158:161], v[198:201], v[114:117]
	v_mfma_f32_16x16x32_bf16 v[42:45], v[166:169], v[198:201], v[42:45]
	v_mfma_f32_16x16x32_bf16 v[106:109], v[158:161], v[214:217], v[106:109]
	v_mfma_f32_16x16x32_bf16 v[34:37], v[166:169], v[214:217], v[34:37]
	v_mfma_f32_16x16x32_bf16 v[126:129], v[158:161], v[232:235], v[126:129]
	v_mfma_f32_16x16x32_bf16 v[54:57], v[166:169], v[232:235], v[54:57]
	v_mfma_f32_16x16x32_bf16 v[122:125], v[158:161], v[240:243], v[122:125]
	v_mfma_f32_16x16x32_bf16 v[50:53], v[166:169], v[240:243], v[50:53]
	s_barrier
	s_add_i32 m0, s63, 0x17f80
	ds_read_b128 v[194:197], v211 offset:49152
	ds_read_b128 v[198:201], v211 offset:50176
	ds_read_b128 v[202:205], v211 offset:51200
	ds_read_b128 v[214:217], v211 offset:52224
	ds_read_b128 v[228:231], v211 offset:53248
	ds_read_b128 v[232:235], v211 offset:54272
	ds_read_b128 v[236:239], v211 offset:55296
	ds_read_b128 v[240:243], v211 offset:56320
	global_load_lds_dwordx4 v0, s[76:77] offset:128
	s_add_i32 m0, s63, 0x19f80
	global_load_lds_dwordx4 v174, s[76:77] offset:128
	s_add_i32 m0, s63, 0x1bf80
	s_nop 0
	global_load_lds_dwordx4 v0, s[48:49] offset:128
	s_add_i32 m0, s63, 0x1df80
	s_nop 0
	global_load_lds_dwordx4 v174, s[48:49] offset:128
	s_add_i32 m0, s70, 0xffffff80
	s_nop 0
	global_load_lds_dwordx4 v170, s[46:47] offset:128
	s_add_i32 m0, s71, 0xffffff80
	s_nop 0
	global_load_lds_dwordx4 v172, s[46:47] offset:128
	s_waitcnt vmcnt(8) lgkmcnt(0)
	s_barrier
	v_mfma_f32_16x16x32_bf16 v[86:89], v[138:141], v[194:197], v[86:89]
	v_mfma_f32_16x16x32_bf16 v[14:17], v[146:149], v[194:197], v[14:17]
	v_mfma_f32_16x16x32_bf16 v[70:73], v[138:141], v[202:205], v[70:73]
	v_mfma_f32_16x16x32_bf16 v[6:9], v[146:149], v[202:205], v[6:9]
	v_mfma_f32_16x16x32_bf16 v[102:105], v[138:141], v[228:231], v[102:105]
	v_mfma_f32_16x16x32_bf16 v[30:33], v[146:149], v[228:231], v[30:33]
	v_mfma_f32_16x16x32_bf16 v[98:101], v[138:141], v[236:239], v[98:101]
	v_mfma_f32_16x16x32_bf16 v[26:29], v[146:149], v[236:239], v[26:29]
	v_mfma_f32_16x16x32_bf16 v[86:89], v[142:145], v[198:201], v[86:89]
	v_mfma_f32_16x16x32_bf16 v[14:17], v[150:153], v[198:201], v[14:17]
	v_mfma_f32_16x16x32_bf16 v[70:73], v[142:145], v[214:217], v[70:73]
	v_mfma_f32_16x16x32_bf16 v[6:9], v[150:153], v[214:217], v[6:9]
	v_mfma_f32_16x16x32_bf16 v[102:105], v[142:145], v[232:235], v[102:105]
	v_mfma_f32_16x16x32_bf16 v[30:33], v[150:153], v[232:235], v[30:33]
	v_mfma_f32_16x16x32_bf16 v[98:101], v[142:145], v[240:243], v[98:101]
	v_mfma_f32_16x16x32_bf16 v[26:29], v[150:153], v[240:243], v[26:29]
	v_mfma_f32_16x16x32_bf16 v[82:85], v[154:157], v[194:197], v[82:85]
	v_mfma_f32_16x16x32_bf16 v[10:13], v[162:165], v[194:197], v[10:13]
	v_mfma_f32_16x16x32_bf16 v[66:69], v[154:157], v[202:205], v[66:69]
	v_mfma_f32_16x16x32_bf16 v[2:5], v[162:165], v[202:205], v[2:5]
	v_mfma_f32_16x16x32_bf16 v[94:97], v[154:157], v[228:231], v[94:97]
	v_mfma_f32_16x16x32_bf16 v[22:25], v[162:165], v[228:231], v[22:25]
	v_mfma_f32_16x16x32_bf16 v[90:93], v[154:157], v[236:239], v[90:93]
	v_mfma_f32_16x16x32_bf16 v[18:21], v[162:165], v[236:239], v[18:21]
	v_mfma_f32_16x16x32_bf16 v[82:85], v[158:161], v[198:201], v[82:85]
	v_mfma_f32_16x16x32_bf16 v[10:13], v[166:169], v[198:201], v[10:13]
	v_mfma_f32_16x16x32_bf16 v[66:69], v[158:161], v[214:217], v[66:69]
	v_mfma_f32_16x16x32_bf16 v[2:5], v[166:169], v[214:217], v[2:5]
	v_mfma_f32_16x16x32_bf16 v[94:97], v[158:161], v[232:235], v[94:97]
	v_mfma_f32_16x16x32_bf16 v[22:25], v[166:169], v[232:235], v[22:25]
	v_mfma_f32_16x16x32_bf16 v[90:93], v[158:161], v[240:243], v[90:93]
	v_mfma_f32_16x16x32_bf16 v[18:21], v[166:169], v[240:243], v[18:21]
	s_barrier
	s_add_u32 s35, s35, 0x100
	s_addc_u32 s51, s51, 0
	s_cmp_ge_i32 s52, s68
	s_mov_b64 s[48:49], s[14:15]
	s_mov_b32 s46, s52
	s_cbranch_scc0 .LBB0_1495
	s_movk_i32 s78, 0x7ff
	s_movk_i32 s76, 0x3000
	s_and_b64 vcc, exec, s[30:31]
	s_cbranch_vccz .LBB0_1470
